# GEMM K-loop: k=0 half of each At fragment set read inside the preceding MMA segment (after MFMA 8), ph3/ph7 stage wait vmcnt(8)
# baseline (speedup 1.0000x reference)
.LBB0_296:
	s_ashr_i32 s9, s8, 31
	v_cmp_lt_i64_e32 vcc, s[12:13], v[180:181]
	s_lshl_b64 s[12:13], s[8:9], 19
	s_add_u32 s12, s29, s12
	s_addc_u32 s13, s30, s13
	s_and_b64 s[14:15], vcc, exec
	s_cselect_b32 s9, s13, s21
	s_cselect_b32 s44, s12, s20
	s_ashr_i32 s7, s6, 31
	s_lshl_b64 s[14:15], s[6:7], 19
	s_add_u32 s14, s31, s14
	s_addc_u32 s15, s33, s15
	s_and_b64 s[24:25], vcc, exec
	s_cselect_b32 s7, s15, s23
	s_cselect_b32 s45, s14, s22
	s_add_u32 s20, s20, 0x40080
	s_addc_u32 s21, s21, 0
	s_add_u32 s46, s22, 0x100
	s_addc_u32 s47, s23, 0
	s_mov_b32 s48, -2
	s_add_u32 s22, s20, 0xfffc0080
	s_addc_u32 s23, s21, -1
	s_add_i32 s49, 0, 0x10000
	v_add_u32_e32 v145, s49, v142
	ds_read_b128 v[146:149], v145
	ds_read_b128 v[150:153], v145 offset:1024
	ds_read_b128 v[154:157], v145 offset:2048
	ds_read_b128 v[158:161], v145 offset:3072
	s_cmp_eq_u32 s48, 12
	s_cselect_b32 s25, s9, s23
	s_cselect_b32 s24, s44, s22
	s_cselect_b32 s23, s7, s47
	s_cselect_b32 s22, s45, s46
	s_add_i32 m0, s19, 0xc000
	ds_read_b128 v[162:165], v144
	ds_read_b128 v[166:169], v144 offset:1024
	ds_read_b128 v[170:173], v144 offset:2048
	ds_read_b128 v[174:177], v144 offset:3072
	ds_read_b128 v[190:193], v144 offset:4096
	ds_read_b128 v[194:197], v144 offset:5120
	ds_read_b128 v[198:201], v144 offset:6144
	ds_read_b128 v[202:205], v144 offset:7168
	global_load_lds_dwordx4 v138, s[20:21]
	s_add_i32 m0, s19, 0xe000
	s_nop 0
	global_load_lds_dwordx4 v140, s[20:21]
	s_waitcnt lgkmcnt(8)
	s_barrier
	s_waitcnt lgkmcnt(0)
	s_waitcnt lgkmcnt(0)
	v_mfma_f32_16x16x32_bf16 v[126:129], v[146:149], v[162:165], 0
	v_mfma_f32_16x16x32_bf16 v[118:121], v[154:157], v[162:165], 0
	v_mfma_f32_16x16x32_bf16 v[110:113], v[146:149], v[170:173], 0
	v_mfma_f32_16x16x32_bf16 v[102:105], v[154:157], v[170:173], 0
	v_mfma_f32_16x16x32_bf16 v[94:97], v[146:149], v[190:193], 0
	v_mfma_f32_16x16x32_bf16 v[86:89], v[154:157], v[190:193], 0
	v_mfma_f32_16x16x32_bf16 v[78:81], v[146:149], v[198:201], 0
	v_mfma_f32_16x16x32_bf16 v[70:73], v[154:157], v[198:201], 0
	v_mfma_f32_16x16x32_bf16 v[126:129], v[150:153], v[166:169], v[126:129]
	v_mfma_f32_16x16x32_bf16 v[118:121], v[158:161], v[166:169], v[118:121]
	v_mfma_f32_16x16x32_bf16 v[110:113], v[150:153], v[174:177], v[110:113]
	v_mfma_f32_16x16x32_bf16 v[102:105], v[158:161], v[174:177], v[102:105]
	v_mfma_f32_16x16x32_bf16 v[94:97], v[150:153], v[194:197], v[94:97]
	v_mfma_f32_16x16x32_bf16 v[86:89], v[158:161], v[194:197], v[86:89]
	v_mfma_f32_16x16x32_bf16 v[78:81], v[150:153], v[202:205], v[78:81]
	v_mfma_f32_16x16x32_bf16 v[70:73], v[158:161], v[202:205], v[70:73]
	s_barrier
	s_add_i32 s54, 0, 0x14000
	s_add_i32 s49, s49, s35
	v_add_u32_e32 v145, s54, v142
	s_add_u32 s64, s22, 0x80
	s_addc_u32 s65, s23, 0
	s_mov_b32 m0, s49
	ds_read_b128 v[206:209], v145
	ds_read_b128 v[210:213], v145 offset:1024
	ds_read_b128 v[214:217], v145 offset:2048
	ds_read_b128 v[218:221], v145 offset:3072
	global_load_lds_dwordx4 v134, s[22:23]
	s_add_i32 m0, s49, 0x2000
	s_nop 0
	global_load_lds_dwordx4 v130, s[22:23]
	s_barrier
	s_waitcnt lgkmcnt(0)
	s_waitcnt lgkmcnt(0)
	v_mfma_f32_16x16x32_bf16 v[122:125], v[206:209], v[162:165], 0
	v_mfma_f32_16x16x32_bf16 v[114:117], v[214:217], v[162:165], 0
	v_mfma_f32_16x16x32_bf16 v[106:109], v[206:209], v[170:173], 0
	v_mfma_f32_16x16x32_bf16 v[98:101], v[214:217], v[170:173], 0
	v_mfma_f32_16x16x32_bf16 v[90:93], v[206:209], v[190:193], 0
	v_mfma_f32_16x16x32_bf16 v[82:85], v[214:217], v[190:193], 0
	v_mfma_f32_16x16x32_bf16 v[74:77], v[206:209], v[198:201], 0
	v_mfma_f32_16x16x32_bf16 v[66:69], v[214:217], v[198:201], 0
	ds_read_b128 v[162:165], v144 offset:16384
	v_mfma_f32_16x16x32_bf16 v[122:125], v[210:213], v[166:169], v[122:125]
	v_mfma_f32_16x16x32_bf16 v[114:117], v[218:221], v[166:169], v[114:117]
	ds_read_b128 v[170:173], v144 offset:18432
	v_mfma_f32_16x16x32_bf16 v[106:109], v[210:213], v[174:177], v[106:109]
	v_mfma_f32_16x16x32_bf16 v[98:101], v[218:221], v[174:177], v[98:101]
	ds_read_b128 v[190:193], v144 offset:20480
	v_mfma_f32_16x16x32_bf16 v[90:93], v[210:213], v[194:197], v[90:93]
	v_mfma_f32_16x16x32_bf16 v[82:85], v[218:221], v[194:197], v[82:85]
	ds_read_b128 v[198:201], v144 offset:22528
	v_mfma_f32_16x16x32_bf16 v[74:77], v[210:213], v[202:205], v[74:77]
	v_mfma_f32_16x16x32_bf16 v[66:69], v[218:221], v[202:205], v[66:69]
	s_barrier
	s_mov_b32 m0, s19
	s_add_u32 s62, s24, 0x80
	s_addc_u32 s63, s25, 0
	ds_read_b128 v[166:169], v144 offset:17408
	ds_read_b128 v[174:177], v144 offset:19456
	ds_read_b128 v[194:197], v144 offset:21504
	ds_read_b128 v[202:205], v144 offset:23552
	global_load_lds_dwordx4 v136, s[24:25]
	s_mov_b32 m0, s36
	s_nop 0
	global_load_lds_dwordx4 v132, s[24:25]
	s_waitcnt vmcnt(8)
	s_barrier
	s_waitcnt lgkmcnt(0)
	s_waitcnt lgkmcnt(0)
	v_mfma_f32_16x16x32_bf16 v[62:65], v[146:149], v[162:165], 0
	v_mfma_f32_16x16x32_bf16 v[54:57], v[154:157], v[162:165], 0
	v_mfma_f32_16x16x32_bf16 v[46:49], v[146:149], v[170:173], 0
	v_mfma_f32_16x16x32_bf16 v[38:41], v[154:157], v[170:173], 0
	v_mfma_f32_16x16x32_bf16 v[30:33], v[146:149], v[190:193], 0
	v_mfma_f32_16x16x32_bf16 v[22:25], v[154:157], v[190:193], 0
	v_mfma_f32_16x16x32_bf16 v[14:17], v[146:149], v[198:201], 0
	v_mfma_f32_16x16x32_bf16 v[6:9], v[154:157], v[198:201], 0
	v_mfma_f32_16x16x32_bf16 v[62:65], v[150:153], v[166:169], v[62:65]
	v_mfma_f32_16x16x32_bf16 v[54:57], v[158:161], v[166:169], v[54:57]
	v_mfma_f32_16x16x32_bf16 v[46:49], v[150:153], v[174:177], v[46:49]
	v_mfma_f32_16x16x32_bf16 v[38:41], v[158:161], v[174:177], v[38:41]
	v_mfma_f32_16x16x32_bf16 v[30:33], v[150:153], v[194:197], v[30:33]
	v_mfma_f32_16x16x32_bf16 v[22:25], v[158:161], v[194:197], v[22:25]
	v_mfma_f32_16x16x32_bf16 v[14:17], v[150:153], v[202:205], v[14:17]
	v_mfma_f32_16x16x32_bf16 v[6:9], v[158:161], v[202:205], v[6:9]
	s_barrier
	v_add_u32_e32 v158, 0x18000, v142
	ds_read_b128 v[146:149], v158
	ds_read_b128 v[150:153], v158 offset:1024
	ds_read_b128 v[154:157], v158 offset:2048
	ds_read_b128 v[158:161], v158 offset:3072
	s_add_u32 s50, s22, 0x40000
	s_addc_u32 s51, s23, 0
	s_add_i32 s49, s54, s35
	s_mov_b32 m0, s49
	s_nop 0
	global_load_lds_dwordx4 v134, s[50:51]
	s_add_i32 m0, s49, 0x2000
	s_nop 0
	global_load_lds_dwordx4 v130, s[50:51]
	s_waitcnt vmcnt(6)
	s_barrier
	v_mfma_f32_16x16x32_bf16 v[58:61], v[206:209], v[162:165], 0
	v_mfma_f32_16x16x32_bf16 v[50:53], v[214:217], v[162:165], 0
	v_mfma_f32_16x16x32_bf16 v[42:45], v[206:209], v[170:173], 0
	v_mfma_f32_16x16x32_bf16 v[34:37], v[214:217], v[170:173], 0
	v_mfma_f32_16x16x32_bf16 v[26:29], v[206:209], v[190:193], 0
	v_mfma_f32_16x16x32_bf16 v[18:21], v[214:217], v[190:193], 0
	v_mfma_f32_16x16x32_bf16 v[10:13], v[206:209], v[198:201], 0
	v_mfma_f32_16x16x32_bf16 v[2:5], v[214:217], v[198:201], 0
	ds_read_b128 v[162:165], v144 offset:32768
	v_mfma_f32_16x16x32_bf16 v[58:61], v[210:213], v[166:169], v[58:61]
	v_mfma_f32_16x16x32_bf16 v[50:53], v[218:221], v[166:169], v[50:53]
	ds_read_b128 v[170:173], v144 offset:34816
	v_mfma_f32_16x16x32_bf16 v[42:45], v[210:213], v[174:177], v[42:45]
	v_mfma_f32_16x16x32_bf16 v[34:37], v[218:221], v[174:177], v[34:37]
	ds_read_b128 v[190:193], v144 offset:36864
	v_mfma_f32_16x16x32_bf16 v[26:29], v[210:213], v[194:197], v[26:29]
	v_mfma_f32_16x16x32_bf16 v[18:21], v[218:221], v[194:197], v[18:21]
	ds_read_b128 v[198:201], v144 offset:38912
	v_mfma_f32_16x16x32_bf16 v[10:13], v[210:213], v[202:205], v[10:13]
	v_mfma_f32_16x16x32_bf16 v[2:5], v[218:221], v[202:205], v[2:5]
	s_barrier
	s_add_i32 s49, 0, 0x18000
	v_add_u32_e32 v145, s49, v142
	s_add_u32 s24, s24, 0x40000
	s_addc_u32 s25, s25, 0
	s_mov_b32 m0, s37
	ds_read_b128 v[166:169], v144 offset:33792
	ds_read_b128 v[174:177], v144 offset:35840
	ds_read_b128 v[194:197], v144 offset:37888
	ds_read_b128 v[202:205], v144 offset:39936
	global_load_lds_dwordx4 v136, s[24:25]
	s_mov_b32 m0, s38
	s_nop 0
	global_load_lds_dwordx4 v132, s[24:25]
	s_waitcnt lgkmcnt(8)
	s_barrier
	s_waitcnt lgkmcnt(0)
	s_waitcnt lgkmcnt(0)
	v_mfma_f32_16x16x32_bf16 v[126:129], v[146:149], v[162:165], v[126:129]
	v_mfma_f32_16x16x32_bf16 v[118:121], v[154:157], v[162:165], v[118:121]
	v_mfma_f32_16x16x32_bf16 v[110:113], v[146:149], v[170:173], v[110:113]
	v_mfma_f32_16x16x32_bf16 v[102:105], v[154:157], v[170:173], v[102:105]
	v_mfma_f32_16x16x32_bf16 v[94:97], v[146:149], v[190:193], v[94:97]
	v_mfma_f32_16x16x32_bf16 v[86:89], v[154:157], v[190:193], v[86:89]
	v_mfma_f32_16x16x32_bf16 v[78:81], v[146:149], v[198:201], v[78:81]
	v_mfma_f32_16x16x32_bf16 v[70:73], v[154:157], v[198:201], v[70:73]
	v_mfma_f32_16x16x32_bf16 v[126:129], v[150:153], v[166:169], v[126:129]
	v_mfma_f32_16x16x32_bf16 v[118:121], v[158:161], v[166:169], v[118:121]
	v_mfma_f32_16x16x32_bf16 v[110:113], v[150:153], v[174:177], v[110:113]
	v_mfma_f32_16x16x32_bf16 v[102:105], v[158:161], v[174:177], v[102:105]
	v_mfma_f32_16x16x32_bf16 v[94:97], v[150:153], v[194:197], v[94:97]
	v_mfma_f32_16x16x32_bf16 v[86:89], v[158:161], v[194:197], v[86:89]
	v_mfma_f32_16x16x32_bf16 v[78:81], v[150:153], v[202:205], v[78:81]
	v_mfma_f32_16x16x32_bf16 v[70:73], v[158:161], v[202:205], v[70:73]
	s_barrier
	s_add_i32 s24, 0, 0x1c000
	s_add_i32 s25, s49, s35
	v_add_u32_e32 v145, s24, v142
	s_mov_b32 m0, s25
	ds_read_b128 v[206:209], v145
	ds_read_b128 v[210:213], v145 offset:1024
	ds_read_b128 v[214:217], v145 offset:2048
	ds_read_b128 v[218:221], v145 offset:3072
	global_load_lds_dwordx4 v134, s[64:65]
	s_add_i32 m0, s25, 0x2000
	s_nop 0
	global_load_lds_dwordx4 v130, s[64:65]
	s_barrier
	s_waitcnt lgkmcnt(0)
	s_waitcnt lgkmcnt(0)
	v_mfma_f32_16x16x32_bf16 v[122:125], v[206:209], v[162:165], v[122:125]
	v_mfma_f32_16x16x32_bf16 v[114:117], v[214:217], v[162:165], v[114:117]
	v_mfma_f32_16x16x32_bf16 v[106:109], v[206:209], v[170:173], v[106:109]
	v_mfma_f32_16x16x32_bf16 v[98:101], v[214:217], v[170:173], v[98:101]
	v_mfma_f32_16x16x32_bf16 v[90:93], v[206:209], v[190:193], v[90:93]
	v_mfma_f32_16x16x32_bf16 v[82:85], v[214:217], v[190:193], v[82:85]
	v_mfma_f32_16x16x32_bf16 v[74:77], v[206:209], v[198:201], v[74:77]
	v_mfma_f32_16x16x32_bf16 v[66:69], v[214:217], v[198:201], v[66:69]
	ds_read_b128 v[162:165], v144 offset:49152
	v_mfma_f32_16x16x32_bf16 v[122:125], v[210:213], v[166:169], v[122:125]
	v_mfma_f32_16x16x32_bf16 v[114:117], v[218:221], v[166:169], v[114:117]
	ds_read_b128 v[170:173], v144 offset:51200
	v_mfma_f32_16x16x32_bf16 v[106:109], v[210:213], v[174:177], v[106:109]
	v_mfma_f32_16x16x32_bf16 v[98:101], v[218:221], v[174:177], v[98:101]
	ds_read_b128 v[190:193], v144 offset:53248
	v_mfma_f32_16x16x32_bf16 v[90:93], v[210:213], v[194:197], v[90:93]
	v_mfma_f32_16x16x32_bf16 v[82:85], v[218:221], v[194:197], v[82:85]
	ds_read_b128 v[198:201], v144 offset:55296
	v_mfma_f32_16x16x32_bf16 v[74:77], v[210:213], v[202:205], v[74:77]
	v_mfma_f32_16x16x32_bf16 v[66:69], v[218:221], v[202:205], v[66:69]
	s_barrier
	s_mov_b32 m0, s39
	ds_read_b128 v[166:169], v144 offset:50176
	ds_read_b128 v[174:177], v144 offset:52224
	ds_read_b128 v[194:197], v144 offset:54272
	ds_read_b128 v[202:205], v144 offset:56320
	global_load_lds_dwordx4 v136, s[62:63]
	s_mov_b32 m0, s40
	s_nop 0
	global_load_lds_dwordx4 v132, s[62:63]
	s_waitcnt vmcnt(8)
	s_barrier
	s_waitcnt lgkmcnt(0)
	s_waitcnt lgkmcnt(0)
	v_mfma_f32_16x16x32_bf16 v[62:65], v[146:149], v[162:165], v[62:65]
	v_mfma_f32_16x16x32_bf16 v[54:57], v[154:157], v[162:165], v[54:57]
	v_mfma_f32_16x16x32_bf16 v[46:49], v[146:149], v[170:173], v[46:49]
	v_mfma_f32_16x16x32_bf16 v[38:41], v[154:157], v[170:173], v[38:41]
	v_mfma_f32_16x16x32_bf16 v[30:33], v[146:149], v[190:193], v[30:33]
	v_mfma_f32_16x16x32_bf16 v[22:25], v[154:157], v[190:193], v[22:25]
	v_mfma_f32_16x16x32_bf16 v[14:17], v[146:149], v[198:201], v[14:17]
	v_mfma_f32_16x16x32_bf16 v[6:9], v[154:157], v[198:201], v[6:9]
	v_mfma_f32_16x16x32_bf16 v[62:65], v[150:153], v[166:169], v[62:65]
	v_mfma_f32_16x16x32_bf16 v[54:57], v[158:161], v[166:169], v[54:57]
	v_mfma_f32_16x16x32_bf16 v[46:49], v[150:153], v[174:177], v[46:49]
	v_mfma_f32_16x16x32_bf16 v[38:41], v[158:161], v[174:177], v[38:41]
	v_mfma_f32_16x16x32_bf16 v[30:33], v[150:153], v[194:197], v[30:33]
	v_mfma_f32_16x16x32_bf16 v[22:25], v[158:161], v[194:197], v[22:25]
	v_mfma_f32_16x16x32_bf16 v[14:17], v[150:153], v[202:205], v[14:17]
	v_mfma_f32_16x16x32_bf16 v[6:9], v[158:161], v[202:205], v[6:9]
	s_barrier
	v_add_u32_e32 v158, 0x10000, v142
	ds_read_b128 v[146:149], v158
	ds_read_b128 v[150:153], v158 offset:1024
	ds_read_b128 v[154:157], v158 offset:2048
	ds_read_b128 v[158:161], v158 offset:3072
	s_add_u32 s22, s22, 0x40080
	s_addc_u32 s23, s23, 0
	s_add_i32 s24, s24, s35
	s_mov_b32 m0, s24
	s_nop 0
	global_load_lds_dwordx4 v134, s[22:23]
	s_add_i32 m0, s24, 0x2000
	s_nop 0
	global_load_lds_dwordx4 v130, s[22:23]
	s_waitcnt vmcnt(6)
	s_barrier
	v_mfma_f32_16x16x32_bf16 v[58:61], v[206:209], v[162:165], v[58:61]
	v_mfma_f32_16x16x32_bf16 v[50:53], v[214:217], v[162:165], v[50:53]
	v_mfma_f32_16x16x32_bf16 v[42:45], v[206:209], v[170:173], v[42:45]
	v_mfma_f32_16x16x32_bf16 v[34:37], v[214:217], v[170:173], v[34:37]
	v_mfma_f32_16x16x32_bf16 v[26:29], v[206:209], v[190:193], v[26:29]
	v_mfma_f32_16x16x32_bf16 v[18:21], v[214:217], v[190:193], v[18:21]
	v_mfma_f32_16x16x32_bf16 v[10:13], v[206:209], v[198:201], v[10:13]
	v_mfma_f32_16x16x32_bf16 v[2:5], v[214:217], v[198:201], v[2:5]
	ds_read_b128 v[162:165], v144
	v_mfma_f32_16x16x32_bf16 v[58:61], v[210:213], v[166:169], v[58:61]
	v_mfma_f32_16x16x32_bf16 v[50:53], v[218:221], v[166:169], v[50:53]
	ds_read_b128 v[170:173], v144 offset:2048
	v_mfma_f32_16x16x32_bf16 v[42:45], v[210:213], v[174:177], v[42:45]
	v_mfma_f32_16x16x32_bf16 v[34:37], v[218:221], v[174:177], v[34:37]
	ds_read_b128 v[190:193], v144 offset:4096
	v_mfma_f32_16x16x32_bf16 v[26:29], v[210:213], v[194:197], v[26:29]
	v_mfma_f32_16x16x32_bf16 v[18:21], v[218:221], v[194:197], v[18:21]
	ds_read_b128 v[198:201], v144 offset:6144
	v_mfma_f32_16x16x32_bf16 v[10:13], v[210:213], v[202:205], v[10:13]
	v_mfma_f32_16x16x32_bf16 v[2:5], v[218:221], v[202:205], v[2:5]
	s_barrier
	s_add_i32 s48, s48, 2
	s_add_u32 s20, s20, 0x100
	s_addc_u32 s21, s21, 0
	s_add_u32 s46, s46, 0x100
	s_addc_u32 s47, s47, 0
.LBB0_297:
	s_add_u32 s22, s20, 0xfffc0080
	s_addc_u32 s23, s21, -1
	s_add_i32 s49, 0, 0x10000
	v_add_u32_e32 v145, s49, v142
	s_cmp_eq_u32 s48, 12
	s_cselect_b32 s25, s9, s23
	s_cselect_b32 s24, s44, s22
	s_cselect_b32 s23, s7, s47
	s_cselect_b32 s22, s45, s46
	s_add_i32 m0, s19, 0xc000
	ds_read_b128 v[166:169], v144 offset:1024
	ds_read_b128 v[174:177], v144 offset:3072
	ds_read_b128 v[194:197], v144 offset:5120
	ds_read_b128 v[202:205], v144 offset:7168
	global_load_lds_dwordx4 v138, s[20:21]
	s_add_i32 m0, s19, 0xe000
	s_nop 0
	global_load_lds_dwordx4 v140, s[20:21]
	s_waitcnt lgkmcnt(8)
	s_barrier
	s_waitcnt lgkmcnt(0)
	s_waitcnt lgkmcnt(0)
	v_mfma_f32_16x16x32_bf16 v[126:129], v[146:149], v[162:165], v[126:129]
	v_mfma_f32_16x16x32_bf16 v[118:121], v[154:157], v[162:165], v[118:121]
	v_mfma_f32_16x16x32_bf16 v[110:113], v[146:149], v[170:173], v[110:113]
	v_mfma_f32_16x16x32_bf16 v[102:105], v[154:157], v[170:173], v[102:105]
	v_mfma_f32_16x16x32_bf16 v[94:97], v[146:149], v[190:193], v[94:97]
	v_mfma_f32_16x16x32_bf16 v[86:89], v[154:157], v[190:193], v[86:89]
	v_mfma_f32_16x16x32_bf16 v[78:81], v[146:149], v[198:201], v[78:81]
	v_mfma_f32_16x16x32_bf16 v[70:73], v[154:157], v[198:201], v[70:73]
	v_mfma_f32_16x16x32_bf16 v[126:129], v[150:153], v[166:169], v[126:129]
	v_mfma_f32_16x16x32_bf16 v[118:121], v[158:161], v[166:169], v[118:121]
	v_mfma_f32_16x16x32_bf16 v[110:113], v[150:153], v[174:177], v[110:113]
	v_mfma_f32_16x16x32_bf16 v[102:105], v[158:161], v[174:177], v[102:105]
	v_mfma_f32_16x16x32_bf16 v[94:97], v[150:153], v[194:197], v[94:97]
	v_mfma_f32_16x16x32_bf16 v[86:89], v[158:161], v[194:197], v[86:89]
	v_mfma_f32_16x16x32_bf16 v[78:81], v[150:153], v[202:205], v[78:81]
	v_mfma_f32_16x16x32_bf16 v[70:73], v[158:161], v[202:205], v[70:73]
	s_barrier
	s_add_i32 s54, 0, 0x14000
	s_add_i32 s49, s49, s35
	v_add_u32_e32 v145, s54, v142
	s_add_u32 s64, s22, 0x80
	s_addc_u32 s65, s23, 0
	s_mov_b32 m0, s49
	ds_read_b128 v[206:209], v145
	ds_read_b128 v[210:213], v145 offset:1024
	ds_read_b128 v[214:217], v145 offset:2048
	ds_read_b128 v[218:221], v145 offset:3072
	global_load_lds_dwordx4 v134, s[22:23]
	s_add_i32 m0, s49, 0x2000
	s_nop 0
	global_load_lds_dwordx4 v130, s[22:23]
	s_barrier
	s_waitcnt lgkmcnt(0)
	s_waitcnt lgkmcnt(0)
	v_mfma_f32_16x16x32_bf16 v[122:125], v[206:209], v[162:165], v[122:125]
	v_mfma_f32_16x16x32_bf16 v[114:117], v[214:217], v[162:165], v[114:117]
	v_mfma_f32_16x16x32_bf16 v[106:109], v[206:209], v[170:173], v[106:109]
	v_mfma_f32_16x16x32_bf16 v[98:101], v[214:217], v[170:173], v[98:101]
	v_mfma_f32_16x16x32_bf16 v[90:93], v[206:209], v[190:193], v[90:93]
	v_mfma_f32_16x16x32_bf16 v[82:85], v[214:217], v[190:193], v[82:85]
	v_mfma_f32_16x16x32_bf16 v[74:77], v[206:209], v[198:201], v[74:77]
	v_mfma_f32_16x16x32_bf16 v[66:69], v[214:217], v[198:201], v[66:69]
	ds_read_b128 v[162:165], v144 offset:16384
	v_mfma_f32_16x16x32_bf16 v[122:125], v[210:213], v[166:169], v[122:125]
	v_mfma_f32_16x16x32_bf16 v[114:117], v[218:221], v[166:169], v[114:117]
	ds_read_b128 v[170:173], v144 offset:18432
	v_mfma_f32_16x16x32_bf16 v[106:109], v[210:213], v[174:177], v[106:109]
	v_mfma_f32_16x16x32_bf16 v[98:101], v[218:221], v[174:177], v[98:101]
	ds_read_b128 v[190:193], v144 offset:20480
	v_mfma_f32_16x16x32_bf16 v[90:93], v[210:213], v[194:197], v[90:93]
	v_mfma_f32_16x16x32_bf16 v[82:85], v[218:221], v[194:197], v[82:85]
	ds_read_b128 v[198:201], v144 offset:22528
	v_mfma_f32_16x16x32_bf16 v[74:77], v[210:213], v[202:205], v[74:77]
	v_mfma_f32_16x16x32_bf16 v[66:69], v[218:221], v[202:205], v[66:69]
	s_barrier
	s_mov_b32 m0, s19
	s_add_u32 s62, s24, 0x80
	s_addc_u32 s63, s25, 0
	ds_read_b128 v[166:169], v144 offset:17408
	ds_read_b128 v[174:177], v144 offset:19456
	ds_read_b128 v[194:197], v144 offset:21504
	ds_read_b128 v[202:205], v144 offset:23552
	global_load_lds_dwordx4 v136, s[24:25]
	s_mov_b32 m0, s36
	s_nop 0
	global_load_lds_dwordx4 v132, s[24:25]
	s_waitcnt vmcnt(8)
	s_barrier
	s_waitcnt lgkmcnt(0)
	s_waitcnt lgkmcnt(0)
	v_mfma_f32_16x16x32_bf16 v[62:65], v[146:149], v[162:165], v[62:65]
	v_mfma_f32_16x16x32_bf16 v[54:57], v[154:157], v[162:165], v[54:57]
	v_mfma_f32_16x16x32_bf16 v[46:49], v[146:149], v[170:173], v[46:49]
	v_mfma_f32_16x16x32_bf16 v[38:41], v[154:157], v[170:173], v[38:41]
	v_mfma_f32_16x16x32_bf16 v[30:33], v[146:149], v[190:193], v[30:33]
	v_mfma_f32_16x16x32_bf16 v[22:25], v[154:157], v[190:193], v[22:25]
	v_mfma_f32_16x16x32_bf16 v[14:17], v[146:149], v[198:201], v[14:17]
	v_mfma_f32_16x16x32_bf16 v[6:9], v[154:157], v[198:201], v[6:9]
	v_mfma_f32_16x16x32_bf16 v[62:65], v[150:153], v[166:169], v[62:65]
	v_mfma_f32_16x16x32_bf16 v[54:57], v[158:161], v[166:169], v[54:57]
	v_mfma_f32_16x16x32_bf16 v[46:49], v[150:153], v[174:177], v[46:49]
	v_mfma_f32_16x16x32_bf16 v[38:41], v[158:161], v[174:177], v[38:41]
	v_mfma_f32_16x16x32_bf16 v[30:33], v[150:153], v[194:197], v[30:33]
	v_mfma_f32_16x16x32_bf16 v[22:25], v[158:161], v[194:197], v[22:25]
	v_mfma_f32_16x16x32_bf16 v[14:17], v[150:153], v[202:205], v[14:17]
	v_mfma_f32_16x16x32_bf16 v[6:9], v[158:161], v[202:205], v[6:9]
	s_barrier
	v_add_u32_e32 v158, 0x18000, v142
	ds_read_b128 v[146:149], v158
	ds_read_b128 v[150:153], v158 offset:1024
	ds_read_b128 v[154:157], v158 offset:2048
	ds_read_b128 v[158:161], v158 offset:3072
	s_add_u32 s50, s22, 0x40000
	s_addc_u32 s51, s23, 0
	s_add_i32 s49, s54, s35
	s_mov_b32 m0, s49
	s_nop 0
	global_load_lds_dwordx4 v134, s[50:51]
	s_add_i32 m0, s49, 0x2000
	s_nop 0
	global_load_lds_dwordx4 v130, s[50:51]
	s_waitcnt vmcnt(6)
	s_barrier
	v_mfma_f32_16x16x32_bf16 v[58:61], v[206:209], v[162:165], v[58:61]
	v_mfma_f32_16x16x32_bf16 v[50:53], v[214:217], v[162:165], v[50:53]
	v_mfma_f32_16x16x32_bf16 v[42:45], v[206:209], v[170:173], v[42:45]
	v_mfma_f32_16x16x32_bf16 v[34:37], v[214:217], v[170:173], v[34:37]
	v_mfma_f32_16x16x32_bf16 v[26:29], v[206:209], v[190:193], v[26:29]
	v_mfma_f32_16x16x32_bf16 v[18:21], v[214:217], v[190:193], v[18:21]
	v_mfma_f32_16x16x32_bf16 v[10:13], v[206:209], v[198:201], v[10:13]
	v_mfma_f32_16x16x32_bf16 v[2:5], v[214:217], v[198:201], v[2:5]
	ds_read_b128 v[162:165], v144 offset:32768
	v_mfma_f32_16x16x32_bf16 v[58:61], v[210:213], v[166:169], v[58:61]
	v_mfma_f32_16x16x32_bf16 v[50:53], v[218:221], v[166:169], v[50:53]
	ds_read_b128 v[170:173], v144 offset:34816
	v_mfma_f32_16x16x32_bf16 v[42:45], v[210:213], v[174:177], v[42:45]
	v_mfma_f32_16x16x32_bf16 v[34:37], v[218:221], v[174:177], v[34:37]
	ds_read_b128 v[190:193], v144 offset:36864
	v_mfma_f32_16x16x32_bf16 v[26:29], v[210:213], v[194:197], v[26:29]
	v_mfma_f32_16x16x32_bf16 v[18:21], v[218:221], v[194:197], v[18:21]
	ds_read_b128 v[198:201], v144 offset:38912
	v_mfma_f32_16x16x32_bf16 v[10:13], v[210:213], v[202:205], v[10:13]
	v_mfma_f32_16x16x32_bf16 v[2:5], v[218:221], v[202:205], v[2:5]
	s_barrier
	s_add_i32 s49, 0, 0x18000
	v_add_u32_e32 v145, s49, v142
	s_add_u32 s24, s24, 0x40000
	s_addc_u32 s25, s25, 0
	s_mov_b32 m0, s37
	ds_read_b128 v[166:169], v144 offset:33792
	ds_read_b128 v[174:177], v144 offset:35840
	ds_read_b128 v[194:197], v144 offset:37888
	ds_read_b128 v[202:205], v144 offset:39936
	global_load_lds_dwordx4 v136, s[24:25]
	s_mov_b32 m0, s38
	s_nop 0
	global_load_lds_dwordx4 v132, s[24:25]
	s_waitcnt lgkmcnt(8)
	s_barrier
	s_waitcnt lgkmcnt(0)
	s_waitcnt lgkmcnt(0)
	v_mfma_f32_16x16x32_bf16 v[126:129], v[146:149], v[162:165], v[126:129]
	v_mfma_f32_16x16x32_bf16 v[118:121], v[154:157], v[162:165], v[118:121]
	v_mfma_f32_16x16x32_bf16 v[110:113], v[146:149], v[170:173], v[110:113]
	v_mfma_f32_16x16x32_bf16 v[102:105], v[154:157], v[170:173], v[102:105]
	v_mfma_f32_16x16x32_bf16 v[94:97], v[146:149], v[190:193], v[94:97]
	v_mfma_f32_16x16x32_bf16 v[86:89], v[154:157], v[190:193], v[86:89]
	v_mfma_f32_16x16x32_bf16 v[78:81], v[146:149], v[198:201], v[78:81]
	v_mfma_f32_16x16x32_bf16 v[70:73], v[154:157], v[198:201], v[70:73]
	v_mfma_f32_16x16x32_bf16 v[126:129], v[150:153], v[166:169], v[126:129]
	v_mfma_f32_16x16x32_bf16 v[118:121], v[158:161], v[166:169], v[118:121]
	v_mfma_f32_16x16x32_bf16 v[110:113], v[150:153], v[174:177], v[110:113]
	v_mfma_f32_16x16x32_bf16 v[102:105], v[158:161], v[174:177], v[102:105]
	v_mfma_f32_16x16x32_bf16 v[94:97], v[150:153], v[194:197], v[94:97]
	v_mfma_f32_16x16x32_bf16 v[86:89], v[158:161], v[194:197], v[86:89]
	v_mfma_f32_16x16x32_bf16 v[78:81], v[150:153], v[202:205], v[78:81]
	v_mfma_f32_16x16x32_bf16 v[70:73], v[158:161], v[202:205], v[70:73]
	s_barrier
	s_add_i32 s24, 0, 0x1c000
	s_add_i32 s25, s49, s35
	v_add_u32_e32 v145, s24, v142
	s_mov_b32 m0, s25
	ds_read_b128 v[206:209], v145
	ds_read_b128 v[210:213], v145 offset:1024
	ds_read_b128 v[214:217], v145 offset:2048
	ds_read_b128 v[218:221], v145 offset:3072
	global_load_lds_dwordx4 v134, s[64:65]
	s_add_i32 m0, s25, 0x2000
	s_nop 0
	global_load_lds_dwordx4 v130, s[64:65]
	s_barrier
	s_waitcnt lgkmcnt(0)
	s_waitcnt lgkmcnt(0)
	v_mfma_f32_16x16x32_bf16 v[122:125], v[206:209], v[162:165], v[122:125]
	v_mfma_f32_16x16x32_bf16 v[114:117], v[214:217], v[162:165], v[114:117]
	v_mfma_f32_16x16x32_bf16 v[106:109], v[206:209], v[170:173], v[106:109]
	v_mfma_f32_16x16x32_bf16 v[98:101], v[214:217], v[170:173], v[98:101]
	v_mfma_f32_16x16x32_bf16 v[90:93], v[206:209], v[190:193], v[90:93]
	v_mfma_f32_16x16x32_bf16 v[82:85], v[214:217], v[190:193], v[82:85]
	v_mfma_f32_16x16x32_bf16 v[74:77], v[206:209], v[198:201], v[74:77]
	v_mfma_f32_16x16x32_bf16 v[66:69], v[214:217], v[198:201], v[66:69]
	ds_read_b128 v[162:165], v144 offset:49152
	v_mfma_f32_16x16x32_bf16 v[122:125], v[210:213], v[166:169], v[122:125]
	v_mfma_f32_16x16x32_bf16 v[114:117], v[218:221], v[166:169], v[114:117]
	ds_read_b128 v[170:173], v144 offset:51200
	v_mfma_f32_16x16x32_bf16 v[106:109], v[210:213], v[174:177], v[106:109]
	v_mfma_f32_16x16x32_bf16 v[98:101], v[218:221], v[174:177], v[98:101]
	ds_read_b128 v[190:193], v144 offset:53248
	v_mfma_f32_16x16x32_bf16 v[90:93], v[210:213], v[194:197], v[90:93]
	v_mfma_f32_16x16x32_bf16 v[82:85], v[218:221], v[194:197], v[82:85]
	ds_read_b128 v[198:201], v144 offset:55296
	v_mfma_f32_16x16x32_bf16 v[74:77], v[210:213], v[202:205], v[74:77]
	v_mfma_f32_16x16x32_bf16 v[66:69], v[218:221], v[202:205], v[66:69]
	s_barrier
	s_mov_b32 m0, s39
	ds_read_b128 v[166:169], v144 offset:50176
	ds_read_b128 v[174:177], v144 offset:52224
	ds_read_b128 v[194:197], v144 offset:54272
	ds_read_b128 v[202:205], v144 offset:56320
	global_load_lds_dwordx4 v136, s[62:63]
	s_mov_b32 m0, s40
	s_nop 0
	global_load_lds_dwordx4 v132, s[62:63]
	s_waitcnt vmcnt(8)
	s_barrier
	s_waitcnt lgkmcnt(0)
	s_waitcnt lgkmcnt(0)
	v_mfma_f32_16x16x32_bf16 v[62:65], v[146:149], v[162:165], v[62:65]
	v_mfma_f32_16x16x32_bf16 v[54:57], v[154:157], v[162:165], v[54:57]
	v_mfma_f32_16x16x32_bf16 v[46:49], v[146:149], v[170:173], v[46:49]
	v_mfma_f32_16x16x32_bf16 v[38:41], v[154:157], v[170:173], v[38:41]
	v_mfma_f32_16x16x32_bf16 v[30:33], v[146:149], v[190:193], v[30:33]
	v_mfma_f32_16x16x32_bf16 v[22:25], v[154:157], v[190:193], v[22:25]
	v_mfma_f32_16x16x32_bf16 v[14:17], v[146:149], v[198:201], v[14:17]
	v_mfma_f32_16x16x32_bf16 v[6:9], v[154:157], v[198:201], v[6:9]
	v_mfma_f32_16x16x32_bf16 v[62:65], v[150:153], v[166:169], v[62:65]
	v_mfma_f32_16x16x32_bf16 v[54:57], v[158:161], v[166:169], v[54:57]
	v_mfma_f32_16x16x32_bf16 v[46:49], v[150:153], v[174:177], v[46:49]
	v_mfma_f32_16x16x32_bf16 v[38:41], v[158:161], v[174:177], v[38:41]
	v_mfma_f32_16x16x32_bf16 v[30:33], v[150:153], v[194:197], v[30:33]
	v_mfma_f32_16x16x32_bf16 v[22:25], v[158:161], v[194:197], v[22:25]
	v_mfma_f32_16x16x32_bf16 v[14:17], v[150:153], v[202:205], v[14:17]
	v_mfma_f32_16x16x32_bf16 v[6:9], v[158:161], v[202:205], v[6:9]
	s_barrier
	v_add_u32_e32 v158, 0x10000, v142
	ds_read_b128 v[146:149], v158
	ds_read_b128 v[150:153], v158 offset:1024
	ds_read_b128 v[154:157], v158 offset:2048
	ds_read_b128 v[158:161], v158 offset:3072
	s_add_u32 s22, s22, 0x40080
	s_addc_u32 s23, s23, 0
	s_add_i32 s24, s24, s35
	s_mov_b32 m0, s24
	s_nop 0
	global_load_lds_dwordx4 v134, s[22:23]
	s_add_i32 m0, s24, 0x2000
	s_nop 0
	global_load_lds_dwordx4 v130, s[22:23]
	s_waitcnt vmcnt(6)
	s_barrier
	v_mfma_f32_16x16x32_bf16 v[58:61], v[206:209], v[162:165], v[58:61]
	v_mfma_f32_16x16x32_bf16 v[50:53], v[214:217], v[162:165], v[50:53]
	v_mfma_f32_16x16x32_bf16 v[42:45], v[206:209], v[170:173], v[42:45]
	v_mfma_f32_16x16x32_bf16 v[34:37], v[214:217], v[170:173], v[34:37]
	v_mfma_f32_16x16x32_bf16 v[26:29], v[206:209], v[190:193], v[26:29]
	v_mfma_f32_16x16x32_bf16 v[18:21], v[214:217], v[190:193], v[18:21]
	v_mfma_f32_16x16x32_bf16 v[10:13], v[206:209], v[198:201], v[10:13]
	v_mfma_f32_16x16x32_bf16 v[2:5], v[214:217], v[198:201], v[2:5]
	ds_read_b128 v[162:165], v144
	v_mfma_f32_16x16x32_bf16 v[58:61], v[210:213], v[166:169], v[58:61]
	v_mfma_f32_16x16x32_bf16 v[50:53], v[218:221], v[166:169], v[50:53]
	ds_read_b128 v[170:173], v144 offset:2048
	v_mfma_f32_16x16x32_bf16 v[42:45], v[210:213], v[174:177], v[42:45]
	v_mfma_f32_16x16x32_bf16 v[34:37], v[218:221], v[174:177], v[34:37]
	ds_read_b128 v[190:193], v144 offset:4096
	v_mfma_f32_16x16x32_bf16 v[26:29], v[210:213], v[194:197], v[26:29]
	v_mfma_f32_16x16x32_bf16 v[18:21], v[218:221], v[194:197], v[18:21]
	ds_read_b128 v[198:201], v144 offset:6144
	v_mfma_f32_16x16x32_bf16 v[10:13], v[210:213], v[202:205], v[10:13]
	v_mfma_f32_16x16x32_bf16 v[2:5], v[218:221], v[202:205], v[2:5]
	s_barrier
	s_add_i32 s48, s48, 2
	s_add_u32 s20, s20, 0x100
	s_addc_u32 s21, s21, 0
	s_add_u32 s46, s46, 0x100
	s_addc_u32 s47, s47, 0
	s_cmp_gt_u32 s48, 13
	s_cbranch_scc0 .LBB0_297
	s_waitcnt lgkmcnt(0)
	v_mov_b32_e32 v226, 0xbfb8aa3b
	v_mov_b32_e32 v227, 0xbfb8aa3b
	v_mov_b32_e32 v228, 1.0
	v_mov_b32_e32 v229, 1.0
	v_pk_mul_f32 v[222:223], v[126:127], v[226:227]
	v_exp_f32_e32 v222, v222
	v_exp_f32_e32 v223, v223
	s_nop 0
	v_pk_add_f32 v[222:223], v[222:223], v[228:229]
	v_rcp_f32_e32 v222, v222
	v_rcp_f32_e32 v223, v223
	v_pk_mul_f32 v[224:225], v[128:129], v[226:227]
	v_exp_f32_e32 v224, v224
	v_exp_f32_e32 v225, v225
	v_pk_mul_f32 v[222:223], v[126:127], v[222:223]
	v_pk_add_f32 v[224:225], v[224:225], v[228:229]
	v_rcp_f32_e32 v224, v224
	v_rcp_f32_e32 v225, v225
	v_pk_mul_f32 v[122:123], v[222:223], v[122:123]
	v_pk_mul_f32 v[222:223], v[118:119], v[226:227]
	v_exp_f32_e32 v222, v222
	v_exp_f32_e32 v223, v223
	v_pk_mul_f32 v[224:225], v[128:129], v[224:225]
	v_pk_add_f32 v[222:223], v[222:223], v[228:229]
	v_rcp_f32_e32 v222, v222
	v_rcp_f32_e32 v223, v223
	v_pk_mul_f32 v[124:125], v[224:225], v[124:125]
	v_pk_mul_f32 v[224:225], v[120:121], v[226:227]
	v_exp_f32_e32 v224, v224
	v_exp_f32_e32 v225, v225
	v_pk_mul_f32 v[222:223], v[118:119], v[222:223]
	v_pk_add_f32 v[224:225], v[224:225], v[228:229]
	v_rcp_f32_e32 v224, v224
	v_rcp_f32_e32 v225, v225
	v_pk_mul_f32 v[114:115], v[222:223], v[114:115]
	v_pk_mul_f32 v[222:223], v[110:111], v[226:227]
	v_exp_f32_e32 v222, v222
	v_exp_f32_e32 v223, v223
	v_pk_mul_f32 v[224:225], v[120:121], v[224:225]
	v_pk_add_f32 v[222:223], v[222:223], v[228:229]
	v_rcp_f32_e32 v222, v222
	v_rcp_f32_e32 v223, v223
	v_pk_mul_f32 v[116:117], v[224:225], v[116:117]
	v_lshl_or_b32 v146, s43, 7, v143
	v_lshl_add_u32 v145, s18, 8, v1
	v_ashrrev_i32_e32 v147, 31, v146
	s_movk_i32 s7, 0x1700
	s_and_b64 vcc, exec, s[4:5]
	s_mov_b32 s43, s6
	s_mov_b32 s18, s8
	s_mov_b64 s[22:23], s[14:15]
	v_cvt_pk_bf16_f32 v120, v114, v115
	v_mov_b64_e32 v[114:115], s[2:3]
	v_cvt_pk_bf16_f32 v118, v122, v123
	v_cvt_pk_bf16_f32 v121, v116, v117
	v_mad_i64_i32 v[122:123], s[20:21], v145, s7, v[114:115]
	v_lshlrev_b64 v[116:117], 1, v[146:147]
	v_cvt_pk_bf16_f32 v119, v124, v125
	v_lshl_add_u64 v[122:123], v[122:123], 0, v[116:117]
	global_store_dwordx4 v[122:123], v[118:121], off
	s_nop 1
	v_pk_mul_f32 v[224:225], v[112:113], v[226:227]
	v_exp_f32_e32 v224, v224
	v_exp_f32_e32 v225, v225
	v_pk_mul_f32 v[222:223], v[110:111], v[222:223]
	v_pk_add_f32 v[224:225], v[224:225], v[228:229]
	v_rcp_f32_e32 v224, v224
	v_rcp_f32_e32 v225, v225
	v_pk_mul_f32 v[106:107], v[222:223], v[106:107]
	v_pk_mul_f32 v[222:223], v[102:103], v[226:227]
	v_exp_f32_e32 v222, v222
	v_exp_f32_e32 v223, v223
	v_pk_mul_f32 v[224:225], v[112:113], v[224:225]
	v_pk_add_f32 v[222:223], v[222:223], v[228:229]
	v_rcp_f32_e32 v222, v222
	v_rcp_f32_e32 v223, v223
	v_pk_mul_f32 v[108:109], v[224:225], v[108:109]
	v_pk_mul_f32 v[224:225], v[104:105], v[226:227]
	v_exp_f32_e32 v224, v224
	v_exp_f32_e32 v225, v225
	v_pk_mul_f32 v[222:223], v[102:103], v[222:223]
	v_pk_add_f32 v[224:225], v[224:225], v[228:229]
	v_rcp_f32_e32 v224, v224
	v_rcp_f32_e32 v225, v225
	v_pk_mul_f32 v[102:103], v[222:223], v[98:99]
	v_pk_mul_f32 v[222:223], v[94:95], v[226:227]
	v_exp_f32_e32 v222, v222
	v_exp_f32_e32 v223, v223
	v_pk_mul_f32 v[224:225], v[104:105], v[224:225]
	v_pk_add_f32 v[222:223], v[222:223], v[228:229]
	v_rcp_f32_e32 v222, v222
	v_rcp_f32_e32 v223, v223
	v_pk_mul_f32 v[104:105], v[224:225], v[100:101]
	v_cvt_pk_bf16_f32 v100, v102, v103
	v_or_b32_e32 v102, 16, v145
	v_mad_i64_i32 v[102:103], s[20:21], v102, s7, v[114:115]
	v_cvt_pk_bf16_f32 v98, v106, v107
	v_cvt_pk_bf16_f32 v99, v108, v109
	v_cvt_pk_bf16_f32 v101, v104, v105
	v_lshl_add_u64 v[102:103], v[102:103], 0, v[116:117]
	global_store_dwordx4 v[102:103], v[98:101], off
	s_nop 1
	v_pk_mul_f32 v[224:225], v[96:97], v[226:227]
	v_exp_f32_e32 v224, v224
	v_exp_f32_e32 v225, v225
	v_pk_mul_f32 v[222:223], v[94:95], v[222:223]
	v_pk_add_f32 v[224:225], v[224:225], v[228:229]
	v_rcp_f32_e32 v224, v224
	v_rcp_f32_e32 v225, v225
	v_pk_mul_f32 v[90:91], v[222:223], v[90:91]
	v_pk_mul_f32 v[222:223], v[86:87], v[226:227]
	v_exp_f32_e32 v222, v222
	v_exp_f32_e32 v223, v223
	v_pk_mul_f32 v[224:225], v[96:97], v[224:225]
	v_pk_add_f32 v[222:223], v[222:223], v[228:229]
	v_rcp_f32_e32 v222, v222
	v_rcp_f32_e32 v223, v223
	v_pk_mul_f32 v[92:93], v[224:225], v[92:93]
	v_pk_mul_f32 v[224:225], v[88:89], v[226:227]
	v_exp_f32_e32 v224, v224
	v_exp_f32_e32 v225, v225
	v_pk_mul_f32 v[222:223], v[86:87], v[222:223]
	v_pk_add_f32 v[224:225], v[224:225], v[228:229]
	v_rcp_f32_e32 v224, v224
	v_rcp_f32_e32 v225, v225
	v_pk_mul_f32 v[86:87], v[222:223], v[82:83]
	v_pk_mul_f32 v[222:223], v[78:79], v[226:227]
	v_exp_f32_e32 v222, v222
	v_exp_f32_e32 v223, v223
	v_pk_mul_f32 v[224:225], v[88:89], v[224:225]
	v_pk_add_f32 v[222:223], v[222:223], v[228:229]
	v_rcp_f32_e32 v222, v222
	v_rcp_f32_e32 v223, v223
	v_pk_mul_f32 v[88:89], v[224:225], v[84:85]
	v_cvt_pk_bf16_f32 v84, v86, v87
	v_or_b32_e32 v86, 32, v145
	v_mad_i64_i32 v[86:87], s[20:21], v86, s7, v[114:115]
	v_cvt_pk_bf16_f32 v82, v90, v91
	v_cvt_pk_bf16_f32 v83, v92, v93
	v_cvt_pk_bf16_f32 v85, v88, v89
	v_lshl_add_u64 v[86:87], v[86:87], 0, v[116:117]
	global_store_dwordx4 v[86:87], v[82:85], off
	s_nop 1
	v_pk_mul_f32 v[224:225], v[80:81], v[226:227]
	v_exp_f32_e32 v224, v224
	v_exp_f32_e32 v225, v225
	v_pk_mul_f32 v[222:223], v[78:79], v[222:223]
	v_pk_add_f32 v[224:225], v[224:225], v[228:229]
	v_rcp_f32_e32 v224, v224
	v_rcp_f32_e32 v225, v225
	v_pk_mul_f32 v[74:75], v[222:223], v[74:75]
	v_pk_mul_f32 v[222:223], v[70:71], v[226:227]
	v_exp_f32_e32 v222, v222
	v_exp_f32_e32 v223, v223
	v_pk_mul_f32 v[224:225], v[80:81], v[224:225]
	v_pk_add_f32 v[222:223], v[222:223], v[228:229]
	v_rcp_f32_e32 v222, v222
	v_rcp_f32_e32 v223, v223
	v_pk_mul_f32 v[76:77], v[224:225], v[76:77]
	v_pk_mul_f32 v[224:225], v[72:73], v[226:227]
	v_exp_f32_e32 v224, v224
	v_exp_f32_e32 v225, v225
	v_pk_mul_f32 v[222:223], v[70:71], v[222:223]
	v_pk_add_f32 v[224:225], v[224:225], v[228:229]
	v_rcp_f32_e32 v224, v224
	v_rcp_f32_e32 v225, v225
	v_pk_mul_f32 v[70:71], v[222:223], v[66:67]
	v_pk_mul_f32 v[222:223], v[62:63], v[226:227]
	v_exp_f32_e32 v222, v222
	v_exp_f32_e32 v223, v223
	v_pk_mul_f32 v[224:225], v[72:73], v[224:225]
	v_pk_add_f32 v[222:223], v[222:223], v[228:229]
	v_rcp_f32_e32 v222, v222
	v_rcp_f32_e32 v223, v223
	v_pk_mul_f32 v[72:73], v[224:225], v[68:69]
	v_cvt_pk_bf16_f32 v68, v70, v71
	v_or_b32_e32 v70, 48, v145
	v_mad_i64_i32 v[70:71], s[20:21], v70, s7, v[114:115]
	v_cvt_pk_bf16_f32 v66, v74, v75
	v_cvt_pk_bf16_f32 v67, v76, v77
	v_cvt_pk_bf16_f32 v69, v72, v73
	v_lshl_add_u64 v[70:71], v[70:71], 0, v[116:117]
	global_store_dwordx4 v[70:71], v[66:69], off
	s_nop 1
	v_pk_mul_f32 v[224:225], v[64:65], v[226:227]
	v_exp_f32_e32 v224, v224
	v_exp_f32_e32 v225, v225
	v_pk_mul_f32 v[222:223], v[62:63], v[222:223]
	v_pk_add_f32 v[224:225], v[224:225], v[228:229]
	v_rcp_f32_e32 v224, v224
	v_rcp_f32_e32 v225, v225
	v_pk_mul_f32 v[58:59], v[222:223], v[58:59]
	v_pk_mul_f32 v[222:223], v[54:55], v[226:227]
	v_exp_f32_e32 v222, v222
	v_exp_f32_e32 v223, v223
	v_pk_mul_f32 v[224:225], v[64:65], v[224:225]
	v_pk_add_f32 v[222:223], v[222:223], v[228:229]
	v_rcp_f32_e32 v222, v222
	v_rcp_f32_e32 v223, v223
	v_pk_mul_f32 v[60:61], v[224:225], v[60:61]
	v_pk_mul_f32 v[224:225], v[56:57], v[226:227]
	v_exp_f32_e32 v224, v224
	v_exp_f32_e32 v225, v225
	v_pk_mul_f32 v[222:223], v[54:55], v[222:223]
	v_pk_add_f32 v[224:225], v[224:225], v[228:229]
	v_rcp_f32_e32 v224, v224
	v_rcp_f32_e32 v225, v225
	v_pk_mul_f32 v[54:55], v[222:223], v[50:51]
	v_pk_mul_f32 v[222:223], v[46:47], v[226:227]
	v_exp_f32_e32 v222, v222
	v_exp_f32_e32 v223, v223
	v_pk_mul_f32 v[224:225], v[56:57], v[224:225]
	v_pk_add_f32 v[222:223], v[222:223], v[228:229]
	v_rcp_f32_e32 v222, v222
	v_rcp_f32_e32 v223, v223
	v_pk_mul_f32 v[56:57], v[224:225], v[52:53]
	v_add_u32_e32 v68, 0x80, v145
	v_cvt_pk_bf16_f32 v52, v54, v55
	v_mad_i64_i32 v[54:55], s[20:21], v68, s7, v[114:115]
	v_cvt_pk_bf16_f32 v50, v58, v59
	v_cvt_pk_bf16_f32 v51, v60, v61
	v_cvt_pk_bf16_f32 v53, v56, v57
	v_lshl_add_u64 v[54:55], v[54:55], 0, v[116:117]
	global_store_dwordx4 v[54:55], v[50:53], off
	s_nop 1
	v_pk_mul_f32 v[224:225], v[48:49], v[226:227]
	v_exp_f32_e32 v224, v224
	v_exp_f32_e32 v225, v225
	v_pk_mul_f32 v[222:223], v[46:47], v[222:223]
	v_pk_add_f32 v[224:225], v[224:225], v[228:229]
	v_rcp_f32_e32 v224, v224
	v_rcp_f32_e32 v225, v225
	v_pk_mul_f32 v[42:43], v[222:223], v[42:43]
	v_pk_mul_f32 v[222:223], v[38:39], v[226:227]
	v_exp_f32_e32 v222, v222
	v_exp_f32_e32 v223, v223
	v_pk_mul_f32 v[224:225], v[48:49], v[224:225]
	v_pk_add_f32 v[222:223], v[222:223], v[228:229]
	v_rcp_f32_e32 v222, v222
	v_rcp_f32_e32 v223, v223
	v_pk_mul_f32 v[44:45], v[224:225], v[44:45]
	v_pk_mul_f32 v[224:225], v[40:41], v[226:227]
	v_exp_f32_e32 v224, v224
	v_exp_f32_e32 v225, v225
	v_pk_mul_f32 v[222:223], v[38:39], v[222:223]
	v_pk_add_f32 v[224:225], v[224:225], v[228:229]
	v_rcp_f32_e32 v224, v224
	v_rcp_f32_e32 v225, v225
	v_pk_mul_f32 v[38:39], v[222:223], v[34:35]
	v_pk_mul_f32 v[222:223], v[30:31], v[226:227]
	v_exp_f32_e32 v222, v222
	v_exp_f32_e32 v223, v223
	v_pk_mul_f32 v[224:225], v[40:41], v[224:225]
	v_pk_add_f32 v[222:223], v[222:223], v[228:229]
	v_rcp_f32_e32 v222, v222
	v_rcp_f32_e32 v223, v223
	v_pk_mul_f32 v[40:41], v[224:225], v[36:37]
	v_cvt_pk_bf16_f32 v36, v38, v39
	v_add_u32_e32 v38, 0x90, v145
	v_mad_i64_i32 v[38:39], s[20:21], v38, s7, v[114:115]
	v_cvt_pk_bf16_f32 v34, v42, v43
	v_cvt_pk_bf16_f32 v35, v44, v45
	v_cvt_pk_bf16_f32 v37, v40, v41
	v_lshl_add_u64 v[38:39], v[38:39], 0, v[116:117]
	global_store_dwordx4 v[38:39], v[34:37], off
	s_nop 1
	v_pk_mul_f32 v[224:225], v[32:33], v[226:227]
	v_exp_f32_e32 v224, v224
	v_exp_f32_e32 v225, v225
	v_pk_mul_f32 v[222:223], v[30:31], v[222:223]
	v_pk_add_f32 v[224:225], v[224:225], v[228:229]
	v_rcp_f32_e32 v224, v224
	v_rcp_f32_e32 v225, v225
	v_pk_mul_f32 v[26:27], v[222:223], v[26:27]
	v_pk_mul_f32 v[222:223], v[22:23], v[226:227]
	v_exp_f32_e32 v222, v222
	v_exp_f32_e32 v223, v223
	v_pk_mul_f32 v[224:225], v[32:33], v[224:225]
	v_pk_add_f32 v[222:223], v[222:223], v[228:229]
	v_rcp_f32_e32 v222, v222
	v_rcp_f32_e32 v223, v223
	v_pk_mul_f32 v[28:29], v[224:225], v[28:29]
	v_pk_mul_f32 v[224:225], v[24:25], v[226:227]
	v_exp_f32_e32 v224, v224
	v_exp_f32_e32 v225, v225
	v_pk_mul_f32 v[222:223], v[22:23], v[222:223]
	v_pk_add_f32 v[224:225], v[224:225], v[228:229]
	v_rcp_f32_e32 v224, v224
	v_rcp_f32_e32 v225, v225
	v_pk_mul_f32 v[22:23], v[222:223], v[18:19]
	v_pk_mul_f32 v[222:223], v[14:15], v[226:227]
	v_exp_f32_e32 v222, v222
	v_exp_f32_e32 v223, v223
	v_pk_mul_f32 v[224:225], v[24:25], v[224:225]
	v_pk_add_f32 v[222:223], v[222:223], v[228:229]
	v_rcp_f32_e32 v222, v222
	v_rcp_f32_e32 v223, v223
	v_pk_mul_f32 v[24:25], v[224:225], v[20:21]
	v_cvt_pk_bf16_f32 v20, v22, v23
	v_add_u32_e32 v22, 0xa0, v145
	v_mad_i64_i32 v[22:23], s[20:21], v22, s7, v[114:115]
	v_cvt_pk_bf16_f32 v18, v26, v27
	v_cvt_pk_bf16_f32 v19, v28, v29
	v_cvt_pk_bf16_f32 v21, v24, v25
	v_lshl_add_u64 v[22:23], v[22:23], 0, v[116:117]
	global_store_dwordx4 v[22:23], v[18:21], off
	s_nop 1
	v_pk_mul_f32 v[224:225], v[16:17], v[226:227]
	v_exp_f32_e32 v224, v224
	v_exp_f32_e32 v225, v225
	v_pk_mul_f32 v[222:223], v[14:15], v[222:223]
	v_pk_add_f32 v[224:225], v[224:225], v[228:229]
	v_rcp_f32_e32 v224, v224
	v_rcp_f32_e32 v225, v225
	v_pk_mul_f32 v[10:11], v[222:223], v[10:11]
	v_pk_mul_f32 v[222:223], v[6:7], v[226:227]
	v_exp_f32_e32 v222, v222
	v_exp_f32_e32 v223, v223
	v_pk_mul_f32 v[224:225], v[16:17], v[224:225]
	v_pk_add_f32 v[222:223], v[222:223], v[228:229]
	v_rcp_f32_e32 v222, v222
	v_rcp_f32_e32 v223, v223
	v_pk_mul_f32 v[12:13], v[224:225], v[12:13]
	v_pk_mul_f32 v[224:225], v[8:9], v[226:227]
	v_exp_f32_e32 v224, v224
	v_exp_f32_e32 v225, v225
	v_pk_mul_f32 v[222:223], v[6:7], v[222:223]
	v_pk_add_f32 v[224:225], v[224:225], v[228:229]
	v_rcp_f32_e32 v224, v224
	v_rcp_f32_e32 v225, v225
	v_pk_mul_f32 v[6:7], v[222:223], v[2:3]
	v_pk_mul_f32 v[224:225], v[8:9], v[224:225]
	v_pk_mul_f32 v[8:9], v[224:225], v[4:5]
	v_cvt_pk_bf16_f32 v4, v6, v7
	v_add_u32_e32 v6, 0xb0, v145
	v_mad_i64_i32 v[6:7], s[20:21], v6, s7, v[114:115]
	v_cvt_pk_bf16_f32 v2, v10, v11
	v_cvt_pk_bf16_f32 v3, v12, v13
	v_cvt_pk_bf16_f32 v5, v8, v9
	v_lshl_add_u64 v[6:7], v[6:7], 0, v[116:117]
	s_mov_b64 s[20:21], s[12:13]
	global_store_dwordx4 v[6:7], v[2:5], off
	s_cbranch_vccz .LBB0_294
	s_waitcnt vmcnt(0)
	s_cmpk_gt_u32 s28, 0xff
	s_cbranch_scc1 .LBB0_301
	s_barrier

.LBB0_373:
	s_add_u32 s46, s16, 0x100
	s_addc_u32 s47, s17, 0
	s_mov_b32 s48, -2
	s_add_u32 s16, s14, 0x100
	s_addc_u32 s17, s15, 0
	s_add_i32 s49, 0, 0x10000
	v_add_u32_e32 v154, s49, v164
	ds_read_b128 v[142:145], v154
	ds_read_b128 v[146:149], v154 offset:1024
	ds_read_b128 v[150:153], v154 offset:2048
	ds_read_b128 v[154:157], v154 offset:3072
	s_cmp_eq_u32 s48, 40
	s_cselect_b32 s21, s7, s17
	s_cselect_b32 s20, s6, s16
	s_cselect_b32 s19, s9, s47
	s_cselect_b32 s18, s8, s46
	v_lshl_add_u64 v[162:163], s[14:15], 0, v[138:139]
	s_add_i32 m0, s35, 0xc000
	ds_read_b128 v[158:161], v166
	ds_read_b128 v[168:171], v166 offset:1024
	ds_read_b128 v[172:175], v166 offset:2048
	ds_read_b128 v[190:193], v166 offset:3072
	ds_read_b128 v[194:197], v166 offset:4096
	ds_read_b128 v[198:201], v166 offset:5120
	ds_read_b128 v[202:205], v166 offset:6144
	ds_read_b128 v[206:209], v166 offset:7168
	global_load_lds_dwordx4 v[162:163], off
	v_lshl_add_u64 v[162:163], s[14:15], 0, v[140:141]
	s_add_i32 m0, s35, 0xe000
	s_nop 0
	global_load_lds_dwordx4 v[162:163], off
	s_waitcnt lgkmcnt(8)
	s_barrier
	s_waitcnt lgkmcnt(0)
	s_waitcnt lgkmcnt(0)
	v_mfma_f32_16x16x32_bf16 v[126:129], v[142:145], v[158:161], 0
	v_mfma_f32_16x16x32_bf16 v[122:125], v[150:153], v[158:161], 0
	v_mfma_f32_16x16x32_bf16 v[110:113], v[142:145], v[172:175], 0
	v_mfma_f32_16x16x32_bf16 v[106:109], v[150:153], v[172:175], 0
	v_mfma_f32_16x16x32_bf16 v[94:97], v[142:145], v[194:197], 0
	v_mfma_f32_16x16x32_bf16 v[90:93], v[150:153], v[194:197], 0
	v_mfma_f32_16x16x32_bf16 v[78:81], v[142:145], v[202:205], 0
	v_mfma_f32_16x16x32_bf16 v[74:77], v[150:153], v[202:205], 0
	v_mfma_f32_16x16x32_bf16 v[126:129], v[146:149], v[168:171], v[126:129]
	v_mfma_f32_16x16x32_bf16 v[122:125], v[154:157], v[168:171], v[122:125]
	v_mfma_f32_16x16x32_bf16 v[110:113], v[146:149], v[190:193], v[110:113]
	v_mfma_f32_16x16x32_bf16 v[106:109], v[154:157], v[190:193], v[106:109]
	v_mfma_f32_16x16x32_bf16 v[94:97], v[146:149], v[198:201], v[94:97]
	v_mfma_f32_16x16x32_bf16 v[90:93], v[154:157], v[198:201], v[90:93]
	v_mfma_f32_16x16x32_bf16 v[78:81], v[146:149], v[206:209], v[78:81]
	v_mfma_f32_16x16x32_bf16 v[74:77], v[154:157], v[206:209], v[74:77]
	s_barrier
	s_add_i32 s50, 0, 0x14000
	v_add_u32_e32 v162, s50, v164
	s_add_i32 s14, s49, s34
	ds_read_b128 v[210:213], v162
	ds_read_b128 v[214:217], v162 offset:1024
	ds_read_b128 v[218:221], v162 offset:2048
	ds_read_b128 v[222:225], v162 offset:3072
	s_add_u32 s64, s18, 0x80
	s_addc_u32 s65, s19, 0
	s_mov_b32 m0, s14
	s_nop 0
	global_load_lds_dwordx4 v132, s[18:19]
	s_add_i32 m0, s14, 0x2000
	s_nop 0
	global_load_lds_dwordx4 v136, s[18:19]
	s_barrier
	s_waitcnt lgkmcnt(0)
	s_waitcnt lgkmcnt(0)
	v_mfma_f32_16x16x32_bf16 v[118:121], v[210:213], v[158:161], 0
	v_mfma_f32_16x16x32_bf16 v[114:117], v[218:221], v[158:161], 0
	v_mfma_f32_16x16x32_bf16 v[102:105], v[210:213], v[172:175], 0
	v_mfma_f32_16x16x32_bf16 v[98:101], v[218:221], v[172:175], 0
	v_mfma_f32_16x16x32_bf16 v[86:89], v[210:213], v[194:197], 0
	v_mfma_f32_16x16x32_bf16 v[82:85], v[218:221], v[194:197], 0
	v_mfma_f32_16x16x32_bf16 v[70:73], v[210:213], v[202:205], 0
	v_mfma_f32_16x16x32_bf16 v[66:69], v[218:221], v[202:205], 0
	ds_read_b128 v[158:161], v166 offset:16384
	v_mfma_f32_16x16x32_bf16 v[118:121], v[214:217], v[168:171], v[118:121]
	v_mfma_f32_16x16x32_bf16 v[114:117], v[222:225], v[168:171], v[114:117]
	ds_read_b128 v[172:175], v166 offset:18432
	v_mfma_f32_16x16x32_bf16 v[102:105], v[214:217], v[190:193], v[102:105]
	v_mfma_f32_16x16x32_bf16 v[98:101], v[222:225], v[190:193], v[98:101]
	ds_read_b128 v[194:197], v166 offset:20480
	v_mfma_f32_16x16x32_bf16 v[86:89], v[214:217], v[198:201], v[86:89]
	v_mfma_f32_16x16x32_bf16 v[82:85], v[222:225], v[198:201], v[82:85]
	ds_read_b128 v[202:205], v166 offset:22528
	v_mfma_f32_16x16x32_bf16 v[70:73], v[214:217], v[206:209], v[70:73]
	v_mfma_f32_16x16x32_bf16 v[66:69], v[222:225], v[206:209], v[66:69]
	s_barrier
	s_mov_b32 m0, s35
	s_add_u32 s62, s20, 0x80
	s_addc_u32 s63, s21, 0
	ds_read_b128 v[168:171], v166 offset:17408
	ds_read_b128 v[190:193], v166 offset:19456
	ds_read_b128 v[198:201], v166 offset:21504
	ds_read_b128 v[206:209], v166 offset:23552
	global_load_lds_dwordx4 v130, s[20:21]
	s_mov_b32 m0, s36
	s_nop 0
	global_load_lds_dwordx4 v134, s[20:21]
	s_waitcnt vmcnt(8)
	s_barrier
	s_waitcnt lgkmcnt(0)
	s_waitcnt lgkmcnt(0)
	v_mfma_f32_16x16x32_bf16 v[62:65], v[142:145], v[158:161], 0
	v_mfma_f32_16x16x32_bf16 v[58:61], v[150:153], v[158:161], 0
	v_mfma_f32_16x16x32_bf16 v[46:49], v[142:145], v[172:175], 0
	v_mfma_f32_16x16x32_bf16 v[42:45], v[150:153], v[172:175], 0
	v_mfma_f32_16x16x32_bf16 v[30:33], v[142:145], v[194:197], 0
	v_mfma_f32_16x16x32_bf16 v[26:29], v[150:153], v[194:197], 0
	v_mfma_f32_16x16x32_bf16 v[14:17], v[142:145], v[202:205], 0
	v_mfma_f32_16x16x32_bf16 v[10:13], v[150:153], v[202:205], 0
	v_mfma_f32_16x16x32_bf16 v[62:65], v[146:149], v[168:171], v[62:65]
	v_mfma_f32_16x16x32_bf16 v[58:61], v[154:157], v[168:171], v[58:61]
	v_mfma_f32_16x16x32_bf16 v[46:49], v[146:149], v[190:193], v[46:49]
	v_mfma_f32_16x16x32_bf16 v[42:45], v[154:157], v[190:193], v[42:45]
	v_mfma_f32_16x16x32_bf16 v[30:33], v[146:149], v[198:201], v[30:33]
	v_mfma_f32_16x16x32_bf16 v[26:29], v[154:157], v[198:201], v[26:29]
	v_mfma_f32_16x16x32_bf16 v[14:17], v[146:149], v[206:209], v[14:17]
	v_mfma_f32_16x16x32_bf16 v[10:13], v[154:157], v[206:209], v[10:13]
	s_barrier
	v_add_u32_e32 v154, 0x18000, v164
	ds_read_b128 v[142:145], v154
	ds_read_b128 v[146:149], v154 offset:1024
	ds_read_b128 v[150:153], v154 offset:2048
	ds_read_b128 v[154:157], v154 offset:3072
	s_add_u32 s14, s18, 0xb0000
	s_addc_u32 s15, s19, 0
	s_add_i32 s49, s50, s34
	s_mov_b32 m0, s49
	s_nop 0
	global_load_lds_dwordx4 v132, s[14:15]
	s_add_i32 m0, s49, 0x2000
	s_nop 0
	global_load_lds_dwordx4 v136, s[14:15]
	s_waitcnt vmcnt(6)
	s_barrier
	v_mfma_f32_16x16x32_bf16 v[54:57], v[210:213], v[158:161], 0
	v_mfma_f32_16x16x32_bf16 v[50:53], v[218:221], v[158:161], 0
	v_mfma_f32_16x16x32_bf16 v[38:41], v[210:213], v[172:175], 0
	v_mfma_f32_16x16x32_bf16 v[34:37], v[218:221], v[172:175], 0
	v_mfma_f32_16x16x32_bf16 v[22:25], v[210:213], v[194:197], 0
	v_mfma_f32_16x16x32_bf16 v[18:21], v[218:221], v[194:197], 0
	v_mfma_f32_16x16x32_bf16 v[6:9], v[210:213], v[202:205], 0
	v_mfma_f32_16x16x32_bf16 v[2:5], v[218:221], v[202:205], 0
	ds_read_b128 v[158:161], v166 offset:32768
	v_mfma_f32_16x16x32_bf16 v[54:57], v[214:217], v[168:171], v[54:57]
	v_mfma_f32_16x16x32_bf16 v[50:53], v[222:225], v[168:171], v[50:53]
	ds_read_b128 v[172:175], v166 offset:34816
	v_mfma_f32_16x16x32_bf16 v[38:41], v[214:217], v[190:193], v[38:41]
	v_mfma_f32_16x16x32_bf16 v[34:37], v[222:225], v[190:193], v[34:37]
	ds_read_b128 v[194:197], v166 offset:36864
	v_mfma_f32_16x16x32_bf16 v[22:25], v[214:217], v[198:201], v[22:25]
	v_mfma_f32_16x16x32_bf16 v[18:21], v[222:225], v[198:201], v[18:21]
	ds_read_b128 v[202:205], v166 offset:38912
	v_mfma_f32_16x16x32_bf16 v[6:9], v[214:217], v[206:209], v[6:9]
	v_mfma_f32_16x16x32_bf16 v[2:5], v[222:225], v[206:209], v[2:5]
	s_barrier
	s_add_i32 s49, 0, 0x18000
	s_add_u32 s14, s20, 0xb8000
	s_addc_u32 s15, s21, 0
	s_mov_b32 m0, s37
	ds_read_b128 v[168:171], v166 offset:33792
	ds_read_b128 v[190:193], v166 offset:35840
	ds_read_b128 v[198:201], v166 offset:37888
	ds_read_b128 v[206:209], v166 offset:39936
	global_load_lds_dwordx4 v130, s[14:15]
	s_mov_b32 m0, s38
	s_nop 0
	global_load_lds_dwordx4 v134, s[14:15]
	s_waitcnt lgkmcnt(8)
	s_barrier
	s_waitcnt lgkmcnt(0)
	s_waitcnt lgkmcnt(0)
	v_mfma_f32_16x16x32_bf16 v[126:129], v[142:145], v[158:161], v[126:129]
	v_mfma_f32_16x16x32_bf16 v[122:125], v[150:153], v[158:161], v[122:125]
	v_mfma_f32_16x16x32_bf16 v[110:113], v[142:145], v[172:175], v[110:113]
	v_mfma_f32_16x16x32_bf16 v[106:109], v[150:153], v[172:175], v[106:109]
	v_mfma_f32_16x16x32_bf16 v[94:97], v[142:145], v[194:197], v[94:97]
	v_mfma_f32_16x16x32_bf16 v[90:93], v[150:153], v[194:197], v[90:93]
	v_mfma_f32_16x16x32_bf16 v[78:81], v[142:145], v[202:205], v[78:81]
	v_mfma_f32_16x16x32_bf16 v[74:77], v[150:153], v[202:205], v[74:77]
	v_mfma_f32_16x16x32_bf16 v[126:129], v[146:149], v[168:171], v[126:129]
	v_mfma_f32_16x16x32_bf16 v[122:125], v[154:157], v[168:171], v[122:125]
	v_mfma_f32_16x16x32_bf16 v[110:113], v[146:149], v[190:193], v[110:113]
	v_mfma_f32_16x16x32_bf16 v[106:109], v[154:157], v[190:193], v[106:109]
	v_mfma_f32_16x16x32_bf16 v[94:97], v[146:149], v[198:201], v[94:97]
	v_mfma_f32_16x16x32_bf16 v[90:93], v[154:157], v[198:201], v[90:93]
	v_mfma_f32_16x16x32_bf16 v[78:81], v[146:149], v[206:209], v[78:81]
	v_mfma_f32_16x16x32_bf16 v[74:77], v[154:157], v[206:209], v[74:77]
	s_barrier
	s_add_i32 s20, 0, 0x1c000
	s_add_i32 s14, s49, s34
	v_add_u32_e32 v167, s20, v164
	s_mov_b32 m0, s14
	ds_read_b128 v[210:213], v167
	ds_read_b128 v[214:217], v167 offset:1024
	ds_read_b128 v[218:221], v167 offset:2048
	ds_read_b128 v[222:225], v167 offset:3072
	global_load_lds_dwordx4 v132, s[64:65]
	s_add_i32 m0, s14, 0x2000
	s_nop 0
	global_load_lds_dwordx4 v136, s[64:65]
	s_barrier
	s_waitcnt lgkmcnt(0)
	s_waitcnt lgkmcnt(0)
	v_mfma_f32_16x16x32_bf16 v[118:121], v[210:213], v[158:161], v[118:121]
	v_mfma_f32_16x16x32_bf16 v[114:117], v[218:221], v[158:161], v[114:117]
	v_mfma_f32_16x16x32_bf16 v[102:105], v[210:213], v[172:175], v[102:105]
	v_mfma_f32_16x16x32_bf16 v[98:101], v[218:221], v[172:175], v[98:101]
	v_mfma_f32_16x16x32_bf16 v[86:89], v[210:213], v[194:197], v[86:89]
	v_mfma_f32_16x16x32_bf16 v[82:85], v[218:221], v[194:197], v[82:85]
	v_mfma_f32_16x16x32_bf16 v[70:73], v[210:213], v[202:205], v[70:73]
	v_mfma_f32_16x16x32_bf16 v[66:69], v[218:221], v[202:205], v[66:69]
	ds_read_b128 v[158:161], v166 offset:49152
	v_mfma_f32_16x16x32_bf16 v[118:121], v[214:217], v[168:171], v[118:121]
	v_mfma_f32_16x16x32_bf16 v[114:117], v[222:225], v[168:171], v[114:117]
	ds_read_b128 v[172:175], v166 offset:51200
	v_mfma_f32_16x16x32_bf16 v[102:105], v[214:217], v[190:193], v[102:105]
	v_mfma_f32_16x16x32_bf16 v[98:101], v[222:225], v[190:193], v[98:101]
	ds_read_b128 v[194:197], v166 offset:53248
	v_mfma_f32_16x16x32_bf16 v[86:89], v[214:217], v[198:201], v[86:89]
	v_mfma_f32_16x16x32_bf16 v[82:85], v[222:225], v[198:201], v[82:85]
	ds_read_b128 v[202:205], v166 offset:55296
	v_mfma_f32_16x16x32_bf16 v[70:73], v[214:217], v[206:209], v[70:73]
	v_mfma_f32_16x16x32_bf16 v[66:69], v[222:225], v[206:209], v[66:69]
	s_barrier
	s_mov_b32 m0, s39
	ds_read_b128 v[168:171], v166 offset:50176
	ds_read_b128 v[190:193], v166 offset:52224
	ds_read_b128 v[198:201], v166 offset:54272
	ds_read_b128 v[206:209], v166 offset:56320
	global_load_lds_dwordx4 v130, s[62:63]
	s_mov_b32 m0, s40
	s_nop 0
	global_load_lds_dwordx4 v134, s[62:63]
	s_waitcnt vmcnt(8)
	s_barrier
	s_waitcnt lgkmcnt(0)
	s_waitcnt lgkmcnt(0)
	v_mfma_f32_16x16x32_bf16 v[62:65], v[142:145], v[158:161], v[62:65]
	v_mfma_f32_16x16x32_bf16 v[58:61], v[150:153], v[158:161], v[58:61]
	v_mfma_f32_16x16x32_bf16 v[46:49], v[142:145], v[172:175], v[46:49]
	v_mfma_f32_16x16x32_bf16 v[42:45], v[150:153], v[172:175], v[42:45]
	v_mfma_f32_16x16x32_bf16 v[30:33], v[142:145], v[194:197], v[30:33]
	v_mfma_f32_16x16x32_bf16 v[26:29], v[150:153], v[194:197], v[26:29]
	v_mfma_f32_16x16x32_bf16 v[14:17], v[142:145], v[202:205], v[14:17]
	v_mfma_f32_16x16x32_bf16 v[10:13], v[150:153], v[202:205], v[10:13]
	v_mfma_f32_16x16x32_bf16 v[62:65], v[146:149], v[168:171], v[62:65]
	v_mfma_f32_16x16x32_bf16 v[58:61], v[154:157], v[168:171], v[58:61]
	v_mfma_f32_16x16x32_bf16 v[46:49], v[146:149], v[190:193], v[46:49]
	v_mfma_f32_16x16x32_bf16 v[42:45], v[154:157], v[190:193], v[42:45]
	v_mfma_f32_16x16x32_bf16 v[30:33], v[146:149], v[198:201], v[30:33]
	v_mfma_f32_16x16x32_bf16 v[26:29], v[154:157], v[198:201], v[26:29]
	v_mfma_f32_16x16x32_bf16 v[14:17], v[146:149], v[206:209], v[14:17]
	v_mfma_f32_16x16x32_bf16 v[10:13], v[154:157], v[206:209], v[10:13]
	s_barrier
	v_add_u32_e32 v154, 0x10000, v164
	ds_read_b128 v[142:145], v154
	ds_read_b128 v[146:149], v154 offset:1024
	ds_read_b128 v[150:153], v154 offset:2048
	ds_read_b128 v[154:157], v154 offset:3072
	s_add_u32 s14, s18, 0xb0080
	s_addc_u32 s15, s19, 0
	s_add_i32 s18, s20, s34
	s_mov_b32 m0, s18
	s_nop 0
	global_load_lds_dwordx4 v132, s[14:15]
	s_add_i32 m0, s18, 0x2000
	s_nop 0
	global_load_lds_dwordx4 v136, s[14:15]
	s_waitcnt vmcnt(6)
	s_barrier
	v_mfma_f32_16x16x32_bf16 v[54:57], v[210:213], v[158:161], v[54:57]
	v_mfma_f32_16x16x32_bf16 v[50:53], v[218:221], v[158:161], v[50:53]
	v_mfma_f32_16x16x32_bf16 v[38:41], v[210:213], v[172:175], v[38:41]
	v_mfma_f32_16x16x32_bf16 v[34:37], v[218:221], v[172:175], v[34:37]
	v_mfma_f32_16x16x32_bf16 v[22:25], v[210:213], v[194:197], v[22:25]
	v_mfma_f32_16x16x32_bf16 v[18:21], v[218:221], v[194:197], v[18:21]
	v_mfma_f32_16x16x32_bf16 v[6:9], v[210:213], v[202:205], v[6:9]
	v_mfma_f32_16x16x32_bf16 v[2:5], v[218:221], v[202:205], v[2:5]
	ds_read_b128 v[158:161], v166
	v_mfma_f32_16x16x32_bf16 v[54:57], v[214:217], v[168:171], v[54:57]
	v_mfma_f32_16x16x32_bf16 v[50:53], v[222:225], v[168:171], v[50:53]
	ds_read_b128 v[172:175], v166 offset:2048
	v_mfma_f32_16x16x32_bf16 v[38:41], v[214:217], v[190:193], v[38:41]
	v_mfma_f32_16x16x32_bf16 v[34:37], v[222:225], v[190:193], v[34:37]
	ds_read_b128 v[194:197], v166 offset:4096
	v_mfma_f32_16x16x32_bf16 v[22:25], v[214:217], v[198:201], v[22:25]
	v_mfma_f32_16x16x32_bf16 v[18:21], v[222:225], v[198:201], v[18:21]
	ds_read_b128 v[202:205], v166 offset:6144
	v_mfma_f32_16x16x32_bf16 v[6:9], v[214:217], v[206:209], v[6:9]
	v_mfma_f32_16x16x32_bf16 v[2:5], v[222:225], v[206:209], v[2:5]
	s_barrier
	s_add_i32 s48, s48, 2
	s_add_u32 s46, s46, 0x100
	s_addc_u32 s47, s47, 0
	s_mov_b64 s[14:15], s[16:17]
.LBB0_374:
	s_add_u32 s16, s14, 0x100
	s_addc_u32 s17, s15, 0
	s_add_i32 s49, 0, 0x10000
	s_cmp_eq_u32 s48, 40
	s_cselect_b32 s21, s7, s17
	s_cselect_b32 s20, s6, s16
	s_cselect_b32 s19, s9, s47
	s_cselect_b32 s18, s8, s46
	v_lshl_add_u64 v[162:163], s[14:15], 0, v[138:139]
	s_add_i32 m0, s35, 0xc000
	ds_read_b128 v[168:171], v166 offset:1024
	ds_read_b128 v[190:193], v166 offset:3072
	ds_read_b128 v[198:201], v166 offset:5120
	ds_read_b128 v[206:209], v166 offset:7168
	global_load_lds_dwordx4 v[162:163], off
	v_lshl_add_u64 v[162:163], s[14:15], 0, v[140:141]
	s_add_i32 m0, s35, 0xe000
	s_nop 0
	global_load_lds_dwordx4 v[162:163], off
	s_waitcnt lgkmcnt(8)
	s_barrier
	s_waitcnt lgkmcnt(0)
	s_waitcnt lgkmcnt(0)
	v_mfma_f32_16x16x32_bf16 v[126:129], v[142:145], v[158:161], v[126:129]
	v_mfma_f32_16x16x32_bf16 v[122:125], v[150:153], v[158:161], v[122:125]
	v_mfma_f32_16x16x32_bf16 v[110:113], v[142:145], v[172:175], v[110:113]
	v_mfma_f32_16x16x32_bf16 v[106:109], v[150:153], v[172:175], v[106:109]
	v_mfma_f32_16x16x32_bf16 v[94:97], v[142:145], v[194:197], v[94:97]
	v_mfma_f32_16x16x32_bf16 v[90:93], v[150:153], v[194:197], v[90:93]
	v_mfma_f32_16x16x32_bf16 v[78:81], v[142:145], v[202:205], v[78:81]
	v_mfma_f32_16x16x32_bf16 v[74:77], v[150:153], v[202:205], v[74:77]
	v_mfma_f32_16x16x32_bf16 v[126:129], v[146:149], v[168:171], v[126:129]
	v_mfma_f32_16x16x32_bf16 v[122:125], v[154:157], v[168:171], v[122:125]
	v_mfma_f32_16x16x32_bf16 v[110:113], v[146:149], v[190:193], v[110:113]
	v_mfma_f32_16x16x32_bf16 v[106:109], v[154:157], v[190:193], v[106:109]
	v_mfma_f32_16x16x32_bf16 v[94:97], v[146:149], v[198:201], v[94:97]
	v_mfma_f32_16x16x32_bf16 v[90:93], v[154:157], v[198:201], v[90:93]
	v_mfma_f32_16x16x32_bf16 v[78:81], v[146:149], v[206:209], v[78:81]
	v_mfma_f32_16x16x32_bf16 v[74:77], v[154:157], v[206:209], v[74:77]
	s_barrier
	s_add_i32 s50, 0, 0x14000
	v_add_u32_e32 v162, s50, v164
	s_add_i32 s14, s49, s34
	ds_read_b128 v[210:213], v162
	ds_read_b128 v[214:217], v162 offset:1024
	ds_read_b128 v[218:221], v162 offset:2048
	ds_read_b128 v[222:225], v162 offset:3072
	s_add_u32 s64, s18, 0x80
	s_addc_u32 s65, s19, 0
	s_mov_b32 m0, s14
	s_nop 0
	global_load_lds_dwordx4 v132, s[18:19]
	s_add_i32 m0, s14, 0x2000
	s_nop 0
	global_load_lds_dwordx4 v136, s[18:19]
	s_barrier
	s_waitcnt lgkmcnt(0)
	s_waitcnt lgkmcnt(0)
	v_mfma_f32_16x16x32_bf16 v[118:121], v[210:213], v[158:161], v[118:121]
	v_mfma_f32_16x16x32_bf16 v[114:117], v[218:221], v[158:161], v[114:117]
	v_mfma_f32_16x16x32_bf16 v[102:105], v[210:213], v[172:175], v[102:105]
	v_mfma_f32_16x16x32_bf16 v[98:101], v[218:221], v[172:175], v[98:101]
	v_mfma_f32_16x16x32_bf16 v[86:89], v[210:213], v[194:197], v[86:89]
	v_mfma_f32_16x16x32_bf16 v[82:85], v[218:221], v[194:197], v[82:85]
	v_mfma_f32_16x16x32_bf16 v[70:73], v[210:213], v[202:205], v[70:73]
	v_mfma_f32_16x16x32_bf16 v[66:69], v[218:221], v[202:205], v[66:69]
	ds_read_b128 v[158:161], v166 offset:16384
	v_mfma_f32_16x16x32_bf16 v[118:121], v[214:217], v[168:171], v[118:121]
	v_mfma_f32_16x16x32_bf16 v[114:117], v[222:225], v[168:171], v[114:117]
	ds_read_b128 v[172:175], v166 offset:18432
	v_mfma_f32_16x16x32_bf16 v[102:105], v[214:217], v[190:193], v[102:105]
	v_mfma_f32_16x16x32_bf16 v[98:101], v[222:225], v[190:193], v[98:101]
	ds_read_b128 v[194:197], v166 offset:20480
	v_mfma_f32_16x16x32_bf16 v[86:89], v[214:217], v[198:201], v[86:89]
	v_mfma_f32_16x16x32_bf16 v[82:85], v[222:225], v[198:201], v[82:85]
	ds_read_b128 v[202:205], v166 offset:22528
	v_mfma_f32_16x16x32_bf16 v[70:73], v[214:217], v[206:209], v[70:73]
	v_mfma_f32_16x16x32_bf16 v[66:69], v[222:225], v[206:209], v[66:69]
	s_barrier
	s_mov_b32 m0, s35
	s_add_u32 s62, s20, 0x80
	s_addc_u32 s63, s21, 0
	ds_read_b128 v[168:171], v166 offset:17408
	ds_read_b128 v[190:193], v166 offset:19456
	ds_read_b128 v[198:201], v166 offset:21504
	ds_read_b128 v[206:209], v166 offset:23552
	global_load_lds_dwordx4 v130, s[20:21]
	s_mov_b32 m0, s36
	s_nop 0
	global_load_lds_dwordx4 v134, s[20:21]
	s_waitcnt vmcnt(8)
	s_barrier
	s_waitcnt lgkmcnt(0)
	s_waitcnt lgkmcnt(0)
	v_mfma_f32_16x16x32_bf16 v[62:65], v[142:145], v[158:161], v[62:65]
	v_mfma_f32_16x16x32_bf16 v[58:61], v[150:153], v[158:161], v[58:61]
	v_mfma_f32_16x16x32_bf16 v[46:49], v[142:145], v[172:175], v[46:49]
	v_mfma_f32_16x16x32_bf16 v[42:45], v[150:153], v[172:175], v[42:45]
	v_mfma_f32_16x16x32_bf16 v[30:33], v[142:145], v[194:197], v[30:33]
	v_mfma_f32_16x16x32_bf16 v[26:29], v[150:153], v[194:197], v[26:29]
	v_mfma_f32_16x16x32_bf16 v[14:17], v[142:145], v[202:205], v[14:17]
	v_mfma_f32_16x16x32_bf16 v[10:13], v[150:153], v[202:205], v[10:13]
	v_mfma_f32_16x16x32_bf16 v[62:65], v[146:149], v[168:171], v[62:65]
	v_mfma_f32_16x16x32_bf16 v[58:61], v[154:157], v[168:171], v[58:61]
	v_mfma_f32_16x16x32_bf16 v[46:49], v[146:149], v[190:193], v[46:49]
	v_mfma_f32_16x16x32_bf16 v[42:45], v[154:157], v[190:193], v[42:45]
	v_mfma_f32_16x16x32_bf16 v[30:33], v[146:149], v[198:201], v[30:33]
	v_mfma_f32_16x16x32_bf16 v[26:29], v[154:157], v[198:201], v[26:29]
	v_mfma_f32_16x16x32_bf16 v[14:17], v[146:149], v[206:209], v[14:17]
	v_mfma_f32_16x16x32_bf16 v[10:13], v[154:157], v[206:209], v[10:13]
	s_barrier
	v_add_u32_e32 v154, 0x18000, v164
	ds_read_b128 v[142:145], v154
	ds_read_b128 v[146:149], v154 offset:1024
	ds_read_b128 v[150:153], v154 offset:2048
	ds_read_b128 v[154:157], v154 offset:3072
	s_add_u32 s14, s18, 0xb0000
	s_addc_u32 s15, s19, 0
	s_add_i32 s49, s50, s34
	s_mov_b32 m0, s49
	s_nop 0
	global_load_lds_dwordx4 v132, s[14:15]
	s_add_i32 m0, s49, 0x2000
	s_nop 0
	global_load_lds_dwordx4 v136, s[14:15]
	s_waitcnt vmcnt(6)
	s_barrier
	v_mfma_f32_16x16x32_bf16 v[54:57], v[210:213], v[158:161], v[54:57]
	v_mfma_f32_16x16x32_bf16 v[50:53], v[218:221], v[158:161], v[50:53]
	v_mfma_f32_16x16x32_bf16 v[38:41], v[210:213], v[172:175], v[38:41]
	v_mfma_f32_16x16x32_bf16 v[34:37], v[218:221], v[172:175], v[34:37]
	v_mfma_f32_16x16x32_bf16 v[22:25], v[210:213], v[194:197], v[22:25]
	v_mfma_f32_16x16x32_bf16 v[18:21], v[218:221], v[194:197], v[18:21]
	v_mfma_f32_16x16x32_bf16 v[6:9], v[210:213], v[202:205], v[6:9]
	v_mfma_f32_16x16x32_bf16 v[2:5], v[218:221], v[202:205], v[2:5]
	ds_read_b128 v[158:161], v166 offset:32768
	v_mfma_f32_16x16x32_bf16 v[54:57], v[214:217], v[168:171], v[54:57]
	v_mfma_f32_16x16x32_bf16 v[50:53], v[222:225], v[168:171], v[50:53]
	ds_read_b128 v[172:175], v166 offset:34816
	v_mfma_f32_16x16x32_bf16 v[38:41], v[214:217], v[190:193], v[38:41]
	v_mfma_f32_16x16x32_bf16 v[34:37], v[222:225], v[190:193], v[34:37]
	ds_read_b128 v[194:197], v166 offset:36864
	v_mfma_f32_16x16x32_bf16 v[22:25], v[214:217], v[198:201], v[22:25]
	v_mfma_f32_16x16x32_bf16 v[18:21], v[222:225], v[198:201], v[18:21]
	ds_read_b128 v[202:205], v166 offset:38912
	v_mfma_f32_16x16x32_bf16 v[6:9], v[214:217], v[206:209], v[6:9]
	v_mfma_f32_16x16x32_bf16 v[2:5], v[222:225], v[206:209], v[2:5]
	s_barrier
	s_add_i32 s49, 0, 0x18000
	s_add_u32 s14, s20, 0xb8000
	s_addc_u32 s15, s21, 0
	s_mov_b32 m0, s37
	ds_read_b128 v[168:171], v166 offset:33792
	ds_read_b128 v[190:193], v166 offset:35840
	ds_read_b128 v[198:201], v166 offset:37888
	ds_read_b128 v[206:209], v166 offset:39936
	global_load_lds_dwordx4 v130, s[14:15]
	s_mov_b32 m0, s38
	s_nop 0
	global_load_lds_dwordx4 v134, s[14:15]
	s_waitcnt lgkmcnt(8)
	s_barrier
	s_waitcnt lgkmcnt(0)
	s_waitcnt lgkmcnt(0)
	v_mfma_f32_16x16x32_bf16 v[126:129], v[142:145], v[158:161], v[126:129]
	v_mfma_f32_16x16x32_bf16 v[122:125], v[150:153], v[158:161], v[122:125]
	v_mfma_f32_16x16x32_bf16 v[110:113], v[142:145], v[172:175], v[110:113]
	v_mfma_f32_16x16x32_bf16 v[106:109], v[150:153], v[172:175], v[106:109]
	v_mfma_f32_16x16x32_bf16 v[94:97], v[142:145], v[194:197], v[94:97]
	v_mfma_f32_16x16x32_bf16 v[90:93], v[150:153], v[194:197], v[90:93]
	v_mfma_f32_16x16x32_bf16 v[78:81], v[142:145], v[202:205], v[78:81]
	v_mfma_f32_16x16x32_bf16 v[74:77], v[150:153], v[202:205], v[74:77]
	v_mfma_f32_16x16x32_bf16 v[126:129], v[146:149], v[168:171], v[126:129]
	v_mfma_f32_16x16x32_bf16 v[122:125], v[154:157], v[168:171], v[122:125]
	v_mfma_f32_16x16x32_bf16 v[110:113], v[146:149], v[190:193], v[110:113]
	v_mfma_f32_16x16x32_bf16 v[106:109], v[154:157], v[190:193], v[106:109]
	v_mfma_f32_16x16x32_bf16 v[94:97], v[146:149], v[198:201], v[94:97]
	v_mfma_f32_16x16x32_bf16 v[90:93], v[154:157], v[198:201], v[90:93]
	v_mfma_f32_16x16x32_bf16 v[78:81], v[146:149], v[206:209], v[78:81]
	v_mfma_f32_16x16x32_bf16 v[74:77], v[154:157], v[206:209], v[74:77]
	s_barrier
	s_add_i32 s20, 0, 0x1c000
	s_add_i32 s14, s49, s34
	v_add_u32_e32 v167, s20, v164
	s_mov_b32 m0, s14
	ds_read_b128 v[210:213], v167
	ds_read_b128 v[214:217], v167 offset:1024
	ds_read_b128 v[218:221], v167 offset:2048
	ds_read_b128 v[222:225], v167 offset:3072
	global_load_lds_dwordx4 v132, s[64:65]
	s_add_i32 m0, s14, 0x2000
	s_nop 0
	global_load_lds_dwordx4 v136, s[64:65]
	s_barrier
	s_waitcnt lgkmcnt(0)
	s_waitcnt lgkmcnt(0)
	v_mfma_f32_16x16x32_bf16 v[118:121], v[210:213], v[158:161], v[118:121]
	v_mfma_f32_16x16x32_bf16 v[114:117], v[218:221], v[158:161], v[114:117]
	v_mfma_f32_16x16x32_bf16 v[102:105], v[210:213], v[172:175], v[102:105]
	v_mfma_f32_16x16x32_bf16 v[98:101], v[218:221], v[172:175], v[98:101]
	v_mfma_f32_16x16x32_bf16 v[86:89], v[210:213], v[194:197], v[86:89]
	v_mfma_f32_16x16x32_bf16 v[82:85], v[218:221], v[194:197], v[82:85]
	v_mfma_f32_16x16x32_bf16 v[70:73], v[210:213], v[202:205], v[70:73]
	v_mfma_f32_16x16x32_bf16 v[66:69], v[218:221], v[202:205], v[66:69]
	ds_read_b128 v[158:161], v166 offset:49152
	v_mfma_f32_16x16x32_bf16 v[118:121], v[214:217], v[168:171], v[118:121]
	v_mfma_f32_16x16x32_bf16 v[114:117], v[222:225], v[168:171], v[114:117]
	ds_read_b128 v[172:175], v166 offset:51200
	v_mfma_f32_16x16x32_bf16 v[102:105], v[214:217], v[190:193], v[102:105]
	v_mfma_f32_16x16x32_bf16 v[98:101], v[222:225], v[190:193], v[98:101]
	ds_read_b128 v[194:197], v166 offset:53248
	v_mfma_f32_16x16x32_bf16 v[86:89], v[214:217], v[198:201], v[86:89]
	v_mfma_f32_16x16x32_bf16 v[82:85], v[222:225], v[198:201], v[82:85]
	ds_read_b128 v[202:205], v166 offset:55296
	v_mfma_f32_16x16x32_bf16 v[70:73], v[214:217], v[206:209], v[70:73]
	v_mfma_f32_16x16x32_bf16 v[66:69], v[222:225], v[206:209], v[66:69]
	s_barrier
	s_mov_b32 m0, s39
	ds_read_b128 v[168:171], v166 offset:50176
	ds_read_b128 v[190:193], v166 offset:52224
	ds_read_b128 v[198:201], v166 offset:54272
	ds_read_b128 v[206:209], v166 offset:56320
	global_load_lds_dwordx4 v130, s[62:63]
	s_mov_b32 m0, s40
	s_nop 0
	global_load_lds_dwordx4 v134, s[62:63]
	s_waitcnt vmcnt(8)
	s_barrier
	s_waitcnt lgkmcnt(0)
	s_waitcnt lgkmcnt(0)
	v_mfma_f32_16x16x32_bf16 v[62:65], v[142:145], v[158:161], v[62:65]
	v_mfma_f32_16x16x32_bf16 v[58:61], v[150:153], v[158:161], v[58:61]
	v_mfma_f32_16x16x32_bf16 v[46:49], v[142:145], v[172:175], v[46:49]
	v_mfma_f32_16x16x32_bf16 v[42:45], v[150:153], v[172:175], v[42:45]
	v_mfma_f32_16x16x32_bf16 v[30:33], v[142:145], v[194:197], v[30:33]
	v_mfma_f32_16x16x32_bf16 v[26:29], v[150:153], v[194:197], v[26:29]
	v_mfma_f32_16x16x32_bf16 v[14:17], v[142:145], v[202:205], v[14:17]
	v_mfma_f32_16x16x32_bf16 v[10:13], v[150:153], v[202:205], v[10:13]
	v_mfma_f32_16x16x32_bf16 v[62:65], v[146:149], v[168:171], v[62:65]
	v_mfma_f32_16x16x32_bf16 v[58:61], v[154:157], v[168:171], v[58:61]
	v_mfma_f32_16x16x32_bf16 v[46:49], v[146:149], v[190:193], v[46:49]
	v_mfma_f32_16x16x32_bf16 v[42:45], v[154:157], v[190:193], v[42:45]
	v_mfma_f32_16x16x32_bf16 v[30:33], v[146:149], v[198:201], v[30:33]
	v_mfma_f32_16x16x32_bf16 v[26:29], v[154:157], v[198:201], v[26:29]
	v_mfma_f32_16x16x32_bf16 v[14:17], v[146:149], v[206:209], v[14:17]
	v_mfma_f32_16x16x32_bf16 v[10:13], v[154:157], v[206:209], v[10:13]
	s_barrier
	v_add_u32_e32 v154, 0x10000, v164
	ds_read_b128 v[142:145], v154
	ds_read_b128 v[146:149], v154 offset:1024
	ds_read_b128 v[150:153], v154 offset:2048
	ds_read_b128 v[154:157], v154 offset:3072
	s_add_u32 s14, s18, 0xb0080
	s_addc_u32 s15, s19, 0
	s_add_i32 s18, s20, s34
	s_mov_b32 m0, s18
	s_nop 0
	global_load_lds_dwordx4 v132, s[14:15]
	s_add_i32 m0, s18, 0x2000
	s_nop 0
	global_load_lds_dwordx4 v136, s[14:15]
	s_waitcnt vmcnt(6)
	s_barrier
	v_mfma_f32_16x16x32_bf16 v[54:57], v[210:213], v[158:161], v[54:57]
	v_mfma_f32_16x16x32_bf16 v[50:53], v[218:221], v[158:161], v[50:53]
	v_mfma_f32_16x16x32_bf16 v[38:41], v[210:213], v[172:175], v[38:41]
	v_mfma_f32_16x16x32_bf16 v[34:37], v[218:221], v[172:175], v[34:37]
	v_mfma_f32_16x16x32_bf16 v[22:25], v[210:213], v[194:197], v[22:25]
	v_mfma_f32_16x16x32_bf16 v[18:21], v[218:221], v[194:197], v[18:21]
	v_mfma_f32_16x16x32_bf16 v[6:9], v[210:213], v[202:205], v[6:9]
	v_mfma_f32_16x16x32_bf16 v[2:5], v[218:221], v[202:205], v[2:5]
	ds_read_b128 v[158:161], v166
	v_mfma_f32_16x16x32_bf16 v[54:57], v[214:217], v[168:171], v[54:57]
	v_mfma_f32_16x16x32_bf16 v[50:53], v[222:225], v[168:171], v[50:53]
	ds_read_b128 v[172:175], v166 offset:2048
	v_mfma_f32_16x16x32_bf16 v[38:41], v[214:217], v[190:193], v[38:41]
	v_mfma_f32_16x16x32_bf16 v[34:37], v[222:225], v[190:193], v[34:37]
	ds_read_b128 v[194:197], v166 offset:4096
	v_mfma_f32_16x16x32_bf16 v[22:25], v[214:217], v[198:201], v[22:25]
	v_mfma_f32_16x16x32_bf16 v[18:21], v[222:225], v[198:201], v[18:21]
	ds_read_b128 v[202:205], v166 offset:6144
	v_mfma_f32_16x16x32_bf16 v[6:9], v[214:217], v[206:209], v[6:9]
	v_mfma_f32_16x16x32_bf16 v[2:5], v[222:225], v[206:209], v[2:5]
	s_barrier
	s_add_i32 s48, s48, 2
	s_add_u32 s46, s46, 0x100
	s_addc_u32 s47, s47, 0
	s_cmp_gt_u32 s48, 41
	s_mov_b64 s[14:15], s[16:17]
	s_cbranch_scc0 .LBB0_374
	s_waitcnt lgkmcnt(0)
	s_ashr_i32 s14, s33, 5
	s_mul_hi_i32 s15, s14, 0x9000
	s_mul_i32 s14, s14, 0x9000
	v_lshl_or_b32 v158, s45, 8, v165
	s_add_u32 s14, s26, s14
	s_addc_u32 s15, s27, s15
	v_ashrrev_i32_e32 v159, 31, v158
	v_lshl_add_u64 v[160:161], v[158:159], 2, s[14:15]
	global_load_dwordx4 v[142:145], v[160:161], off offset:16
	global_load_dwordx4 v[146:149], v[160:161], off
	v_lshl_add_u32 v162, s33, 8, v1
	v_ashrrev_i32_e32 v163, 31, v162
	v_lshlrev_b64 v[150:151], 12, v[162:163]
	v_lshl_add_u64 v[150:151], s[12:13], 0, v[150:151]
	v_lshl_add_u64 v[150:151], v[158:159], 1, v[150:151]
	v_mov_b32_e32 v152, 0x10000
	v_mov_b32_e32 v153, 0
	global_load_dwordx4 v[174:177], v[150:151], off offset:2048
	global_load_dwordx4 v[186:189], v[150:151], off offset:2304
	v_lshl_add_u64 v[150:151], v[150:151], 0, v[152:153]
	global_load_dwordx4 v[190:193], v[150:151], off offset:2048
	global_load_dwordx4 v[194:197], v[150:151], off offset:2304
	v_lshl_add_u64 v[150:151], v[150:151], 0, v[152:153]
	global_load_dwordx4 v[198:201], v[150:151], off offset:2048
	global_load_dwordx4 v[202:205], v[150:151], off offset:2304
	v_lshl_add_u64 v[150:151], v[150:151], 0, v[152:153]
	global_load_dwordx4 v[206:209], v[150:151], off offset:2048
	global_load_dwordx4 v[210:213], v[150:151], off offset:2304
	v_mov_b32_e32 v152, 0x50000
	v_lshl_add_u64 v[150:151], v[150:151], 0, v[152:153]
	v_mov_b32_e32 v152, 0x10000
	global_load_dwordx4 v[214:217], v[150:151], off offset:2048
	global_load_dwordx4 v[218:221], v[150:151], off offset:2304
	v_lshl_add_u64 v[150:151], v[150:151], 0, v[152:153]
	global_load_dwordx4 v[222:225], v[150:151], off offset:2048
	global_load_dwordx4 v[226:229], v[150:151], off offset:2304
	v_lshl_add_u64 v[150:151], v[150:151], 0, v[152:153]
	global_load_dwordx4 v[230:233], v[150:151], off offset:2048
	global_load_dwordx4 v[236:239], v[150:151], off offset:2304
	v_lshl_add_u64 v[150:151], v[150:151], 0, v[152:153]
	global_load_dwordx4 v[246:249], v[150:151], off offset:2048
	global_load_dwordx4 v[250:253], v[150:151], off offset:2304
	s_mov_b64 s[14:15], 0x80000
	s_and_b64 vcc, exec, s[4:5]
	s_mov_b32 s45, s43
	s_mov_b32 s33, s44
	s_mov_b64 s[16:17], s[8:9]
	s_waitcnt vmcnt(16)
	v_pk_add_f32 v[144:145], v[144:145], 1.0 op_sel_hi:[1,0]
	v_pk_add_f32 v[148:149], v[148:149], 1.0 op_sel_hi:[1,0]
	v_pk_add_f32 v[146:147], v[146:147], 1.0 op_sel_hi:[1,0]
	v_pk_add_f32 v[142:143], v[142:143], 1.0 op_sel_hi:[1,0]
	v_pk_mul_f32 v[152:153], v[148:149], 0.5 op_sel_hi:[1,0]
	v_pk_mul_f32 v[156:157], v[146:147], 0.5 op_sel_hi:[1,0]
	v_pk_mul_f32 v[150:151], v[144:145], 0.5 op_sel_hi:[1,0]
	v_pk_mul_f32 v[154:155], v[142:143], 0.5 op_sel_hi:[1,0]
	global_load_dwordx4 v[142:145], v[160:161], off offset:528
	global_load_dwordx4 v[146:149], v[160:161], off offset:512
	s_waitcnt vmcnt(0)
	v_pk_add_f32 v[144:145], v[144:145], 1.0 op_sel_hi:[1,0]
	v_pk_add_f32 v[148:149], v[148:149], 1.0 op_sel_hi:[1,0]
	v_pk_add_f32 v[160:161], v[146:147], 1.0 op_sel_hi:[1,0]
	v_pk_mul_f32 v[146:147], v[148:149], 0.5 op_sel_hi:[1,0]
	v_pk_mul_f32 v[148:149], v[160:161], 0.5 op_sel_hi:[1,0]
	v_pk_add_f32 v[160:161], v[142:143], 1.0 op_sel_hi:[1,0]
	v_pk_mul_f32 v[142:143], v[144:145], 0.5 op_sel_hi:[1,0]
	v_pk_mul_f32 v[144:145], v[160:161], 0.5 op_sel_hi:[1,0]
	v_lshlrev_b64 v[160:161], 12, v[162:163]
	v_lshl_add_u64 v[168:169], s[12:13], 0, v[160:161]
	v_lshlrev_b64 v[160:161], 1, v[158:159]
	v_lshl_add_u64 v[158:159], v[168:169], 0, v[160:161]
	v_mov_b32_e32 v168, v174
	v_mov_b32_e32 v169, v175
	v_mov_b32_e32 v170, v176
	v_mov_b32_e32 v171, v177
	s_nop 0
	v_lshlrev_b32_e32 v172, 16, v168
	v_and_b32_e32 v173, 0xffff0000, v168
	v_lshlrev_b32_e32 v168, 16, v169
	v_and_b32_e32 v169, 0xffff0000, v169
	v_pk_fma_f32 v[128:129], v[128:129], v[152:153], v[168:169]
	v_lshlrev_b32_e32 v168, 16, v170
	v_and_b32_e32 v169, 0xffff0000, v170
	v_pk_fma_f32 v[168:169], v[122:123], v[154:155], v[168:169]
	v_lshlrev_b32_e32 v122, 16, v171
	v_and_b32_e32 v123, 0xffff0000, v171
	v_pk_fma_f32 v[126:127], v[126:127], v[156:157], v[172:173]
	v_pk_fma_f32 v[170:171], v[124:125], v[150:151], v[122:123]
	v_cvt_pk_bf16_f32 v122, v126, v127
	v_cvt_pk_bf16_f32 v123, v128, v129
	v_cvt_pk_bf16_f32 v124, v168, v169
	v_cvt_pk_bf16_f32 v125, v170, v171
	global_store_dwordx4 v[158:159], v[122:125], off offset:2048
	s_nop 1
	v_mov_b32_e32 v122, v186
	v_mov_b32_e32 v123, v187
	v_mov_b32_e32 v124, v188
	v_mov_b32_e32 v125, v189
	s_nop 0
	v_lshlrev_b32_e32 v126, 16, v122
	v_and_b32_e32 v127, 0xffff0000, v122
	v_lshlrev_b32_e32 v122, 16, v123
	v_and_b32_e32 v123, 0xffff0000, v123
	v_pk_fma_f32 v[120:121], v[120:121], v[146:147], v[122:123]
	v_lshlrev_b32_e32 v122, 16, v124
	v_and_b32_e32 v123, 0xffff0000, v124
	v_pk_fma_f32 v[122:123], v[114:115], v[144:145], v[122:123]
	v_lshlrev_b32_e32 v114, 16, v125
	v_and_b32_e32 v115, 0xffff0000, v125
	v_pk_fma_f32 v[118:119], v[118:119], v[148:149], v[126:127]
	v_pk_fma_f32 v[124:125], v[116:117], v[142:143], v[114:115]
	v_cvt_pk_bf16_f32 v114, v118, v119
	v_cvt_pk_bf16_f32 v115, v120, v121
	v_cvt_pk_bf16_f32 v116, v122, v123
	v_cvt_pk_bf16_f32 v117, v124, v125
	global_store_dwordx4 v[158:159], v[114:117], off offset:2304
	s_nop 1
	v_or_b32_e32 v114, 16, v162
	v_ashrrev_i32_e32 v115, 31, v114
	v_lshlrev_b64 v[114:115], 12, v[114:115]
	v_lshl_add_u64 v[114:115], s[12:13], 0, v[114:115]
	v_lshl_add_u64 v[118:119], v[114:115], 0, v[160:161]
	v_mov_b32_e32 v114, v190
	v_mov_b32_e32 v115, v191
	v_mov_b32_e32 v116, v192
	v_mov_b32_e32 v117, v193
	s_nop 0
	v_lshlrev_b32_e32 v120, 16, v114
	v_and_b32_e32 v121, 0xffff0000, v114
	v_lshlrev_b32_e32 v114, 16, v115
	v_and_b32_e32 v115, 0xffff0000, v115
	v_pk_fma_f32 v[112:113], v[112:113], v[152:153], v[114:115]
	v_lshlrev_b32_e32 v114, 16, v116
	v_and_b32_e32 v115, 0xffff0000, v116
	v_pk_fma_f32 v[114:115], v[106:107], v[154:155], v[114:115]
	v_lshlrev_b32_e32 v106, 16, v117
	v_and_b32_e32 v107, 0xffff0000, v117
	v_pk_fma_f32 v[110:111], v[110:111], v[156:157], v[120:121]
	v_pk_fma_f32 v[116:117], v[108:109], v[150:151], v[106:107]
	v_cvt_pk_bf16_f32 v106, v110, v111
	v_cvt_pk_bf16_f32 v107, v112, v113
	v_cvt_pk_bf16_f32 v108, v114, v115
	v_cvt_pk_bf16_f32 v109, v116, v117
	global_store_dwordx4 v[118:119], v[106:109], off offset:2048
	s_nop 1
	v_mov_b32_e32 v106, v194
	v_mov_b32_e32 v107, v195
	v_mov_b32_e32 v108, v196
	v_mov_b32_e32 v109, v197
	s_nop 0
	v_lshlrev_b32_e32 v110, 16, v106
	v_and_b32_e32 v111, 0xffff0000, v106
	v_lshlrev_b32_e32 v106, 16, v107
	v_and_b32_e32 v107, 0xffff0000, v107
	v_pk_fma_f32 v[104:105], v[104:105], v[146:147], v[106:107]
	v_lshlrev_b32_e32 v106, 16, v108
	v_and_b32_e32 v107, 0xffff0000, v108
	v_pk_fma_f32 v[106:107], v[98:99], v[144:145], v[106:107]
	v_lshlrev_b32_e32 v98, 16, v109
	v_and_b32_e32 v99, 0xffff0000, v109
	v_pk_fma_f32 v[102:103], v[102:103], v[148:149], v[110:111]
	v_pk_fma_f32 v[108:109], v[100:101], v[142:143], v[98:99]
	v_cvt_pk_bf16_f32 v98, v102, v103
	v_cvt_pk_bf16_f32 v99, v104, v105
	v_cvt_pk_bf16_f32 v100, v106, v107
	v_cvt_pk_bf16_f32 v101, v108, v109
	global_store_dwordx4 v[118:119], v[98:101], off offset:2304
	s_nop 1
	v_or_b32_e32 v98, 32, v162
	v_ashrrev_i32_e32 v99, 31, v98
	v_lshlrev_b64 v[98:99], 12, v[98:99]
	v_lshl_add_u64 v[98:99], s[12:13], 0, v[98:99]
	v_lshl_add_u64 v[102:103], v[98:99], 0, v[160:161]
	v_mov_b32_e32 v98, v198
	v_mov_b32_e32 v99, v199
	v_mov_b32_e32 v100, v200
	v_mov_b32_e32 v101, v201
	s_nop 0
	v_lshlrev_b32_e32 v104, 16, v98
	v_and_b32_e32 v105, 0xffff0000, v98
	v_lshlrev_b32_e32 v98, 16, v99
	v_and_b32_e32 v99, 0xffff0000, v99
	v_pk_fma_f32 v[96:97], v[96:97], v[152:153], v[98:99]
	v_lshlrev_b32_e32 v98, 16, v100
	v_and_b32_e32 v99, 0xffff0000, v100
	v_pk_fma_f32 v[98:99], v[90:91], v[154:155], v[98:99]
	v_lshlrev_b32_e32 v90, 16, v101
	v_and_b32_e32 v91, 0xffff0000, v101
	v_pk_fma_f32 v[94:95], v[94:95], v[156:157], v[104:105]
	v_pk_fma_f32 v[100:101], v[92:93], v[150:151], v[90:91]
	v_cvt_pk_bf16_f32 v90, v94, v95
	v_cvt_pk_bf16_f32 v91, v96, v97
	v_cvt_pk_bf16_f32 v92, v98, v99
	v_cvt_pk_bf16_f32 v93, v100, v101
	global_store_dwordx4 v[102:103], v[90:93], off offset:2048
	s_nop 1
	v_mov_b32_e32 v90, v202
	v_mov_b32_e32 v91, v203
	v_mov_b32_e32 v92, v204
	v_mov_b32_e32 v93, v205
	s_nop 0
	v_lshlrev_b32_e32 v94, 16, v90
	v_and_b32_e32 v95, 0xffff0000, v90
	v_lshlrev_b32_e32 v90, 16, v91
	v_and_b32_e32 v91, 0xffff0000, v91
	v_pk_fma_f32 v[88:89], v[88:89], v[146:147], v[90:91]
	v_lshlrev_b32_e32 v90, 16, v92
	v_and_b32_e32 v91, 0xffff0000, v92
	v_pk_fma_f32 v[90:91], v[82:83], v[144:145], v[90:91]
	v_lshlrev_b32_e32 v82, 16, v93
	v_and_b32_e32 v83, 0xffff0000, v93
	v_pk_fma_f32 v[86:87], v[86:87], v[148:149], v[94:95]
	v_pk_fma_f32 v[92:93], v[84:85], v[142:143], v[82:83]
	v_cvt_pk_bf16_f32 v82, v86, v87
	v_cvt_pk_bf16_f32 v83, v88, v89
	v_cvt_pk_bf16_f32 v84, v90, v91
	v_cvt_pk_bf16_f32 v85, v92, v93
	global_store_dwordx4 v[102:103], v[82:85], off offset:2304
	s_nop 1
	v_or_b32_e32 v82, 48, v162
	v_ashrrev_i32_e32 v83, 31, v82
	v_lshlrev_b64 v[82:83], 12, v[82:83]
	v_lshl_add_u64 v[82:83], s[12:13], 0, v[82:83]
	v_lshl_add_u64 v[82:83], v[82:83], 0, v[160:161]
	v_mov_b32_e32 v84, v206
	v_mov_b32_e32 v85, v207
	v_mov_b32_e32 v86, v208
	v_mov_b32_e32 v87, v209
	s_nop 0
	v_lshlrev_b32_e32 v88, 16, v84
	v_and_b32_e32 v89, 0xffff0000, v84
	v_lshlrev_b32_e32 v84, 16, v85
	v_and_b32_e32 v85, 0xffff0000, v85
	v_pk_fma_f32 v[80:81], v[80:81], v[152:153], v[84:85]
	v_lshlrev_b32_e32 v84, 16, v86
	v_and_b32_e32 v85, 0xffff0000, v86
	v_pk_fma_f32 v[84:85], v[74:75], v[154:155], v[84:85]
	v_lshlrev_b32_e32 v74, 16, v87
	v_and_b32_e32 v75, 0xffff0000, v87
	v_pk_fma_f32 v[78:79], v[78:79], v[156:157], v[88:89]
	v_pk_fma_f32 v[86:87], v[76:77], v[150:151], v[74:75]
	v_cvt_pk_bf16_f32 v74, v78, v79
	v_cvt_pk_bf16_f32 v75, v80, v81
	v_cvt_pk_bf16_f32 v76, v84, v85
	v_cvt_pk_bf16_f32 v77, v86, v87
	global_store_dwordx4 v[82:83], v[74:77], off offset:2048
	s_nop 1
	v_mov_b32_e32 v74, v210
	v_mov_b32_e32 v75, v211
	v_mov_b32_e32 v76, v212
	v_mov_b32_e32 v77, v213
	s_nop 0
	v_lshlrev_b32_e32 v78, 16, v74
	v_and_b32_e32 v79, 0xffff0000, v74
	v_lshlrev_b32_e32 v74, 16, v75
	v_and_b32_e32 v75, 0xffff0000, v75
	v_pk_fma_f32 v[72:73], v[72:73], v[146:147], v[74:75]
	v_lshlrev_b32_e32 v74, 16, v76
	v_and_b32_e32 v75, 0xffff0000, v76
	v_pk_fma_f32 v[74:75], v[66:67], v[144:145], v[74:75]
	v_lshlrev_b32_e32 v66, 16, v77
	v_and_b32_e32 v67, 0xffff0000, v77
	v_pk_fma_f32 v[70:71], v[70:71], v[148:149], v[78:79]
	v_pk_fma_f32 v[76:77], v[68:69], v[142:143], v[66:67]
	v_cvt_pk_bf16_f32 v66, v70, v71
	v_cvt_pk_bf16_f32 v67, v72, v73
	v_cvt_pk_bf16_f32 v68, v74, v75
	v_cvt_pk_bf16_f32 v69, v76, v77
	v_lshl_add_u64 v[70:71], v[158:159], 0, s[14:15]
	global_store_dwordx4 v[82:83], v[66:69], off offset:2304
	s_nop 1
	v_mov_b32_e32 v66, v214
	v_mov_b32_e32 v67, v215
	v_mov_b32_e32 v68, v216
	v_mov_b32_e32 v69, v217
	s_mov_b64 s[14:15], 0x90000
	s_nop 0
	v_lshlrev_b32_e32 v72, 16, v66
	v_and_b32_e32 v73, 0xffff0000, v66
	v_lshlrev_b32_e32 v66, 16, v67
	v_and_b32_e32 v67, 0xffff0000, v67
	v_pk_fma_f32 v[64:65], v[64:65], v[152:153], v[66:67]
	v_lshlrev_b32_e32 v66, 16, v68
	v_and_b32_e32 v67, 0xffff0000, v68
	v_pk_fma_f32 v[66:67], v[58:59], v[154:155], v[66:67]
	v_lshlrev_b32_e32 v58, 16, v69
	v_and_b32_e32 v59, 0xffff0000, v69
	v_pk_fma_f32 v[62:63], v[62:63], v[156:157], v[72:73]
	v_pk_fma_f32 v[68:69], v[60:61], v[150:151], v[58:59]
	v_cvt_pk_bf16_f32 v58, v62, v63
	v_cvt_pk_bf16_f32 v59, v64, v65
	v_cvt_pk_bf16_f32 v60, v66, v67
	v_cvt_pk_bf16_f32 v61, v68, v69
	global_store_dwordx4 v[70:71], v[58:61], off offset:2048
	s_nop 1
	v_mov_b32_e32 v58, v218
	v_mov_b32_e32 v59, v219
	v_mov_b32_e32 v60, v220
	v_mov_b32_e32 v61, v221
	s_nop 0
	v_lshlrev_b32_e32 v62, 16, v58
	v_and_b32_e32 v63, 0xffff0000, v58
	v_lshlrev_b32_e32 v58, 16, v59
	v_and_b32_e32 v59, 0xffff0000, v59
	v_pk_fma_f32 v[56:57], v[56:57], v[146:147], v[58:59]
	v_lshlrev_b32_e32 v58, 16, v60
	v_and_b32_e32 v59, 0xffff0000, v60
	v_pk_fma_f32 v[58:59], v[50:51], v[144:145], v[58:59]
	v_lshlrev_b32_e32 v50, 16, v61
	v_and_b32_e32 v51, 0xffff0000, v61
	v_pk_fma_f32 v[54:55], v[54:55], v[148:149], v[62:63]
	v_pk_fma_f32 v[60:61], v[52:53], v[142:143], v[50:51]
	v_cvt_pk_bf16_f32 v50, v54, v55
	v_cvt_pk_bf16_f32 v51, v56, v57
	v_cvt_pk_bf16_f32 v52, v58, v59
	v_cvt_pk_bf16_f32 v53, v60, v61
	v_lshl_add_u64 v[54:55], v[158:159], 0, s[14:15]
	global_store_dwordx4 v[70:71], v[50:53], off offset:2304
	s_nop 1
	v_mov_b32_e32 v50, v222
	v_mov_b32_e32 v51, v223
	v_mov_b32_e32 v52, v224
	v_mov_b32_e32 v53, v225
	s_mov_b64 s[14:15], 0xa0000
	s_nop 0
	v_lshlrev_b32_e32 v56, 16, v50
	v_and_b32_e32 v57, 0xffff0000, v50
	v_lshlrev_b32_e32 v50, 16, v51
	v_and_b32_e32 v51, 0xffff0000, v51
	v_pk_fma_f32 v[48:49], v[48:49], v[152:153], v[50:51]
	v_lshlrev_b32_e32 v50, 16, v52
	v_and_b32_e32 v51, 0xffff0000, v52
	v_pk_fma_f32 v[50:51], v[42:43], v[154:155], v[50:51]
	v_lshlrev_b32_e32 v42, 16, v53
	v_and_b32_e32 v43, 0xffff0000, v53
	v_pk_fma_f32 v[46:47], v[46:47], v[156:157], v[56:57]
	v_pk_fma_f32 v[52:53], v[44:45], v[150:151], v[42:43]
	v_cvt_pk_bf16_f32 v42, v46, v47
	v_cvt_pk_bf16_f32 v43, v48, v49
	v_cvt_pk_bf16_f32 v44, v50, v51
	v_cvt_pk_bf16_f32 v45, v52, v53
	global_store_dwordx4 v[54:55], v[42:45], off offset:2048
	s_nop 1
	v_mov_b32_e32 v42, v226
	v_mov_b32_e32 v43, v227
	v_mov_b32_e32 v44, v228
	v_mov_b32_e32 v45, v229
	s_nop 0
	v_lshlrev_b32_e32 v46, 16, v42
	v_and_b32_e32 v47, 0xffff0000, v42
	v_lshlrev_b32_e32 v42, 16, v43
	v_and_b32_e32 v43, 0xffff0000, v43
	v_pk_fma_f32 v[40:41], v[40:41], v[146:147], v[42:43]
	v_lshlrev_b32_e32 v42, 16, v44
	v_and_b32_e32 v43, 0xffff0000, v44
	v_pk_fma_f32 v[42:43], v[34:35], v[144:145], v[42:43]
	v_lshlrev_b32_e32 v34, 16, v45
	v_and_b32_e32 v35, 0xffff0000, v45
	v_pk_fma_f32 v[38:39], v[38:39], v[148:149], v[46:47]
	v_pk_fma_f32 v[44:45], v[36:37], v[142:143], v[34:35]
	v_cvt_pk_bf16_f32 v34, v38, v39
	v_cvt_pk_bf16_f32 v35, v40, v41
	v_cvt_pk_bf16_f32 v36, v42, v43
	v_cvt_pk_bf16_f32 v37, v44, v45
	v_lshl_add_u64 v[38:39], v[158:159], 0, s[14:15]
	global_store_dwordx4 v[54:55], v[34:37], off offset:2304
	s_nop 1
	v_mov_b32_e32 v34, v230
	v_mov_b32_e32 v35, v231
	v_mov_b32_e32 v36, v232
	v_mov_b32_e32 v37, v233
	s_mov_b64 s[14:15], 0xb0000
	s_nop 0
	v_lshlrev_b32_e32 v40, 16, v34
	v_and_b32_e32 v41, 0xffff0000, v34
	v_lshlrev_b32_e32 v34, 16, v35
	v_and_b32_e32 v35, 0xffff0000, v35
	v_pk_fma_f32 v[32:33], v[32:33], v[152:153], v[34:35]
	v_lshlrev_b32_e32 v34, 16, v36
	v_and_b32_e32 v35, 0xffff0000, v36
	v_pk_fma_f32 v[34:35], v[26:27], v[154:155], v[34:35]
	v_lshlrev_b32_e32 v26, 16, v37
	v_and_b32_e32 v27, 0xffff0000, v37
	v_pk_fma_f32 v[30:31], v[30:31], v[156:157], v[40:41]
	v_pk_fma_f32 v[36:37], v[28:29], v[150:151], v[26:27]
	v_cvt_pk_bf16_f32 v26, v30, v31
	v_cvt_pk_bf16_f32 v27, v32, v33
	v_cvt_pk_bf16_f32 v28, v34, v35
	v_cvt_pk_bf16_f32 v29, v36, v37
	global_store_dwordx4 v[38:39], v[26:29], off offset:2048
	s_nop 1
	v_mov_b32_e32 v26, v236
	v_mov_b32_e32 v27, v237
	v_mov_b32_e32 v28, v238
	v_mov_b32_e32 v29, v239
	s_nop 0
	v_lshlrev_b32_e32 v30, 16, v26
	v_and_b32_e32 v31, 0xffff0000, v26
	v_lshlrev_b32_e32 v26, 16, v27
	v_and_b32_e32 v27, 0xffff0000, v27
	v_pk_fma_f32 v[24:25], v[24:25], v[146:147], v[26:27]
	v_lshlrev_b32_e32 v26, 16, v28
	v_and_b32_e32 v27, 0xffff0000, v28
	v_pk_fma_f32 v[26:27], v[18:19], v[144:145], v[26:27]
	v_lshlrev_b32_e32 v18, 16, v29
	v_and_b32_e32 v19, 0xffff0000, v29
	v_pk_fma_f32 v[22:23], v[22:23], v[148:149], v[30:31]
	v_pk_fma_f32 v[28:29], v[20:21], v[142:143], v[18:19]
	v_cvt_pk_bf16_f32 v18, v22, v23
	v_cvt_pk_bf16_f32 v19, v24, v25
	v_cvt_pk_bf16_f32 v20, v26, v27
	v_cvt_pk_bf16_f32 v21, v28, v29
	global_store_dwordx4 v[38:39], v[18:21], off offset:2304
	s_nop 1
	v_lshl_add_u64 v[18:19], v[158:159], 0, s[14:15]
	v_mov_b32_e32 v20, v246
	v_mov_b32_e32 v21, v247
	v_mov_b32_e32 v22, v248
	v_mov_b32_e32 v23, v249
	s_mov_b64 s[14:15], s[6:7]
	s_nop 0
	v_lshlrev_b32_e32 v24, 16, v20
	v_and_b32_e32 v25, 0xffff0000, v20
	v_lshlrev_b32_e32 v20, 16, v21
	v_and_b32_e32 v21, 0xffff0000, v21
	v_pk_fma_f32 v[16:17], v[16:17], v[152:153], v[20:21]
	v_lshlrev_b32_e32 v20, 16, v22
	v_and_b32_e32 v21, 0xffff0000, v22
	v_pk_fma_f32 v[20:21], v[10:11], v[154:155], v[20:21]
	v_lshlrev_b32_e32 v10, 16, v23
	v_and_b32_e32 v11, 0xffff0000, v23
	v_pk_fma_f32 v[14:15], v[14:15], v[156:157], v[24:25]
	v_pk_fma_f32 v[22:23], v[12:13], v[150:151], v[10:11]
	v_cvt_pk_bf16_f32 v10, v14, v15
	v_cvt_pk_bf16_f32 v11, v16, v17
	v_cvt_pk_bf16_f32 v12, v20, v21
	v_cvt_pk_bf16_f32 v13, v22, v23
	global_store_dwordx4 v[18:19], v[10:13], off offset:2048
	s_nop 1
	v_mov_b32_e32 v10, v250
	v_mov_b32_e32 v11, v251
	v_mov_b32_e32 v12, v252
	v_mov_b32_e32 v13, v253
	s_nop 0
	v_lshlrev_b32_e32 v14, 16, v10
	v_and_b32_e32 v15, 0xffff0000, v10
	v_lshlrev_b32_e32 v10, 16, v11
	v_and_b32_e32 v11, 0xffff0000, v11
	v_pk_fma_f32 v[8:9], v[8:9], v[146:147], v[10:11]
	v_lshlrev_b32_e32 v10, 16, v12
	v_and_b32_e32 v11, 0xffff0000, v12
	v_pk_fma_f32 v[10:11], v[2:3], v[144:145], v[10:11]
	v_lshlrev_b32_e32 v2, 16, v13
	v_and_b32_e32 v3, 0xffff0000, v13
	v_pk_fma_f32 v[6:7], v[6:7], v[148:149], v[14:15]
	v_pk_fma_f32 v[12:13], v[4:5], v[142:143], v[2:3]
	v_cvt_pk_bf16_f32 v2, v6, v7
	v_cvt_pk_bf16_f32 v3, v8, v9
	v_cvt_pk_bf16_f32 v4, v10, v11
	v_cvt_pk_bf16_f32 v5, v12, v13
	global_store_dwordx4 v[18:19], v[2:5], off offset:2304
	s_cbranch_vccz .LBB0_363
	s_waitcnt vmcnt(0)
	s_cmpk_gt_u32 s30, 0xff
	s_cbranch_scc1 .LBB0_378
	s_barrier

.LBB0_399:
	s_add_u32 s46, s16, 0x100
	s_addc_u32 s47, s17, 0
	s_mov_b32 s48, -2
	s_add_u32 s16, s14, 0x100
	s_addc_u32 s17, s15, 0
	s_add_i32 s49, 0, 0x10000
	v_add_u32_e32 v154, s49, v164
	ds_read_b128 v[142:145], v154
	ds_read_b128 v[146:149], v154 offset:1024
	ds_read_b128 v[150:153], v154 offset:2048
	ds_read_b128 v[154:157], v154 offset:3072
	s_cmp_eq_u32 s48, 40
	s_cselect_b32 s21, s7, s17
	s_cselect_b32 s20, s6, s16
	s_cselect_b32 s19, s9, s47
	s_cselect_b32 s18, s8, s46
	v_lshl_add_u64 v[162:163], s[14:15], 0, v[138:139]
	s_add_i32 m0, s34, 0xc000
	ds_read_b128 v[158:161], v166
	ds_read_b128 v[168:171], v166 offset:1024
	ds_read_b128 v[172:175], v166 offset:2048
	ds_read_b128 v[190:193], v166 offset:3072
	ds_read_b128 v[194:197], v166 offset:4096
	ds_read_b128 v[198:201], v166 offset:5120
	ds_read_b128 v[202:205], v166 offset:6144
	ds_read_b128 v[206:209], v166 offset:7168
	global_load_lds_dwordx4 v[162:163], off
	v_lshl_add_u64 v[162:163], s[14:15], 0, v[140:141]
	s_add_i32 m0, s34, 0xe000
	s_nop 0
	global_load_lds_dwordx4 v[162:163], off
	s_waitcnt lgkmcnt(8)
	s_barrier
	s_waitcnt lgkmcnt(0)
	s_waitcnt lgkmcnt(0)
	v_mfma_f32_16x16x32_bf16 v[126:129], v[142:145], v[158:161], 0
	v_mfma_f32_16x16x32_bf16 v[122:125], v[150:153], v[158:161], 0
	v_mfma_f32_16x16x32_bf16 v[110:113], v[142:145], v[172:175], 0
	v_mfma_f32_16x16x32_bf16 v[106:109], v[150:153], v[172:175], 0
	v_mfma_f32_16x16x32_bf16 v[94:97], v[142:145], v[194:197], 0
	v_mfma_f32_16x16x32_bf16 v[90:93], v[150:153], v[194:197], 0
	v_mfma_f32_16x16x32_bf16 v[78:81], v[142:145], v[202:205], 0
	v_mfma_f32_16x16x32_bf16 v[74:77], v[150:153], v[202:205], 0
	v_mfma_f32_16x16x32_bf16 v[126:129], v[146:149], v[168:171], v[126:129]
	v_mfma_f32_16x16x32_bf16 v[122:125], v[154:157], v[168:171], v[122:125]
	v_mfma_f32_16x16x32_bf16 v[110:113], v[146:149], v[190:193], v[110:113]
	v_mfma_f32_16x16x32_bf16 v[106:109], v[154:157], v[190:193], v[106:109]
	v_mfma_f32_16x16x32_bf16 v[94:97], v[146:149], v[198:201], v[94:97]
	v_mfma_f32_16x16x32_bf16 v[90:93], v[154:157], v[198:201], v[90:93]
	v_mfma_f32_16x16x32_bf16 v[78:81], v[146:149], v[206:209], v[78:81]
	v_mfma_f32_16x16x32_bf16 v[74:77], v[154:157], v[206:209], v[74:77]
	s_barrier
	s_add_i32 s50, 0, 0x14000
	v_add_u32_e32 v162, s50, v164
	s_add_i32 s14, s49, s33
	ds_read_b128 v[210:213], v162
	ds_read_b128 v[214:217], v162 offset:1024
	ds_read_b128 v[218:221], v162 offset:2048
	ds_read_b128 v[222:225], v162 offset:3072
	s_add_u32 s64, s18, 0x80
	s_addc_u32 s65, s19, 0
	s_mov_b32 m0, s14
	s_nop 0
	global_load_lds_dwordx4 v132, s[18:19]
	s_add_i32 m0, s14, 0x2000
	s_nop 0
	global_load_lds_dwordx4 v136, s[18:19]
	s_barrier
	s_waitcnt lgkmcnt(0)
	s_waitcnt lgkmcnt(0)
	v_mfma_f32_16x16x32_bf16 v[118:121], v[210:213], v[158:161], 0
	v_mfma_f32_16x16x32_bf16 v[114:117], v[218:221], v[158:161], 0
	v_mfma_f32_16x16x32_bf16 v[102:105], v[210:213], v[172:175], 0
	v_mfma_f32_16x16x32_bf16 v[98:101], v[218:221], v[172:175], 0
	v_mfma_f32_16x16x32_bf16 v[86:89], v[210:213], v[194:197], 0
	v_mfma_f32_16x16x32_bf16 v[82:85], v[218:221], v[194:197], 0
	v_mfma_f32_16x16x32_bf16 v[70:73], v[210:213], v[202:205], 0
	v_mfma_f32_16x16x32_bf16 v[66:69], v[218:221], v[202:205], 0
	ds_read_b128 v[158:161], v166 offset:16384
	v_mfma_f32_16x16x32_bf16 v[118:121], v[214:217], v[168:171], v[118:121]
	v_mfma_f32_16x16x32_bf16 v[114:117], v[222:225], v[168:171], v[114:117]
	ds_read_b128 v[172:175], v166 offset:18432
	v_mfma_f32_16x16x32_bf16 v[102:105], v[214:217], v[190:193], v[102:105]
	v_mfma_f32_16x16x32_bf16 v[98:101], v[222:225], v[190:193], v[98:101]
	ds_read_b128 v[194:197], v166 offset:20480
	v_mfma_f32_16x16x32_bf16 v[86:89], v[214:217], v[198:201], v[86:89]
	v_mfma_f32_16x16x32_bf16 v[82:85], v[222:225], v[198:201], v[82:85]
	ds_read_b128 v[202:205], v166 offset:22528
	v_mfma_f32_16x16x32_bf16 v[70:73], v[214:217], v[206:209], v[70:73]
	v_mfma_f32_16x16x32_bf16 v[66:69], v[222:225], v[206:209], v[66:69]
	s_barrier
	s_mov_b32 m0, s34
	s_add_u32 s62, s20, 0x80
	s_addc_u32 s63, s21, 0
	ds_read_b128 v[168:171], v166 offset:17408
	ds_read_b128 v[190:193], v166 offset:19456
	ds_read_b128 v[198:201], v166 offset:21504
	ds_read_b128 v[206:209], v166 offset:23552
	global_load_lds_dwordx4 v130, s[20:21]
	s_mov_b32 m0, s35
	s_nop 0
	global_load_lds_dwordx4 v134, s[20:21]
	s_waitcnt vmcnt(8)
	s_barrier
	s_waitcnt lgkmcnt(0)
	s_waitcnt lgkmcnt(0)
	v_mfma_f32_16x16x32_bf16 v[62:65], v[142:145], v[158:161], 0
	v_mfma_f32_16x16x32_bf16 v[58:61], v[150:153], v[158:161], 0
	v_mfma_f32_16x16x32_bf16 v[46:49], v[142:145], v[172:175], 0
	v_mfma_f32_16x16x32_bf16 v[42:45], v[150:153], v[172:175], 0
	v_mfma_f32_16x16x32_bf16 v[30:33], v[142:145], v[194:197], 0
	v_mfma_f32_16x16x32_bf16 v[26:29], v[150:153], v[194:197], 0
	v_mfma_f32_16x16x32_bf16 v[14:17], v[142:145], v[202:205], 0
	v_mfma_f32_16x16x32_bf16 v[10:13], v[150:153], v[202:205], 0
	v_mfma_f32_16x16x32_bf16 v[62:65], v[146:149], v[168:171], v[62:65]
	v_mfma_f32_16x16x32_bf16 v[58:61], v[154:157], v[168:171], v[58:61]
	v_mfma_f32_16x16x32_bf16 v[46:49], v[146:149], v[190:193], v[46:49]
	v_mfma_f32_16x16x32_bf16 v[42:45], v[154:157], v[190:193], v[42:45]
	v_mfma_f32_16x16x32_bf16 v[30:33], v[146:149], v[198:201], v[30:33]
	v_mfma_f32_16x16x32_bf16 v[26:29], v[154:157], v[198:201], v[26:29]
	v_mfma_f32_16x16x32_bf16 v[14:17], v[146:149], v[206:209], v[14:17]
	v_mfma_f32_16x16x32_bf16 v[10:13], v[154:157], v[206:209], v[10:13]
	s_barrier
	v_add_u32_e32 v154, 0x18000, v164
	ds_read_b128 v[142:145], v154
	ds_read_b128 v[146:149], v154 offset:1024
	ds_read_b128 v[150:153], v154 offset:2048
	ds_read_b128 v[154:157], v154 offset:3072
	s_add_u32 s14, s18, 0xb0000
	s_addc_u32 s15, s19, 0
	s_add_i32 s49, s50, s33
	s_mov_b32 m0, s49
	s_nop 0
	global_load_lds_dwordx4 v132, s[14:15]
	s_add_i32 m0, s49, 0x2000
	s_nop 0
	global_load_lds_dwordx4 v136, s[14:15]
	s_waitcnt vmcnt(6)
	s_barrier
	v_mfma_f32_16x16x32_bf16 v[54:57], v[210:213], v[158:161], 0
	v_mfma_f32_16x16x32_bf16 v[50:53], v[218:221], v[158:161], 0
	v_mfma_f32_16x16x32_bf16 v[38:41], v[210:213], v[172:175], 0
	v_mfma_f32_16x16x32_bf16 v[34:37], v[218:221], v[172:175], 0
	v_mfma_f32_16x16x32_bf16 v[22:25], v[210:213], v[194:197], 0
	v_mfma_f32_16x16x32_bf16 v[18:21], v[218:221], v[194:197], 0
	v_mfma_f32_16x16x32_bf16 v[6:9], v[210:213], v[202:205], 0
	v_mfma_f32_16x16x32_bf16 v[2:5], v[218:221], v[202:205], 0
	ds_read_b128 v[158:161], v166 offset:32768
	v_mfma_f32_16x16x32_bf16 v[54:57], v[214:217], v[168:171], v[54:57]
	v_mfma_f32_16x16x32_bf16 v[50:53], v[222:225], v[168:171], v[50:53]
	ds_read_b128 v[172:175], v166 offset:34816
	v_mfma_f32_16x16x32_bf16 v[38:41], v[214:217], v[190:193], v[38:41]
	v_mfma_f32_16x16x32_bf16 v[34:37], v[222:225], v[190:193], v[34:37]
	ds_read_b128 v[194:197], v166 offset:36864
	v_mfma_f32_16x16x32_bf16 v[22:25], v[214:217], v[198:201], v[22:25]
	v_mfma_f32_16x16x32_bf16 v[18:21], v[222:225], v[198:201], v[18:21]
	ds_read_b128 v[202:205], v166 offset:38912
	v_mfma_f32_16x16x32_bf16 v[6:9], v[214:217], v[206:209], v[6:9]
	v_mfma_f32_16x16x32_bf16 v[2:5], v[222:225], v[206:209], v[2:5]
	s_barrier
	s_add_i32 s49, 0, 0x18000
	s_add_u32 s14, s20, 0xb8000
	s_addc_u32 s15, s21, 0
	s_mov_b32 m0, s36
	ds_read_b128 v[168:171], v166 offset:33792
	ds_read_b128 v[190:193], v166 offset:35840
	ds_read_b128 v[198:201], v166 offset:37888
	ds_read_b128 v[206:209], v166 offset:39936
	global_load_lds_dwordx4 v130, s[14:15]
	s_mov_b32 m0, s37
	s_nop 0
	global_load_lds_dwordx4 v134, s[14:15]
	s_waitcnt lgkmcnt(8)
	s_barrier
	s_waitcnt lgkmcnt(0)
	s_waitcnt lgkmcnt(0)
	v_mfma_f32_16x16x32_bf16 v[126:129], v[142:145], v[158:161], v[126:129]
	v_mfma_f32_16x16x32_bf16 v[122:125], v[150:153], v[158:161], v[122:125]
	v_mfma_f32_16x16x32_bf16 v[110:113], v[142:145], v[172:175], v[110:113]
	v_mfma_f32_16x16x32_bf16 v[106:109], v[150:153], v[172:175], v[106:109]
	v_mfma_f32_16x16x32_bf16 v[94:97], v[142:145], v[194:197], v[94:97]
	v_mfma_f32_16x16x32_bf16 v[90:93], v[150:153], v[194:197], v[90:93]
	v_mfma_f32_16x16x32_bf16 v[78:81], v[142:145], v[202:205], v[78:81]
	v_mfma_f32_16x16x32_bf16 v[74:77], v[150:153], v[202:205], v[74:77]
	v_mfma_f32_16x16x32_bf16 v[126:129], v[146:149], v[168:171], v[126:129]
	v_mfma_f32_16x16x32_bf16 v[122:125], v[154:157], v[168:171], v[122:125]
	v_mfma_f32_16x16x32_bf16 v[110:113], v[146:149], v[190:193], v[110:113]
	v_mfma_f32_16x16x32_bf16 v[106:109], v[154:157], v[190:193], v[106:109]
	v_mfma_f32_16x16x32_bf16 v[94:97], v[146:149], v[198:201], v[94:97]
	v_mfma_f32_16x16x32_bf16 v[90:93], v[154:157], v[198:201], v[90:93]
	v_mfma_f32_16x16x32_bf16 v[78:81], v[146:149], v[206:209], v[78:81]
	v_mfma_f32_16x16x32_bf16 v[74:77], v[154:157], v[206:209], v[74:77]
	s_barrier
	s_add_i32 s20, 0, 0x1c000
	s_add_i32 s14, s49, s33
	v_add_u32_e32 v167, s20, v164
	s_mov_b32 m0, s14
	ds_read_b128 v[210:213], v167
	ds_read_b128 v[214:217], v167 offset:1024
	ds_read_b128 v[218:221], v167 offset:2048
	ds_read_b128 v[222:225], v167 offset:3072
	global_load_lds_dwordx4 v132, s[64:65]
	s_add_i32 m0, s14, 0x2000
	s_nop 0
	global_load_lds_dwordx4 v136, s[64:65]
	s_barrier
	s_waitcnt lgkmcnt(0)
	s_waitcnt lgkmcnt(0)
	v_mfma_f32_16x16x32_bf16 v[118:121], v[210:213], v[158:161], v[118:121]
	v_mfma_f32_16x16x32_bf16 v[114:117], v[218:221], v[158:161], v[114:117]
	v_mfma_f32_16x16x32_bf16 v[102:105], v[210:213], v[172:175], v[102:105]
	v_mfma_f32_16x16x32_bf16 v[98:101], v[218:221], v[172:175], v[98:101]
	v_mfma_f32_16x16x32_bf16 v[86:89], v[210:213], v[194:197], v[86:89]
	v_mfma_f32_16x16x32_bf16 v[82:85], v[218:221], v[194:197], v[82:85]
	v_mfma_f32_16x16x32_bf16 v[70:73], v[210:213], v[202:205], v[70:73]
	v_mfma_f32_16x16x32_bf16 v[66:69], v[218:221], v[202:205], v[66:69]
	ds_read_b128 v[158:161], v166 offset:49152
	v_mfma_f32_16x16x32_bf16 v[118:121], v[214:217], v[168:171], v[118:121]
	v_mfma_f32_16x16x32_bf16 v[114:117], v[222:225], v[168:171], v[114:117]
	ds_read_b128 v[172:175], v166 offset:51200
	v_mfma_f32_16x16x32_bf16 v[102:105], v[214:217], v[190:193], v[102:105]
	v_mfma_f32_16x16x32_bf16 v[98:101], v[222:225], v[190:193], v[98:101]
	ds_read_b128 v[194:197], v166 offset:53248
	v_mfma_f32_16x16x32_bf16 v[86:89], v[214:217], v[198:201], v[86:89]
	v_mfma_f32_16x16x32_bf16 v[82:85], v[222:225], v[198:201], v[82:85]
	ds_read_b128 v[202:205], v166 offset:55296
	v_mfma_f32_16x16x32_bf16 v[70:73], v[214:217], v[206:209], v[70:73]
	v_mfma_f32_16x16x32_bf16 v[66:69], v[222:225], v[206:209], v[66:69]
	s_barrier
	s_mov_b32 m0, s38
	ds_read_b128 v[168:171], v166 offset:50176
	ds_read_b128 v[190:193], v166 offset:52224
	ds_read_b128 v[198:201], v166 offset:54272
	ds_read_b128 v[206:209], v166 offset:56320
	global_load_lds_dwordx4 v130, s[62:63]
	s_mov_b32 m0, s39
	s_nop 0
	global_load_lds_dwordx4 v134, s[62:63]
	s_waitcnt vmcnt(8)
	s_barrier
	s_waitcnt lgkmcnt(0)
	s_waitcnt lgkmcnt(0)
	v_mfma_f32_16x16x32_bf16 v[62:65], v[142:145], v[158:161], v[62:65]
	v_mfma_f32_16x16x32_bf16 v[58:61], v[150:153], v[158:161], v[58:61]
	v_mfma_f32_16x16x32_bf16 v[46:49], v[142:145], v[172:175], v[46:49]
	v_mfma_f32_16x16x32_bf16 v[42:45], v[150:153], v[172:175], v[42:45]
	v_mfma_f32_16x16x32_bf16 v[30:33], v[142:145], v[194:197], v[30:33]
	v_mfma_f32_16x16x32_bf16 v[26:29], v[150:153], v[194:197], v[26:29]
	v_mfma_f32_16x16x32_bf16 v[14:17], v[142:145], v[202:205], v[14:17]
	v_mfma_f32_16x16x32_bf16 v[10:13], v[150:153], v[202:205], v[10:13]
	v_mfma_f32_16x16x32_bf16 v[62:65], v[146:149], v[168:171], v[62:65]
	v_mfma_f32_16x16x32_bf16 v[58:61], v[154:157], v[168:171], v[58:61]
	v_mfma_f32_16x16x32_bf16 v[46:49], v[146:149], v[190:193], v[46:49]
	v_mfma_f32_16x16x32_bf16 v[42:45], v[154:157], v[190:193], v[42:45]
	v_mfma_f32_16x16x32_bf16 v[30:33], v[146:149], v[198:201], v[30:33]
	v_mfma_f32_16x16x32_bf16 v[26:29], v[154:157], v[198:201], v[26:29]
	v_mfma_f32_16x16x32_bf16 v[14:17], v[146:149], v[206:209], v[14:17]
	v_mfma_f32_16x16x32_bf16 v[10:13], v[154:157], v[206:209], v[10:13]
	s_barrier
	v_add_u32_e32 v154, 0x10000, v164
	ds_read_b128 v[142:145], v154
	ds_read_b128 v[146:149], v154 offset:1024
	ds_read_b128 v[150:153], v154 offset:2048
	ds_read_b128 v[154:157], v154 offset:3072
	s_add_u32 s14, s18, 0xb0080
	s_addc_u32 s15, s19, 0
	s_add_i32 s18, s20, s33
	s_mov_b32 m0, s18
	s_nop 0
	global_load_lds_dwordx4 v132, s[14:15]
	s_add_i32 m0, s18, 0x2000
	s_nop 0
	global_load_lds_dwordx4 v136, s[14:15]
	s_waitcnt vmcnt(6)
	s_barrier
	v_mfma_f32_16x16x32_bf16 v[54:57], v[210:213], v[158:161], v[54:57]
	v_mfma_f32_16x16x32_bf16 v[50:53], v[218:221], v[158:161], v[50:53]
	v_mfma_f32_16x16x32_bf16 v[38:41], v[210:213], v[172:175], v[38:41]
	v_mfma_f32_16x16x32_bf16 v[34:37], v[218:221], v[172:175], v[34:37]
	v_mfma_f32_16x16x32_bf16 v[22:25], v[210:213], v[194:197], v[22:25]
	v_mfma_f32_16x16x32_bf16 v[18:21], v[218:221], v[194:197], v[18:21]
	v_mfma_f32_16x16x32_bf16 v[6:9], v[210:213], v[202:205], v[6:9]
	v_mfma_f32_16x16x32_bf16 v[2:5], v[218:221], v[202:205], v[2:5]
	ds_read_b128 v[158:161], v166
	v_mfma_f32_16x16x32_bf16 v[54:57], v[214:217], v[168:171], v[54:57]
	v_mfma_f32_16x16x32_bf16 v[50:53], v[222:225], v[168:171], v[50:53]
	ds_read_b128 v[172:175], v166 offset:2048
	v_mfma_f32_16x16x32_bf16 v[38:41], v[214:217], v[190:193], v[38:41]
	v_mfma_f32_16x16x32_bf16 v[34:37], v[222:225], v[190:193], v[34:37]
	ds_read_b128 v[194:197], v166 offset:4096
	v_mfma_f32_16x16x32_bf16 v[22:25], v[214:217], v[198:201], v[22:25]
	v_mfma_f32_16x16x32_bf16 v[18:21], v[222:225], v[198:201], v[18:21]
	ds_read_b128 v[202:205], v166 offset:6144
	v_mfma_f32_16x16x32_bf16 v[6:9], v[214:217], v[206:209], v[6:9]
	v_mfma_f32_16x16x32_bf16 v[2:5], v[222:225], v[206:209], v[2:5]
	s_barrier
	s_add_i32 s48, s48, 2
	s_add_u32 s46, s46, 0x100
	s_addc_u32 s47, s47, 0
	s_mov_b64 s[14:15], s[16:17]
.LBB0_400:
	s_add_u32 s16, s14, 0x100
	s_addc_u32 s17, s15, 0
	s_add_i32 s49, 0, 0x10000
	s_cmp_eq_u32 s48, 40
	s_cselect_b32 s21, s7, s17
	s_cselect_b32 s20, s6, s16
	s_cselect_b32 s19, s9, s47
	s_cselect_b32 s18, s8, s46
	v_lshl_add_u64 v[162:163], s[14:15], 0, v[138:139]
	s_add_i32 m0, s34, 0xc000
	ds_read_b128 v[168:171], v166 offset:1024
	ds_read_b128 v[190:193], v166 offset:3072
	ds_read_b128 v[198:201], v166 offset:5120
	ds_read_b128 v[206:209], v166 offset:7168
	global_load_lds_dwordx4 v[162:163], off
	v_lshl_add_u64 v[162:163], s[14:15], 0, v[140:141]
	s_add_i32 m0, s34, 0xe000
	s_nop 0
	global_load_lds_dwordx4 v[162:163], off
	s_waitcnt lgkmcnt(8)
	s_barrier
	s_waitcnt lgkmcnt(0)
	s_waitcnt lgkmcnt(0)
	v_mfma_f32_16x16x32_bf16 v[126:129], v[142:145], v[158:161], v[126:129]
	v_mfma_f32_16x16x32_bf16 v[122:125], v[150:153], v[158:161], v[122:125]
	v_mfma_f32_16x16x32_bf16 v[110:113], v[142:145], v[172:175], v[110:113]
	v_mfma_f32_16x16x32_bf16 v[106:109], v[150:153], v[172:175], v[106:109]
	v_mfma_f32_16x16x32_bf16 v[94:97], v[142:145], v[194:197], v[94:97]
	v_mfma_f32_16x16x32_bf16 v[90:93], v[150:153], v[194:197], v[90:93]
	v_mfma_f32_16x16x32_bf16 v[78:81], v[142:145], v[202:205], v[78:81]
	v_mfma_f32_16x16x32_bf16 v[74:77], v[150:153], v[202:205], v[74:77]
	v_mfma_f32_16x16x32_bf16 v[126:129], v[146:149], v[168:171], v[126:129]
	v_mfma_f32_16x16x32_bf16 v[122:125], v[154:157], v[168:171], v[122:125]
	v_mfma_f32_16x16x32_bf16 v[110:113], v[146:149], v[190:193], v[110:113]
	v_mfma_f32_16x16x32_bf16 v[106:109], v[154:157], v[190:193], v[106:109]
	v_mfma_f32_16x16x32_bf16 v[94:97], v[146:149], v[198:201], v[94:97]
	v_mfma_f32_16x16x32_bf16 v[90:93], v[154:157], v[198:201], v[90:93]
	v_mfma_f32_16x16x32_bf16 v[78:81], v[146:149], v[206:209], v[78:81]
	v_mfma_f32_16x16x32_bf16 v[74:77], v[154:157], v[206:209], v[74:77]
	s_barrier
	s_add_i32 s50, 0, 0x14000
	v_add_u32_e32 v162, s50, v164
	s_add_i32 s14, s49, s33
	ds_read_b128 v[210:213], v162
	ds_read_b128 v[214:217], v162 offset:1024
	ds_read_b128 v[218:221], v162 offset:2048
	ds_read_b128 v[222:225], v162 offset:3072
	s_add_u32 s64, s18, 0x80
	s_addc_u32 s65, s19, 0
	s_mov_b32 m0, s14
	s_nop 0
	global_load_lds_dwordx4 v132, s[18:19]
	s_add_i32 m0, s14, 0x2000
	s_nop 0
	global_load_lds_dwordx4 v136, s[18:19]
	s_barrier
	s_waitcnt lgkmcnt(0)
	s_waitcnt lgkmcnt(0)
	v_mfma_f32_16x16x32_bf16 v[118:121], v[210:213], v[158:161], v[118:121]
	v_mfma_f32_16x16x32_bf16 v[114:117], v[218:221], v[158:161], v[114:117]
	v_mfma_f32_16x16x32_bf16 v[102:105], v[210:213], v[172:175], v[102:105]
	v_mfma_f32_16x16x32_bf16 v[98:101], v[218:221], v[172:175], v[98:101]
	v_mfma_f32_16x16x32_bf16 v[86:89], v[210:213], v[194:197], v[86:89]
	v_mfma_f32_16x16x32_bf16 v[82:85], v[218:221], v[194:197], v[82:85]
	v_mfma_f32_16x16x32_bf16 v[70:73], v[210:213], v[202:205], v[70:73]
	v_mfma_f32_16x16x32_bf16 v[66:69], v[218:221], v[202:205], v[66:69]
	ds_read_b128 v[158:161], v166 offset:16384
	v_mfma_f32_16x16x32_bf16 v[118:121], v[214:217], v[168:171], v[118:121]
	v_mfma_f32_16x16x32_bf16 v[114:117], v[222:225], v[168:171], v[114:117]
	ds_read_b128 v[172:175], v166 offset:18432
	v_mfma_f32_16x16x32_bf16 v[102:105], v[214:217], v[190:193], v[102:105]
	v_mfma_f32_16x16x32_bf16 v[98:101], v[222:225], v[190:193], v[98:101]
	ds_read_b128 v[194:197], v166 offset:20480
	v_mfma_f32_16x16x32_bf16 v[86:89], v[214:217], v[198:201], v[86:89]
	v_mfma_f32_16x16x32_bf16 v[82:85], v[222:225], v[198:201], v[82:85]
	ds_read_b128 v[202:205], v166 offset:22528
	v_mfma_f32_16x16x32_bf16 v[70:73], v[214:217], v[206:209], v[70:73]
	v_mfma_f32_16x16x32_bf16 v[66:69], v[222:225], v[206:209], v[66:69]
	s_barrier
	s_mov_b32 m0, s34
	s_add_u32 s62, s20, 0x80
	s_addc_u32 s63, s21, 0
	ds_read_b128 v[168:171], v166 offset:17408
	ds_read_b128 v[190:193], v166 offset:19456
	ds_read_b128 v[198:201], v166 offset:21504
	ds_read_b128 v[206:209], v166 offset:23552
	global_load_lds_dwordx4 v130, s[20:21]
	s_mov_b32 m0, s35
	s_nop 0
	global_load_lds_dwordx4 v134, s[20:21]
	s_waitcnt vmcnt(8)
	s_barrier
	s_waitcnt lgkmcnt(0)
	s_waitcnt lgkmcnt(0)
	v_mfma_f32_16x16x32_bf16 v[62:65], v[142:145], v[158:161], v[62:65]
	v_mfma_f32_16x16x32_bf16 v[58:61], v[150:153], v[158:161], v[58:61]
	v_mfma_f32_16x16x32_bf16 v[46:49], v[142:145], v[172:175], v[46:49]
	v_mfma_f32_16x16x32_bf16 v[42:45], v[150:153], v[172:175], v[42:45]
	v_mfma_f32_16x16x32_bf16 v[30:33], v[142:145], v[194:197], v[30:33]
	v_mfma_f32_16x16x32_bf16 v[26:29], v[150:153], v[194:197], v[26:29]
	v_mfma_f32_16x16x32_bf16 v[14:17], v[142:145], v[202:205], v[14:17]
	v_mfma_f32_16x16x32_bf16 v[10:13], v[150:153], v[202:205], v[10:13]
	v_mfma_f32_16x16x32_bf16 v[62:65], v[146:149], v[168:171], v[62:65]
	v_mfma_f32_16x16x32_bf16 v[58:61], v[154:157], v[168:171], v[58:61]
	v_mfma_f32_16x16x32_bf16 v[46:49], v[146:149], v[190:193], v[46:49]
	v_mfma_f32_16x16x32_bf16 v[42:45], v[154:157], v[190:193], v[42:45]
	v_mfma_f32_16x16x32_bf16 v[30:33], v[146:149], v[198:201], v[30:33]
	v_mfma_f32_16x16x32_bf16 v[26:29], v[154:157], v[198:201], v[26:29]
	v_mfma_f32_16x16x32_bf16 v[14:17], v[146:149], v[206:209], v[14:17]
	v_mfma_f32_16x16x32_bf16 v[10:13], v[154:157], v[206:209], v[10:13]
	s_barrier
	v_add_u32_e32 v154, 0x18000, v164
	ds_read_b128 v[142:145], v154
	ds_read_b128 v[146:149], v154 offset:1024
	ds_read_b128 v[150:153], v154 offset:2048
	ds_read_b128 v[154:157], v154 offset:3072
	s_add_u32 s14, s18, 0xb0000
	s_addc_u32 s15, s19, 0
	s_add_i32 s49, s50, s33
	s_mov_b32 m0, s49
	s_nop 0
	global_load_lds_dwordx4 v132, s[14:15]
	s_add_i32 m0, s49, 0x2000
	s_nop 0
	global_load_lds_dwordx4 v136, s[14:15]
	s_waitcnt vmcnt(6)
	s_barrier
	v_mfma_f32_16x16x32_bf16 v[54:57], v[210:213], v[158:161], v[54:57]
	v_mfma_f32_16x16x32_bf16 v[50:53], v[218:221], v[158:161], v[50:53]
	v_mfma_f32_16x16x32_bf16 v[38:41], v[210:213], v[172:175], v[38:41]
	v_mfma_f32_16x16x32_bf16 v[34:37], v[218:221], v[172:175], v[34:37]
	v_mfma_f32_16x16x32_bf16 v[22:25], v[210:213], v[194:197], v[22:25]
	v_mfma_f32_16x16x32_bf16 v[18:21], v[218:221], v[194:197], v[18:21]
	v_mfma_f32_16x16x32_bf16 v[6:9], v[210:213], v[202:205], v[6:9]
	v_mfma_f32_16x16x32_bf16 v[2:5], v[218:221], v[202:205], v[2:5]
	ds_read_b128 v[158:161], v166 offset:32768
	v_mfma_f32_16x16x32_bf16 v[54:57], v[214:217], v[168:171], v[54:57]
	v_mfma_f32_16x16x32_bf16 v[50:53], v[222:225], v[168:171], v[50:53]
	ds_read_b128 v[172:175], v166 offset:34816
	v_mfma_f32_16x16x32_bf16 v[38:41], v[214:217], v[190:193], v[38:41]
	v_mfma_f32_16x16x32_bf16 v[34:37], v[222:225], v[190:193], v[34:37]
	ds_read_b128 v[194:197], v166 offset:36864
	v_mfma_f32_16x16x32_bf16 v[22:25], v[214:217], v[198:201], v[22:25]
	v_mfma_f32_16x16x32_bf16 v[18:21], v[222:225], v[198:201], v[18:21]
	ds_read_b128 v[202:205], v166 offset:38912
	v_mfma_f32_16x16x32_bf16 v[6:9], v[214:217], v[206:209], v[6:9]
	v_mfma_f32_16x16x32_bf16 v[2:5], v[222:225], v[206:209], v[2:5]
	s_barrier
	s_add_i32 s49, 0, 0x18000
	s_add_u32 s14, s20, 0xb8000
	s_addc_u32 s15, s21, 0
	s_mov_b32 m0, s36
	ds_read_b128 v[168:171], v166 offset:33792
	ds_read_b128 v[190:193], v166 offset:35840
	ds_read_b128 v[198:201], v166 offset:37888
	ds_read_b128 v[206:209], v166 offset:39936
	global_load_lds_dwordx4 v130, s[14:15]
	s_mov_b32 m0, s37
	s_nop 0
	global_load_lds_dwordx4 v134, s[14:15]
	s_waitcnt lgkmcnt(8)
	s_barrier
	s_waitcnt lgkmcnt(0)
	s_waitcnt lgkmcnt(0)
	v_mfma_f32_16x16x32_bf16 v[126:129], v[142:145], v[158:161], v[126:129]
	v_mfma_f32_16x16x32_bf16 v[122:125], v[150:153], v[158:161], v[122:125]
	v_mfma_f32_16x16x32_bf16 v[110:113], v[142:145], v[172:175], v[110:113]
	v_mfma_f32_16x16x32_bf16 v[106:109], v[150:153], v[172:175], v[106:109]
	v_mfma_f32_16x16x32_bf16 v[94:97], v[142:145], v[194:197], v[94:97]
	v_mfma_f32_16x16x32_bf16 v[90:93], v[150:153], v[194:197], v[90:93]
	v_mfma_f32_16x16x32_bf16 v[78:81], v[142:145], v[202:205], v[78:81]
	v_mfma_f32_16x16x32_bf16 v[74:77], v[150:153], v[202:205], v[74:77]
	v_mfma_f32_16x16x32_bf16 v[126:129], v[146:149], v[168:171], v[126:129]
	v_mfma_f32_16x16x32_bf16 v[122:125], v[154:157], v[168:171], v[122:125]
	v_mfma_f32_16x16x32_bf16 v[110:113], v[146:149], v[190:193], v[110:113]
	v_mfma_f32_16x16x32_bf16 v[106:109], v[154:157], v[190:193], v[106:109]
	v_mfma_f32_16x16x32_bf16 v[94:97], v[146:149], v[198:201], v[94:97]
	v_mfma_f32_16x16x32_bf16 v[90:93], v[154:157], v[198:201], v[90:93]
	v_mfma_f32_16x16x32_bf16 v[78:81], v[146:149], v[206:209], v[78:81]
	v_mfma_f32_16x16x32_bf16 v[74:77], v[154:157], v[206:209], v[74:77]
	s_barrier
	s_add_i32 s20, 0, 0x1c000
	s_add_i32 s14, s49, s33
	v_add_u32_e32 v167, s20, v164
	s_mov_b32 m0, s14
	ds_read_b128 v[210:213], v167
	ds_read_b128 v[214:217], v167 offset:1024
	ds_read_b128 v[218:221], v167 offset:2048
	ds_read_b128 v[222:225], v167 offset:3072
	global_load_lds_dwordx4 v132, s[64:65]
	s_add_i32 m0, s14, 0x2000
	s_nop 0
	global_load_lds_dwordx4 v136, s[64:65]
	s_barrier
	s_waitcnt lgkmcnt(0)
	s_waitcnt lgkmcnt(0)
	v_mfma_f32_16x16x32_bf16 v[118:121], v[210:213], v[158:161], v[118:121]
	v_mfma_f32_16x16x32_bf16 v[114:117], v[218:221], v[158:161], v[114:117]
	v_mfma_f32_16x16x32_bf16 v[102:105], v[210:213], v[172:175], v[102:105]
	v_mfma_f32_16x16x32_bf16 v[98:101], v[218:221], v[172:175], v[98:101]
	v_mfma_f32_16x16x32_bf16 v[86:89], v[210:213], v[194:197], v[86:89]
	v_mfma_f32_16x16x32_bf16 v[82:85], v[218:221], v[194:197], v[82:85]
	v_mfma_f32_16x16x32_bf16 v[70:73], v[210:213], v[202:205], v[70:73]
	v_mfma_f32_16x16x32_bf16 v[66:69], v[218:221], v[202:205], v[66:69]
	ds_read_b128 v[158:161], v166 offset:49152
	v_mfma_f32_16x16x32_bf16 v[118:121], v[214:217], v[168:171], v[118:121]
	v_mfma_f32_16x16x32_bf16 v[114:117], v[222:225], v[168:171], v[114:117]
	ds_read_b128 v[172:175], v166 offset:51200
	v_mfma_f32_16x16x32_bf16 v[102:105], v[214:217], v[190:193], v[102:105]
	v_mfma_f32_16x16x32_bf16 v[98:101], v[222:225], v[190:193], v[98:101]
	ds_read_b128 v[194:197], v166 offset:53248
	v_mfma_f32_16x16x32_bf16 v[86:89], v[214:217], v[198:201], v[86:89]
	v_mfma_f32_16x16x32_bf16 v[82:85], v[222:225], v[198:201], v[82:85]
	ds_read_b128 v[202:205], v166 offset:55296
	v_mfma_f32_16x16x32_bf16 v[70:73], v[214:217], v[206:209], v[70:73]
	v_mfma_f32_16x16x32_bf16 v[66:69], v[222:225], v[206:209], v[66:69]
	s_barrier
	s_mov_b32 m0, s38
	ds_read_b128 v[168:171], v166 offset:50176
	ds_read_b128 v[190:193], v166 offset:52224
	ds_read_b128 v[198:201], v166 offset:54272
	ds_read_b128 v[206:209], v166 offset:56320
	global_load_lds_dwordx4 v130, s[62:63]
	s_mov_b32 m0, s39
	s_nop 0
	global_load_lds_dwordx4 v134, s[62:63]
	s_waitcnt vmcnt(8)
	s_barrier
	s_waitcnt lgkmcnt(0)
	s_waitcnt lgkmcnt(0)
	v_mfma_f32_16x16x32_bf16 v[62:65], v[142:145], v[158:161], v[62:65]
	v_mfma_f32_16x16x32_bf16 v[58:61], v[150:153], v[158:161], v[58:61]
	v_mfma_f32_16x16x32_bf16 v[46:49], v[142:145], v[172:175], v[46:49]
	v_mfma_f32_16x16x32_bf16 v[42:45], v[150:153], v[172:175], v[42:45]
	v_mfma_f32_16x16x32_bf16 v[30:33], v[142:145], v[194:197], v[30:33]
	v_mfma_f32_16x16x32_bf16 v[26:29], v[150:153], v[194:197], v[26:29]
	v_mfma_f32_16x16x32_bf16 v[14:17], v[142:145], v[202:205], v[14:17]
	v_mfma_f32_16x16x32_bf16 v[10:13], v[150:153], v[202:205], v[10:13]
	v_mfma_f32_16x16x32_bf16 v[62:65], v[146:149], v[168:171], v[62:65]
	v_mfma_f32_16x16x32_bf16 v[58:61], v[154:157], v[168:171], v[58:61]
	v_mfma_f32_16x16x32_bf16 v[46:49], v[146:149], v[190:193], v[46:49]
	v_mfma_f32_16x16x32_bf16 v[42:45], v[154:157], v[190:193], v[42:45]
	v_mfma_f32_16x16x32_bf16 v[30:33], v[146:149], v[198:201], v[30:33]
	v_mfma_f32_16x16x32_bf16 v[26:29], v[154:157], v[198:201], v[26:29]
	v_mfma_f32_16x16x32_bf16 v[14:17], v[146:149], v[206:209], v[14:17]
	v_mfma_f32_16x16x32_bf16 v[10:13], v[154:157], v[206:209], v[10:13]
	s_barrier
	v_add_u32_e32 v154, 0x10000, v164
	ds_read_b128 v[142:145], v154
	ds_read_b128 v[146:149], v154 offset:1024
	ds_read_b128 v[150:153], v154 offset:2048
	ds_read_b128 v[154:157], v154 offset:3072
	s_add_u32 s14, s18, 0xb0080
	s_addc_u32 s15, s19, 0
	s_add_i32 s18, s20, s33
	s_mov_b32 m0, s18
	s_nop 0
	global_load_lds_dwordx4 v132, s[14:15]
	s_add_i32 m0, s18, 0x2000
	s_nop 0
	global_load_lds_dwordx4 v136, s[14:15]
	s_waitcnt vmcnt(6)
	s_barrier
	v_mfma_f32_16x16x32_bf16 v[54:57], v[210:213], v[158:161], v[54:57]
	v_mfma_f32_16x16x32_bf16 v[50:53], v[218:221], v[158:161], v[50:53]
	v_mfma_f32_16x16x32_bf16 v[38:41], v[210:213], v[172:175], v[38:41]
	v_mfma_f32_16x16x32_bf16 v[34:37], v[218:221], v[172:175], v[34:37]
	v_mfma_f32_16x16x32_bf16 v[22:25], v[210:213], v[194:197], v[22:25]
	v_mfma_f32_16x16x32_bf16 v[18:21], v[218:221], v[194:197], v[18:21]
	v_mfma_f32_16x16x32_bf16 v[6:9], v[210:213], v[202:205], v[6:9]
	v_mfma_f32_16x16x32_bf16 v[2:5], v[218:221], v[202:205], v[2:5]
	ds_read_b128 v[158:161], v166
	v_mfma_f32_16x16x32_bf16 v[54:57], v[214:217], v[168:171], v[54:57]
	v_mfma_f32_16x16x32_bf16 v[50:53], v[222:225], v[168:171], v[50:53]
	ds_read_b128 v[172:175], v166 offset:2048
	v_mfma_f32_16x16x32_bf16 v[38:41], v[214:217], v[190:193], v[38:41]
	v_mfma_f32_16x16x32_bf16 v[34:37], v[222:225], v[190:193], v[34:37]
	ds_read_b128 v[194:197], v166 offset:4096
	v_mfma_f32_16x16x32_bf16 v[22:25], v[214:217], v[198:201], v[22:25]
	v_mfma_f32_16x16x32_bf16 v[18:21], v[222:225], v[198:201], v[18:21]
	ds_read_b128 v[202:205], v166 offset:6144
	v_mfma_f32_16x16x32_bf16 v[6:9], v[214:217], v[206:209], v[6:9]
	v_mfma_f32_16x16x32_bf16 v[2:5], v[222:225], v[206:209], v[2:5]
	s_barrier
	s_add_i32 s48, s48, 2
	s_add_u32 s46, s46, 0x100
	s_addc_u32 s47, s47, 0
	s_cmp_gt_u32 s48, 41
	s_mov_b64 s[14:15], s[16:17]
	s_cbranch_scc0 .LBB0_400
	s_waitcnt lgkmcnt(0)
	s_ashr_i32 s14, s44, 5
	v_lshl_or_b32 v176, s45, 8, v165
	s_mul_hi_i32 s15, s14, 0x9000
	s_mul_i32 s14, s14, 0x9000
	s_add_u32 s14, s26, s14
	v_ashrrev_i32_e32 v177, 31, v176
	s_addc_u32 s15, s27, s15
	v_lshlrev_b64 v[158:159], 2, v[176:177]
	v_lshl_add_u64 v[160:161], s[14:15], 0, v[158:159]
	global_load_dwordx4 v[142:145], v[160:161], off offset:16
	global_load_dwordx4 v[146:149], v[160:161], off
	v_lshl_add_u32 v162, s44, 8, v1
	v_ashrrev_i32_e32 v163, 31, v162
	v_lshl_add_u32 v131, v162, 12, v158
	global_load_dwordx4 v[188:191], v131, s[2:3] offset:16
	global_load_dwordx4 v[192:195], v131, s[2:3]
	global_load_dwordx4 v[196:199], v131, s[2:3] offset:528
	global_load_dwordx4 v[200:203], v131, s[2:3] offset:512
	v_add_u32_e32 v131, 0x10000, v131
	global_load_dwordx4 v[204:207], v131, s[2:3] offset:16
	global_load_dwordx4 v[208:211], v131, s[2:3]
	global_load_dwordx4 v[212:215], v131, s[2:3] offset:528
	global_load_dwordx4 v[216:219], v131, s[2:3] offset:512
	v_add_u32_e32 v131, 0x10000, v131
	global_load_dwordx4 v[220:223], v131, s[2:3] offset:16
	global_load_dwordx4 v[224:227], v131, s[2:3]
	global_load_dwordx4 v[228:231], v131, s[2:3] offset:528
	global_load_dwordx4 v[236:239], v131, s[2:3] offset:512
	v_add_u32_e32 v131, 0x10000, v131
	global_load_dwordx4 v[246:249], v131, s[2:3] offset:16
	global_load_dwordx4 v[250:253], v131, s[2:3]
	v_mov_b32_e32 v133, v131
	s_mov_b64 s[14:15], 0x80000
	s_and_b64 vcc, exec, s[4:5]
	s_mov_b32 s45, s42
	s_mov_b32 s44, s43
	s_mov_b64 s[16:17], s[8:9]
	s_waitcnt vmcnt(14)
	v_pk_add_f32 v[144:145], v[144:145], 1.0 op_sel_hi:[1,0]
	v_pk_add_f32 v[148:149], v[148:149], 1.0 op_sel_hi:[1,0]
	v_pk_add_f32 v[146:147], v[146:147], 1.0 op_sel_hi:[1,0]
	v_pk_add_f32 v[142:143], v[142:143], 1.0 op_sel_hi:[1,0]
	v_pk_mul_f32 v[150:151], v[148:149], 0.5 op_sel_hi:[1,0]
	v_pk_mul_f32 v[152:153], v[146:147], 0.5 op_sel_hi:[1,0]
	v_pk_mul_f32 v[154:155], v[144:145], 0.5 op_sel_hi:[1,0]
	v_pk_mul_f32 v[156:157], v[142:143], 0.5 op_sel_hi:[1,0]
	global_load_dwordx4 v[146:149], v[160:161], off offset:528
	global_load_dwordx4 v[142:145], v[160:161], off offset:512
	s_waitcnt vmcnt(0)
	v_pk_add_f32 v[148:149], v[148:149], 1.0 op_sel_hi:[1,0]
	v_pk_add_f32 v[144:145], v[144:145], 1.0 op_sel_hi:[1,0]
	v_pk_add_f32 v[160:161], v[142:143], 1.0 op_sel_hi:[1,0]
	v_pk_mul_f32 v[142:143], v[144:145], 0.5 op_sel_hi:[1,0]
	v_pk_mul_f32 v[144:145], v[160:161], 0.5 op_sel_hi:[1,0]
	v_pk_add_f32 v[160:161], v[146:147], 1.0 op_sel_hi:[1,0]
	v_pk_mul_f32 v[146:147], v[148:149], 0.5 op_sel_hi:[1,0]
	v_pk_mul_f32 v[148:149], v[160:161], 0.5 op_sel_hi:[1,0]
	v_lshlrev_b64 v[160:161], 12, v[162:163]
	v_lshl_add_u64 v[168:169], s[2:3], 0, v[160:161]
	v_lshl_add_u64 v[186:187], v[168:169], 0, v[158:159]
	v_mov_b32_e32 v168, v188
	v_mov_b32_e32 v169, v189
	v_mov_b32_e32 v170, v190
	v_mov_b32_e32 v171, v191
	v_mov_b32_e32 v172, v192
	v_mov_b32_e32 v173, v193
	v_mov_b32_e32 v174, v194
	v_mov_b32_e32 v175, v195
	global_load_dwordx4 v[188:191], v133, s[2:3] offset:528
	global_load_dwordx4 v[192:195], v133, s[2:3] offset:512
	v_pk_fma_f32 v[122:123], v[122:123], v[156:157], v[168:169]
	v_pk_fma_f32 v[128:129], v[128:129], v[150:151], v[174:175]
	v_pk_fma_f32 v[126:127], v[126:127], v[152:153], v[172:173]
	v_pk_fma_f32 v[170:171], v[124:125], v[154:155], v[170:171]
	v_cvt_pk_bf16_f32 v124, v126, v127
	v_cvt_pk_bf16_f32 v125, v128, v129
	v_cvt_pk_bf16_f32 v126, v122, v123
	v_lshl_add_u64 v[128:129], s[12:13], 0, v[160:161]
	v_lshlrev_b64 v[122:123], 1, v[176:177]
	v_cvt_pk_bf16_f32 v127, v170, v171
	v_lshl_add_u64 v[128:129], v[128:129], 0, v[122:123]
	global_store_dwordx4 v[128:129], v[124:127], off offset:2048
	s_nop 1
	v_mov_b32_e32 v124, v196
	v_mov_b32_e32 v125, v197
	v_mov_b32_e32 v126, v198
	v_mov_b32_e32 v127, v199
	s_nop 0
	v_mov_b32_e32 v168, v200
	v_mov_b32_e32 v169, v201
	v_mov_b32_e32 v170, v202
	v_mov_b32_e32 v171, v203
	v_add_u32_e32 v133, 0x50000, v133
	global_load_dwordx4 v[196:199], v133, s[2:3] offset:16
	global_load_dwordx4 v[200:203], v133, s[2:3]
	v_pk_fma_f32 v[126:127], v[116:117], v[146:147], v[126:127]
	v_pk_fma_f32 v[120:121], v[120:121], v[142:143], v[170:171]
	v_pk_fma_f32 v[118:119], v[118:119], v[144:145], v[168:169]
	v_pk_fma_f32 v[116:117], v[114:115], v[148:149], v[124:125]
	v_cvt_pk_bf16_f32 v114, v118, v119
	v_cvt_pk_bf16_f32 v115, v120, v121
	v_cvt_pk_bf16_f32 v116, v116, v117
	v_cvt_pk_bf16_f32 v117, v126, v127
	global_store_dwordx4 v[128:129], v[114:117], off offset:2304
	s_nop 1
	v_or_b32_e32 v114, 16, v162
	v_ashrrev_i32_e32 v115, 31, v114
	v_lshlrev_b64 v[124:125], 12, v[114:115]
	v_lshl_add_u64 v[114:115], s[2:3], 0, v[124:125]
	v_lshl_add_u64 v[126:127], v[114:115], 0, v[158:159]
	v_mov_b32_e32 v114, v204
	v_mov_b32_e32 v115, v205
	v_mov_b32_e32 v116, v206
	v_mov_b32_e32 v117, v207
	v_mov_b32_e32 v118, v208
	v_mov_b32_e32 v119, v209
	v_mov_b32_e32 v120, v210
	v_mov_b32_e32 v121, v211
	global_load_dwordx4 v[204:207], v133, s[2:3] offset:528
	global_load_dwordx4 v[208:211], v133, s[2:3] offset:512
	v_pk_fma_f32 v[116:117], v[108:109], v[154:155], v[116:117]
	v_pk_fma_f32 v[110:111], v[110:111], v[152:153], v[118:119]
	v_pk_fma_f32 v[112:113], v[112:113], v[150:151], v[120:121]
	v_pk_fma_f32 v[108:109], v[106:107], v[156:157], v[114:115]
	v_cvt_pk_bf16_f32 v106, v110, v111
	v_lshl_add_u64 v[110:111], s[12:13], 0, v[124:125]
	v_cvt_pk_bf16_f32 v107, v112, v113
	v_cvt_pk_bf16_f32 v108, v108, v109
	v_cvt_pk_bf16_f32 v109, v116, v117
	v_lshl_add_u64 v[114:115], v[110:111], 0, v[122:123]
	global_store_dwordx4 v[114:115], v[106:109], off offset:2048
	s_nop 1
	v_mov_b32_e32 v106, v212
	v_mov_b32_e32 v107, v213
	v_mov_b32_e32 v108, v214
	v_mov_b32_e32 v109, v215
	s_nop 0
	v_mov_b32_e32 v110, v216
	v_mov_b32_e32 v111, v217
	v_mov_b32_e32 v112, v218
	v_mov_b32_e32 v113, v219
	v_add_u32_e32 v133, 0x10000, v133
	global_load_dwordx4 v[212:215], v133, s[2:3] offset:16
	global_load_dwordx4 v[216:219], v133, s[2:3]
	v_pk_fma_f32 v[108:109], v[100:101], v[146:147], v[108:109]
	v_pk_fma_f32 v[104:105], v[104:105], v[142:143], v[112:113]
	v_pk_fma_f32 v[102:103], v[102:103], v[144:145], v[110:111]
	v_pk_fma_f32 v[100:101], v[98:99], v[148:149], v[106:107]
	v_cvt_pk_bf16_f32 v98, v102, v103
	v_cvt_pk_bf16_f32 v99, v104, v105
	v_cvt_pk_bf16_f32 v100, v100, v101
	v_cvt_pk_bf16_f32 v101, v108, v109
	global_store_dwordx4 v[114:115], v[98:101], off offset:2304
	s_nop 1
	v_or_b32_e32 v98, 32, v162
	v_ashrrev_i32_e32 v99, 31, v98
	v_lshlrev_b64 v[106:107], 12, v[98:99]
	v_lshl_add_u64 v[98:99], s[2:3], 0, v[106:107]
	v_lshl_add_u64 v[108:109], v[98:99], 0, v[158:159]
	v_mov_b32_e32 v98, v220
	v_mov_b32_e32 v99, v221
	v_mov_b32_e32 v100, v222
	v_mov_b32_e32 v101, v223
	v_mov_b32_e32 v102, v224
	v_mov_b32_e32 v103, v225
	v_mov_b32_e32 v104, v226
	v_mov_b32_e32 v105, v227
	global_load_dwordx4 v[220:223], v133, s[2:3] offset:528
	global_load_dwordx4 v[224:227], v133, s[2:3] offset:512
	v_pk_fma_f32 v[100:101], v[92:93], v[154:155], v[100:101]
	v_pk_fma_f32 v[94:95], v[94:95], v[152:153], v[102:103]
	v_pk_fma_f32 v[96:97], v[96:97], v[150:151], v[104:105]
	v_pk_fma_f32 v[92:93], v[90:91], v[156:157], v[98:99]
	v_cvt_pk_bf16_f32 v90, v94, v95
	v_lshl_add_u64 v[94:95], s[12:13], 0, v[106:107]
	v_cvt_pk_bf16_f32 v91, v96, v97
	v_cvt_pk_bf16_f32 v92, v92, v93
	v_cvt_pk_bf16_f32 v93, v100, v101
	v_lshl_add_u64 v[98:99], v[94:95], 0, v[122:123]
	global_store_dwordx4 v[98:99], v[90:93], off offset:2048
	s_nop 1
	v_mov_b32_e32 v90, v228
	v_mov_b32_e32 v91, v229
	v_mov_b32_e32 v92, v230
	v_mov_b32_e32 v93, v231
	s_nop 0
	v_mov_b32_e32 v94, v236
	v_mov_b32_e32 v95, v237
	v_mov_b32_e32 v96, v238
	v_mov_b32_e32 v97, v239
	v_add_u32_e32 v133, 0x10000, v133
	global_load_dwordx4 v[228:231], v133, s[2:3] offset:16
	global_load_dwordx4 v[236:239], v133, s[2:3]
	v_pk_fma_f32 v[92:93], v[84:85], v[146:147], v[92:93]
	v_pk_fma_f32 v[88:89], v[88:89], v[142:143], v[96:97]
	v_pk_fma_f32 v[86:87], v[86:87], v[144:145], v[94:95]
	v_pk_fma_f32 v[84:85], v[82:83], v[148:149], v[90:91]
	v_cvt_pk_bf16_f32 v82, v86, v87
	v_cvt_pk_bf16_f32 v83, v88, v89
	v_cvt_pk_bf16_f32 v84, v84, v85
	v_cvt_pk_bf16_f32 v85, v92, v93
	global_store_dwordx4 v[98:99], v[82:85], off offset:2304
	s_nop 1
	v_or_b32_e32 v82, 48, v162
	v_ashrrev_i32_e32 v83, 31, v82
	v_lshlrev_b64 v[90:91], 12, v[82:83]
	v_lshl_add_u64 v[82:83], s[2:3], 0, v[90:91]
	v_lshl_add_u64 v[92:93], v[82:83], 0, v[158:159]
	v_mov_b32_e32 v82, v246
	v_mov_b32_e32 v83, v247
	v_mov_b32_e32 v84, v248
	v_mov_b32_e32 v85, v249
	v_mov_b32_e32 v86, v250
	v_mov_b32_e32 v87, v251
	v_mov_b32_e32 v88, v252
	v_mov_b32_e32 v89, v253
	global_load_dwordx4 v[246:249], v133, s[2:3] offset:528
	global_load_dwordx4 v[250:253], v133, s[2:3] offset:512
	v_pk_fma_f32 v[84:85], v[76:77], v[154:155], v[84:85]
	v_pk_fma_f32 v[78:79], v[78:79], v[152:153], v[86:87]
	v_pk_fma_f32 v[80:81], v[80:81], v[150:151], v[88:89]
	v_pk_fma_f32 v[76:77], v[74:75], v[156:157], v[82:83]
	v_cvt_pk_bf16_f32 v74, v78, v79
	v_lshl_add_u64 v[78:79], s[12:13], 0, v[90:91]
	v_cvt_pk_bf16_f32 v75, v80, v81
	v_cvt_pk_bf16_f32 v76, v76, v77
	v_cvt_pk_bf16_f32 v77, v84, v85
	v_lshl_add_u64 v[82:83], v[78:79], 0, v[122:123]
	global_store_dwordx4 v[82:83], v[74:77], off offset:2048
	s_nop 1
	s_waitcnt vmcnt(19)
	v_mov_b32_e32 v74, v188
	v_mov_b32_e32 v75, v189
	v_mov_b32_e32 v76, v190
	v_mov_b32_e32 v77, v191
	s_nop 0
	v_mov_b32_e32 v78, v192
	v_mov_b32_e32 v79, v193
	v_mov_b32_e32 v80, v194
	v_mov_b32_e32 v81, v195
	v_add_u32_e32 v133, 0x10000, v133
	global_load_dwordx4 v[188:191], v133, s[2:3] offset:16
	global_load_dwordx4 v[192:195], v133, s[2:3]
	v_pk_fma_f32 v[76:77], v[68:69], v[146:147], v[76:77]
	v_pk_fma_f32 v[72:73], v[72:73], v[142:143], v[80:81]
	v_pk_fma_f32 v[70:71], v[70:71], v[144:145], v[78:79]
	v_pk_fma_f32 v[68:69], v[66:67], v[148:149], v[74:75]
	v_cvt_pk_bf16_f32 v66, v70, v71
	v_cvt_pk_bf16_f32 v67, v72, v73
	v_cvt_pk_bf16_f32 v68, v68, v69
	v_cvt_pk_bf16_f32 v69, v76, v77
	v_lshl_add_u64 v[74:75], v[160:161], 0, s[14:15]
	global_store_dwordx4 v[82:83], v[66:69], off offset:2304
	s_mov_b64 s[14:15], 0x90000
	s_nop 0
	v_lshl_add_u64 v[66:67], s[2:3], 0, v[74:75]
	v_lshl_add_u64 v[76:77], v[66:67], 0, v[158:159]
	s_waitcnt vmcnt(19)
	v_mov_b32_e32 v66, v196
	v_mov_b32_e32 v67, v197
	v_mov_b32_e32 v68, v198
	v_mov_b32_e32 v69, v199
	v_mov_b32_e32 v70, v200
	v_mov_b32_e32 v71, v201
	v_mov_b32_e32 v72, v202
	v_mov_b32_e32 v73, v203
	global_load_dwordx4 v[196:199], v133, s[2:3] offset:528
	global_load_dwordx4 v[200:203], v133, s[2:3] offset:512
	v_pk_fma_f32 v[68:69], v[60:61], v[154:155], v[68:69]
	v_pk_fma_f32 v[62:63], v[62:63], v[152:153], v[70:71]
	v_pk_fma_f32 v[64:65], v[64:65], v[150:151], v[72:73]
	v_pk_fma_f32 v[60:61], v[58:59], v[156:157], v[66:67]
	v_cvt_pk_bf16_f32 v58, v62, v63
	v_lshl_add_u64 v[62:63], s[12:13], 0, v[74:75]
	v_cvt_pk_bf16_f32 v59, v64, v65
	v_cvt_pk_bf16_f32 v60, v60, v61
	v_cvt_pk_bf16_f32 v61, v68, v69
	v_lshl_add_u64 v[66:67], v[62:63], 0, v[122:123]
	global_store_dwordx4 v[66:67], v[58:61], off offset:2048
	s_nop 1
	s_waitcnt vmcnt(19)
	v_mov_b32_e32 v58, v204
	v_mov_b32_e32 v59, v205
	v_mov_b32_e32 v60, v206
	v_mov_b32_e32 v61, v207
	s_nop 0
	v_mov_b32_e32 v62, v208
	v_mov_b32_e32 v63, v209
	v_mov_b32_e32 v64, v210
	v_mov_b32_e32 v65, v211
	s_nop 0
	v_pk_fma_f32 v[60:61], v[52:53], v[146:147], v[60:61]
	v_pk_fma_f32 v[56:57], v[56:57], v[142:143], v[64:65]
	v_pk_fma_f32 v[54:55], v[54:55], v[144:145], v[62:63]
	v_pk_fma_f32 v[52:53], v[50:51], v[148:149], v[58:59]
	v_cvt_pk_bf16_f32 v50, v54, v55
	v_cvt_pk_bf16_f32 v51, v56, v57
	v_cvt_pk_bf16_f32 v52, v52, v53
	v_cvt_pk_bf16_f32 v53, v60, v61
	v_lshl_add_u64 v[58:59], v[160:161], 0, s[14:15]
	global_store_dwordx4 v[66:67], v[50:53], off offset:2304
	s_mov_b64 s[14:15], 0xa0000
	s_nop 0
	v_lshl_add_u64 v[50:51], s[2:3], 0, v[58:59]
	v_lshl_add_u64 v[60:61], v[50:51], 0, v[158:159]
	s_waitcnt vmcnt(17)
	v_mov_b32_e32 v50, v212
	v_mov_b32_e32 v51, v213
	v_mov_b32_e32 v52, v214
	v_mov_b32_e32 v53, v215
	v_mov_b32_e32 v54, v216
	v_mov_b32_e32 v55, v217
	v_mov_b32_e32 v56, v218
	v_mov_b32_e32 v57, v219
	s_nop 0
	v_pk_fma_f32 v[52:53], v[44:45], v[154:155], v[52:53]
	v_pk_fma_f32 v[46:47], v[46:47], v[152:153], v[54:55]
	v_pk_fma_f32 v[48:49], v[48:49], v[150:151], v[56:57]
	v_pk_fma_f32 v[44:45], v[42:43], v[156:157], v[50:51]
	v_cvt_pk_bf16_f32 v42, v46, v47
	v_lshl_add_u64 v[46:47], s[12:13], 0, v[58:59]
	v_cvt_pk_bf16_f32 v43, v48, v49
	v_cvt_pk_bf16_f32 v44, v44, v45
	v_cvt_pk_bf16_f32 v45, v52, v53
	v_lshl_add_u64 v[50:51], v[46:47], 0, v[122:123]
	global_store_dwordx4 v[50:51], v[42:45], off offset:2048
	s_nop 1
	s_waitcnt vmcnt(15)
	v_mov_b32_e32 v42, v220
	v_mov_b32_e32 v43, v221
	v_mov_b32_e32 v44, v222
	v_mov_b32_e32 v45, v223
	s_nop 0
	v_mov_b32_e32 v46, v224
	v_mov_b32_e32 v47, v225
	v_mov_b32_e32 v48, v226
	v_mov_b32_e32 v49, v227
	s_nop 0
	v_pk_fma_f32 v[44:45], v[36:37], v[146:147], v[44:45]
	v_pk_fma_f32 v[40:41], v[40:41], v[142:143], v[48:49]
	v_pk_fma_f32 v[38:39], v[38:39], v[144:145], v[46:47]
	v_pk_fma_f32 v[36:37], v[34:35], v[148:149], v[42:43]
	v_cvt_pk_bf16_f32 v34, v38, v39
	v_cvt_pk_bf16_f32 v35, v40, v41
	v_cvt_pk_bf16_f32 v36, v36, v37
	v_cvt_pk_bf16_f32 v37, v44, v45
	v_lshl_add_u64 v[42:43], v[160:161], 0, s[14:15]
	global_store_dwordx4 v[50:51], v[34:37], off offset:2304
	s_mov_b64 s[14:15], 0xb0000
	s_nop 0
	v_lshl_add_u64 v[34:35], s[2:3], 0, v[42:43]
	v_lshl_add_u64 v[44:45], v[34:35], 0, v[158:159]
	s_waitcnt vmcnt(13)
	v_mov_b32_e32 v34, v228
	v_mov_b32_e32 v35, v229
	v_mov_b32_e32 v36, v230
	v_mov_b32_e32 v37, v231
	v_mov_b32_e32 v38, v236
	v_mov_b32_e32 v39, v237
	v_mov_b32_e32 v40, v238
	v_mov_b32_e32 v41, v239
	s_nop 0
	v_pk_fma_f32 v[36:37], v[28:29], v[154:155], v[36:37]
	v_pk_fma_f32 v[30:31], v[30:31], v[152:153], v[38:39]
	v_pk_fma_f32 v[32:33], v[32:33], v[150:151], v[40:41]
	v_pk_fma_f32 v[28:29], v[26:27], v[156:157], v[34:35]
	v_cvt_pk_bf16_f32 v26, v30, v31
	v_lshl_add_u64 v[30:31], s[12:13], 0, v[42:43]
	v_cvt_pk_bf16_f32 v27, v32, v33
	v_cvt_pk_bf16_f32 v28, v28, v29
	v_cvt_pk_bf16_f32 v29, v36, v37
	v_lshl_add_u64 v[34:35], v[30:31], 0, v[122:123]
	global_store_dwordx4 v[34:35], v[26:29], off offset:2048
	s_nop 1
	s_waitcnt vmcnt(11)
	v_mov_b32_e32 v26, v246
	v_mov_b32_e32 v27, v247
	v_mov_b32_e32 v28, v248
	v_mov_b32_e32 v29, v249
	s_nop 0
	v_mov_b32_e32 v30, v250
	v_mov_b32_e32 v31, v251
	v_mov_b32_e32 v32, v252
	v_mov_b32_e32 v33, v253
	s_nop 0
	v_pk_fma_f32 v[28:29], v[20:21], v[146:147], v[28:29]
	v_pk_fma_f32 v[24:25], v[24:25], v[142:143], v[32:33]
	v_pk_fma_f32 v[22:23], v[22:23], v[144:145], v[30:31]
	v_pk_fma_f32 v[20:21], v[18:19], v[148:149], v[26:27]
	v_cvt_pk_bf16_f32 v18, v22, v23
	v_cvt_pk_bf16_f32 v19, v24, v25
	v_cvt_pk_bf16_f32 v20, v20, v21
	v_cvt_pk_bf16_f32 v21, v28, v29
	v_lshl_add_u64 v[26:27], v[160:161], 0, s[14:15]
	global_store_dwordx4 v[34:35], v[18:21], off offset:2304
	s_mov_b64 s[14:15], s[6:7]
	s_nop 0
	v_lshl_add_u64 v[18:19], s[2:3], 0, v[26:27]
	v_lshl_add_u64 v[28:29], v[18:19], 0, v[158:159]
	s_waitcnt vmcnt(9)
	v_mov_b32_e32 v18, v188
	v_mov_b32_e32 v19, v189
	v_mov_b32_e32 v20, v190
	v_mov_b32_e32 v21, v191
	v_mov_b32_e32 v22, v192
	v_mov_b32_e32 v23, v193
	v_mov_b32_e32 v24, v194
	v_mov_b32_e32 v25, v195
	s_nop 0
	v_pk_fma_f32 v[20:21], v[12:13], v[154:155], v[20:21]
	v_pk_fma_f32 v[14:15], v[14:15], v[152:153], v[22:23]
	v_pk_fma_f32 v[16:17], v[16:17], v[150:151], v[24:25]
	v_pk_fma_f32 v[12:13], v[10:11], v[156:157], v[18:19]
	v_cvt_pk_bf16_f32 v10, v14, v15
	v_lshl_add_u64 v[14:15], s[12:13], 0, v[26:27]
	v_cvt_pk_bf16_f32 v11, v16, v17
	v_cvt_pk_bf16_f32 v12, v12, v13
	v_cvt_pk_bf16_f32 v13, v20, v21
	v_lshl_add_u64 v[18:19], v[14:15], 0, v[122:123]
	global_store_dwordx4 v[18:19], v[10:13], off offset:2048
	s_nop 1
	s_waitcnt vmcnt(7)
	v_mov_b32_e32 v10, v196
	v_mov_b32_e32 v11, v197
	v_mov_b32_e32 v12, v198
	v_mov_b32_e32 v13, v199
	s_nop 0
	v_mov_b32_e32 v14, v200
	v_mov_b32_e32 v15, v201
	v_mov_b32_e32 v16, v202
	v_mov_b32_e32 v17, v203
	s_nop 0
	v_pk_fma_f32 v[12:13], v[4:5], v[146:147], v[12:13]
	v_pk_fma_f32 v[8:9], v[8:9], v[142:143], v[16:17]
	v_pk_fma_f32 v[6:7], v[6:7], v[144:145], v[14:15]
	v_pk_fma_f32 v[4:5], v[2:3], v[148:149], v[10:11]
	v_cvt_pk_bf16_f32 v2, v6, v7
	v_cvt_pk_bf16_f32 v3, v8, v9
	v_cvt_pk_bf16_f32 v4, v4, v5
	v_cvt_pk_bf16_f32 v5, v12, v13
	global_store_dwordx4 v[18:19], v[2:5], off offset:2304
	s_cbranch_vccz .LBB0_389
	s_waitcnt vmcnt(0)
	s_cmpk_gt_u32 s30, 0xff
	s_cbranch_scc1 .LBB0_404
	s_barrier

.LBB0_527:
	v_mov_b64_e32 v[2:3], s[80:81]
	s_ashr_i32 s15, s14, 31
	v_cmp_lt_i64_e32 vcc, s[16:17], v[2:3]
	s_lshl_b64 s[16:17], s[14:15], 19
	s_add_u32 s16, s29, s16
	s_addc_u32 s17, s30, s17
	s_and_b64 s[18:19], vcc, exec
	s_cselect_b32 s11, s17, s21
	s_cselect_b32 s15, s16, s20
	s_ashr_i32 s13, s12, 31
	s_lshl_b64 s[18:19], s[12:13], 19
	s_add_u32 s18, s31, s18
	s_addc_u32 s19, s33, s19
	s_and_b64 s[24:25], vcc, exec
	s_cselect_b32 s13, s19, s23
	s_cselect_b32 s51, s18, s22
	s_add_u32 s20, s20, 0x40080
	s_addc_u32 s21, s21, 0
	s_add_u32 s52, s22, 0x100
	s_addc_u32 s53, s23, 0
	s_mov_b32 s54, -2
	s_add_u32 s22, s20, 0xfffc0080
	s_addc_u32 s23, s21, -1
	s_add_i32 s55, 0, 0x10000
	v_add_u32_e32 v144, s55, v146
	ds_read_b128 v[150:153], v144
	ds_read_b128 v[154:157], v144 offset:1024
	ds_read_b128 v[158:161], v144 offset:2048
	ds_read_b128 v[162:165], v144 offset:3072
	s_cmp_eq_u32 s54, 12
	s_cselect_b32 s25, s11, s23
	s_cselect_b32 s24, s15, s22
	s_cselect_b32 s23, s13, s53
	s_cselect_b32 s22, s51, s52
	s_add_i32 m0, s41, 0xc000
	ds_read_b128 v[166:169], v148
	ds_read_b128 v[170:173], v148 offset:1024
	ds_read_b128 v[174:177], v148 offset:2048
	ds_read_b128 v[190:193], v148 offset:3072
	ds_read_b128 v[194:197], v148 offset:4096
	ds_read_b128 v[198:201], v148 offset:5120
	ds_read_b128 v[202:205], v148 offset:6144
	ds_read_b128 v[206:209], v148 offset:7168
	global_load_lds_dwordx4 v140, s[20:21]
	v_lshl_add_u64 v[144:145], s[20:21], 0, v[142:143]
	s_add_i32 m0, s41, 0xe000
	s_nop 0
	global_load_lds_dwordx4 v[144:145], off
	s_waitcnt lgkmcnt(8)
	s_barrier
	s_waitcnt lgkmcnt(0)
	s_waitcnt lgkmcnt(0)
	v_mfma_f32_16x16x32_bf16 v[86:89], v[150:153], v[166:169], 0
	v_mfma_f32_16x16x32_bf16 v[82:85], v[158:161], v[166:169], 0
	v_mfma_f32_16x16x32_bf16 v[78:81], v[150:153], v[174:177], 0
	v_mfma_f32_16x16x32_bf16 v[74:77], v[158:161], v[174:177], 0
	v_mfma_f32_16x16x32_bf16 v[62:65], v[150:153], v[194:197], 0
	v_mfma_f32_16x16x32_bf16 v[58:61], v[158:161], v[194:197], 0
	v_mfma_f32_16x16x32_bf16 v[54:57], v[150:153], v[202:205], 0
	v_mfma_f32_16x16x32_bf16 v[50:53], v[158:161], v[202:205], 0
	v_mfma_f32_16x16x32_bf16 v[86:89], v[154:157], v[170:173], v[86:89]
	v_mfma_f32_16x16x32_bf16 v[82:85], v[162:165], v[170:173], v[82:85]
	v_mfma_f32_16x16x32_bf16 v[78:81], v[154:157], v[190:193], v[78:81]
	v_mfma_f32_16x16x32_bf16 v[74:77], v[162:165], v[190:193], v[74:77]
	v_mfma_f32_16x16x32_bf16 v[62:65], v[154:157], v[198:201], v[62:65]
	v_mfma_f32_16x16x32_bf16 v[58:61], v[162:165], v[198:201], v[58:61]
	v_mfma_f32_16x16x32_bf16 v[54:57], v[154:157], v[206:209], v[54:57]
	v_mfma_f32_16x16x32_bf16 v[50:53], v[162:165], v[206:209], v[50:53]
	s_barrier
	s_add_i32 s58, 0, 0x14000
	v_add_u32_e32 v144, s58, v146
	s_add_i32 s55, s55, s35
	ds_read_b128 v[210:213], v144
	ds_read_b128 v[214:217], v144 offset:1024
	ds_read_b128 v[218:221], v144 offset:2048
	ds_read_b128 v[222:225], v144 offset:3072
	s_add_u32 s64, s22, 0x80
	s_addc_u32 s65, s23, 0
	s_mov_b32 m0, s55
	s_nop 0
	global_load_lds_dwordx4 v134, s[22:23]
	s_add_i32 m0, s55, 0x2000
	s_nop 0
	global_load_lds_dwordx4 v130, s[22:23]
	s_barrier
	s_waitcnt lgkmcnt(0)
	s_waitcnt lgkmcnt(0)
	v_mfma_f32_16x16x32_bf16 v[126:129], v[210:213], v[166:169], 0
	v_mfma_f32_16x16x32_bf16 v[122:125], v[218:221], v[166:169], 0
	v_mfma_f32_16x16x32_bf16 v[118:121], v[210:213], v[174:177], 0
	v_mfma_f32_16x16x32_bf16 v[114:117], v[218:221], v[174:177], 0
	v_mfma_f32_16x16x32_bf16 v[110:113], v[210:213], v[194:197], 0
	v_mfma_f32_16x16x32_bf16 v[106:109], v[218:221], v[194:197], 0
	v_mfma_f32_16x16x32_bf16 v[102:105], v[210:213], v[202:205], 0
	v_mfma_f32_16x16x32_bf16 v[98:101], v[218:221], v[202:205], 0
	ds_read_b128 v[166:169], v148 offset:16384
	v_mfma_f32_16x16x32_bf16 v[126:129], v[214:217], v[170:173], v[126:129]
	v_mfma_f32_16x16x32_bf16 v[122:125], v[222:225], v[170:173], v[122:125]
	ds_read_b128 v[174:177], v148 offset:18432
	v_mfma_f32_16x16x32_bf16 v[118:121], v[214:217], v[190:193], v[118:121]
	v_mfma_f32_16x16x32_bf16 v[114:117], v[222:225], v[190:193], v[114:117]
	ds_read_b128 v[194:197], v148 offset:20480
	v_mfma_f32_16x16x32_bf16 v[110:113], v[214:217], v[198:201], v[110:113]
	v_mfma_f32_16x16x32_bf16 v[106:109], v[222:225], v[198:201], v[106:109]
	ds_read_b128 v[202:205], v148 offset:22528
	v_mfma_f32_16x16x32_bf16 v[102:105], v[214:217], v[206:209], v[102:105]
	v_mfma_f32_16x16x32_bf16 v[98:101], v[222:225], v[206:209], v[98:101]
	s_barrier
	s_mov_b32 m0, s41
	s_add_u32 s62, s24, 0x80
	s_addc_u32 s63, s25, 0
	ds_read_b128 v[170:173], v148 offset:17408
	ds_read_b128 v[190:193], v148 offset:19456
	ds_read_b128 v[198:201], v148 offset:21504
	ds_read_b128 v[206:209], v148 offset:23552
	global_load_lds_dwordx4 v136, s[24:25]
	s_mov_b32 m0, s42
	s_nop 0
	global_load_lds_dwordx4 v132, s[24:25]
	s_waitcnt vmcnt(8)
	s_barrier
	s_waitcnt lgkmcnt(0)
	s_waitcnt lgkmcnt(0)
	v_mfma_f32_16x16x32_bf16 v[34:37], v[150:153], v[166:169], 0
	v_mfma_f32_16x16x32_bf16 v[26:29], v[158:161], v[166:169], 0
	v_mfma_f32_16x16x32_bf16 v[22:25], v[150:153], v[174:177], 0
	v_mfma_f32_16x16x32_bf16 v[18:21], v[158:161], v[174:177], 0
	v_mfma_f32_16x16x32_bf16 v[14:17], v[150:153], v[194:197], 0
	v_mfma_f32_16x16x32_bf16 v[10:13], v[158:161], v[194:197], 0
	v_mfma_f32_16x16x32_bf16 v[6:9], v[150:153], v[202:205], 0
	v_mfma_f32_16x16x32_bf16 v[2:5], v[158:161], v[202:205], 0
	v_mfma_f32_16x16x32_bf16 v[34:37], v[154:157], v[170:173], v[34:37]
	v_mfma_f32_16x16x32_bf16 v[26:29], v[162:165], v[170:173], v[26:29]
	v_mfma_f32_16x16x32_bf16 v[22:25], v[154:157], v[190:193], v[22:25]
	v_mfma_f32_16x16x32_bf16 v[18:21], v[162:165], v[190:193], v[18:21]
	v_mfma_f32_16x16x32_bf16 v[14:17], v[154:157], v[198:201], v[14:17]
	v_mfma_f32_16x16x32_bf16 v[10:13], v[162:165], v[198:201], v[10:13]
	v_mfma_f32_16x16x32_bf16 v[6:9], v[154:157], v[206:209], v[6:9]
	v_mfma_f32_16x16x32_bf16 v[2:5], v[162:165], v[206:209], v[2:5]
	s_barrier
	v_add_u32_e32 v162, 0x18000, v146
	ds_read_b128 v[150:153], v162
	ds_read_b128 v[154:157], v162 offset:1024
	ds_read_b128 v[158:161], v162 offset:2048
	ds_read_b128 v[162:165], v162 offset:3072
	s_add_u32 s56, s22, 0x40000
	s_addc_u32 s57, s23, 0
	s_add_i32 s55, s58, s35
	s_mov_b32 m0, s55
	s_nop 0
	global_load_lds_dwordx4 v134, s[56:57]
	s_add_i32 m0, s55, 0x2000
	s_nop 0
	global_load_lds_dwordx4 v130, s[56:57]
	s_waitcnt vmcnt(6)
	s_barrier
	v_mfma_f32_16x16x32_bf16 v[94:97], v[210:213], v[166:169], 0
	v_mfma_f32_16x16x32_bf16 v[90:93], v[218:221], v[166:169], 0
	v_mfma_f32_16x16x32_bf16 v[70:73], v[210:213], v[174:177], 0
	v_mfma_f32_16x16x32_bf16 v[66:69], v[218:221], v[174:177], 0
	v_mfma_f32_16x16x32_bf16 v[46:49], v[210:213], v[194:197], 0
	v_mfma_f32_16x16x32_bf16 v[42:45], v[218:221], v[194:197], 0
	v_mfma_f32_16x16x32_bf16 v[38:41], v[210:213], v[202:205], 0
	v_mfma_f32_16x16x32_bf16 v[30:33], v[218:221], v[202:205], 0
	ds_read_b128 v[166:169], v148 offset:32768
	v_mfma_f32_16x16x32_bf16 v[94:97], v[214:217], v[170:173], v[94:97]
	v_mfma_f32_16x16x32_bf16 v[90:93], v[222:225], v[170:173], v[90:93]
	ds_read_b128 v[174:177], v148 offset:34816
	v_mfma_f32_16x16x32_bf16 v[70:73], v[214:217], v[190:193], v[70:73]
	v_mfma_f32_16x16x32_bf16 v[66:69], v[222:225], v[190:193], v[66:69]
	ds_read_b128 v[194:197], v148 offset:36864
	v_mfma_f32_16x16x32_bf16 v[46:49], v[214:217], v[198:201], v[46:49]
	v_mfma_f32_16x16x32_bf16 v[42:45], v[222:225], v[198:201], v[42:45]
	ds_read_b128 v[202:205], v148 offset:38912
	v_mfma_f32_16x16x32_bf16 v[38:41], v[214:217], v[206:209], v[38:41]
	v_mfma_f32_16x16x32_bf16 v[30:33], v[222:225], v[206:209], v[30:33]
	s_barrier
	s_add_i32 s55, 0, 0x18000
	v_add_u32_e32 v149, s55, v146
	s_add_u32 s24, s24, 0x40000
	s_addc_u32 s25, s25, 0
	s_mov_b32 m0, s43
	ds_read_b128 v[170:173], v148 offset:33792
	ds_read_b128 v[190:193], v148 offset:35840
	ds_read_b128 v[198:201], v148 offset:37888
	ds_read_b128 v[206:209], v148 offset:39936
	global_load_lds_dwordx4 v136, s[24:25]
	s_mov_b32 m0, s44
	s_nop 0
	global_load_lds_dwordx4 v132, s[24:25]
	s_waitcnt lgkmcnt(8)
	s_barrier
	s_waitcnt lgkmcnt(0)
	s_waitcnt lgkmcnt(0)
	v_mfma_f32_16x16x32_bf16 v[86:89], v[150:153], v[166:169], v[86:89]
	v_mfma_f32_16x16x32_bf16 v[82:85], v[158:161], v[166:169], v[82:85]
	v_mfma_f32_16x16x32_bf16 v[78:81], v[150:153], v[174:177], v[78:81]
	v_mfma_f32_16x16x32_bf16 v[74:77], v[158:161], v[174:177], v[74:77]
	v_mfma_f32_16x16x32_bf16 v[62:65], v[150:153], v[194:197], v[62:65]
	v_mfma_f32_16x16x32_bf16 v[58:61], v[158:161], v[194:197], v[58:61]
	v_mfma_f32_16x16x32_bf16 v[54:57], v[150:153], v[202:205], v[54:57]
	v_mfma_f32_16x16x32_bf16 v[50:53], v[158:161], v[202:205], v[50:53]
	v_mfma_f32_16x16x32_bf16 v[86:89], v[154:157], v[170:173], v[86:89]
	v_mfma_f32_16x16x32_bf16 v[82:85], v[162:165], v[170:173], v[82:85]
	v_mfma_f32_16x16x32_bf16 v[78:81], v[154:157], v[190:193], v[78:81]
	v_mfma_f32_16x16x32_bf16 v[74:77], v[162:165], v[190:193], v[74:77]
	v_mfma_f32_16x16x32_bf16 v[62:65], v[154:157], v[198:201], v[62:65]
	v_mfma_f32_16x16x32_bf16 v[58:61], v[162:165], v[198:201], v[58:61]
	v_mfma_f32_16x16x32_bf16 v[54:57], v[154:157], v[206:209], v[54:57]
	v_mfma_f32_16x16x32_bf16 v[50:53], v[162:165], v[206:209], v[50:53]
	s_barrier
	s_add_i32 s24, 0, 0x1c000
	s_add_i32 s25, s55, s35
	v_add_u32_e32 v149, s24, v146
	s_mov_b32 m0, s25
	ds_read_b128 v[210:213], v149
	ds_read_b128 v[214:217], v149 offset:1024
	ds_read_b128 v[218:221], v149 offset:2048
	ds_read_b128 v[222:225], v149 offset:3072
	global_load_lds_dwordx4 v134, s[64:65]
	s_add_i32 m0, s25, 0x2000
	s_nop 0
	global_load_lds_dwordx4 v130, s[64:65]
	s_barrier
	s_waitcnt lgkmcnt(0)
	s_waitcnt lgkmcnt(0)
	v_mfma_f32_16x16x32_bf16 v[126:129], v[210:213], v[166:169], v[126:129]
	v_mfma_f32_16x16x32_bf16 v[122:125], v[218:221], v[166:169], v[122:125]
	v_mfma_f32_16x16x32_bf16 v[118:121], v[210:213], v[174:177], v[118:121]
	v_mfma_f32_16x16x32_bf16 v[114:117], v[218:221], v[174:177], v[114:117]
	v_mfma_f32_16x16x32_bf16 v[110:113], v[210:213], v[194:197], v[110:113]
	v_mfma_f32_16x16x32_bf16 v[106:109], v[218:221], v[194:197], v[106:109]
	v_mfma_f32_16x16x32_bf16 v[102:105], v[210:213], v[202:205], v[102:105]
	v_mfma_f32_16x16x32_bf16 v[98:101], v[218:221], v[202:205], v[98:101]
	ds_read_b128 v[166:169], v148 offset:49152
	v_mfma_f32_16x16x32_bf16 v[126:129], v[214:217], v[170:173], v[126:129]
	v_mfma_f32_16x16x32_bf16 v[122:125], v[222:225], v[170:173], v[122:125]
	ds_read_b128 v[174:177], v148 offset:51200
	v_mfma_f32_16x16x32_bf16 v[118:121], v[214:217], v[190:193], v[118:121]
	v_mfma_f32_16x16x32_bf16 v[114:117], v[222:225], v[190:193], v[114:117]
	ds_read_b128 v[194:197], v148 offset:53248
	v_mfma_f32_16x16x32_bf16 v[110:113], v[214:217], v[198:201], v[110:113]
	v_mfma_f32_16x16x32_bf16 v[106:109], v[222:225], v[198:201], v[106:109]
	ds_read_b128 v[202:205], v148 offset:55296
	v_mfma_f32_16x16x32_bf16 v[102:105], v[214:217], v[206:209], v[102:105]
	v_mfma_f32_16x16x32_bf16 v[98:101], v[222:225], v[206:209], v[98:101]
	s_barrier
	s_mov_b32 m0, s46
	ds_read_b128 v[170:173], v148 offset:50176
	ds_read_b128 v[190:193], v148 offset:52224
	ds_read_b128 v[198:201], v148 offset:54272
	ds_read_b128 v[206:209], v148 offset:56320
	global_load_lds_dwordx4 v136, s[62:63]
	s_mov_b32 m0, s47
	s_nop 0
	global_load_lds_dwordx4 v132, s[62:63]
	s_waitcnt vmcnt(8)
	s_barrier
	s_waitcnt lgkmcnt(0)
	s_waitcnt lgkmcnt(0)
	v_mfma_f32_16x16x32_bf16 v[34:37], v[150:153], v[166:169], v[34:37]
	v_mfma_f32_16x16x32_bf16 v[26:29], v[158:161], v[166:169], v[26:29]
	v_mfma_f32_16x16x32_bf16 v[22:25], v[150:153], v[174:177], v[22:25]
	v_mfma_f32_16x16x32_bf16 v[18:21], v[158:161], v[174:177], v[18:21]
	v_mfma_f32_16x16x32_bf16 v[14:17], v[150:153], v[194:197], v[14:17]
	v_mfma_f32_16x16x32_bf16 v[10:13], v[158:161], v[194:197], v[10:13]
	v_mfma_f32_16x16x32_bf16 v[6:9], v[150:153], v[202:205], v[6:9]
	v_mfma_f32_16x16x32_bf16 v[2:5], v[158:161], v[202:205], v[2:5]
	v_mfma_f32_16x16x32_bf16 v[34:37], v[154:157], v[170:173], v[34:37]
	v_mfma_f32_16x16x32_bf16 v[26:29], v[162:165], v[170:173], v[26:29]
	v_mfma_f32_16x16x32_bf16 v[22:25], v[154:157], v[190:193], v[22:25]
	v_mfma_f32_16x16x32_bf16 v[18:21], v[162:165], v[190:193], v[18:21]
	v_mfma_f32_16x16x32_bf16 v[14:17], v[154:157], v[198:201], v[14:17]
	v_mfma_f32_16x16x32_bf16 v[10:13], v[162:165], v[198:201], v[10:13]
	v_mfma_f32_16x16x32_bf16 v[6:9], v[154:157], v[206:209], v[6:9]
	v_mfma_f32_16x16x32_bf16 v[2:5], v[162:165], v[206:209], v[2:5]
	s_barrier
	v_add_u32_e32 v162, 0x10000, v146
	ds_read_b128 v[150:153], v162
	ds_read_b128 v[154:157], v162 offset:1024
	ds_read_b128 v[158:161], v162 offset:2048
	ds_read_b128 v[162:165], v162 offset:3072
	s_add_u32 s22, s22, 0x40080
	s_addc_u32 s23, s23, 0
	s_add_i32 s24, s24, s35
	s_mov_b32 m0, s24
	s_nop 0
	global_load_lds_dwordx4 v134, s[22:23]
	v_lshl_add_u64 v[144:145], s[22:23], 0, v[130:131]
	s_add_i32 m0, s24, 0x2000
	s_nop 0
	global_load_lds_dwordx4 v[144:145], off
	s_waitcnt vmcnt(6)
	s_barrier
	v_mfma_f32_16x16x32_bf16 v[94:97], v[210:213], v[166:169], v[94:97]
	v_mfma_f32_16x16x32_bf16 v[90:93], v[218:221], v[166:169], v[90:93]
	v_mfma_f32_16x16x32_bf16 v[70:73], v[210:213], v[174:177], v[70:73]
	v_mfma_f32_16x16x32_bf16 v[66:69], v[218:221], v[174:177], v[66:69]
	v_mfma_f32_16x16x32_bf16 v[46:49], v[210:213], v[194:197], v[46:49]
	v_mfma_f32_16x16x32_bf16 v[42:45], v[218:221], v[194:197], v[42:45]
	v_mfma_f32_16x16x32_bf16 v[38:41], v[210:213], v[202:205], v[38:41]
	v_mfma_f32_16x16x32_bf16 v[30:33], v[218:221], v[202:205], v[30:33]
	ds_read_b128 v[166:169], v148
	v_mfma_f32_16x16x32_bf16 v[94:97], v[214:217], v[170:173], v[94:97]
	v_mfma_f32_16x16x32_bf16 v[90:93], v[222:225], v[170:173], v[90:93]
	ds_read_b128 v[174:177], v148 offset:2048
	v_mfma_f32_16x16x32_bf16 v[70:73], v[214:217], v[190:193], v[70:73]
	v_mfma_f32_16x16x32_bf16 v[66:69], v[222:225], v[190:193], v[66:69]
	ds_read_b128 v[194:197], v148 offset:4096
	v_mfma_f32_16x16x32_bf16 v[46:49], v[214:217], v[198:201], v[46:49]
	v_mfma_f32_16x16x32_bf16 v[42:45], v[222:225], v[198:201], v[42:45]
	ds_read_b128 v[202:205], v148 offset:6144
	v_mfma_f32_16x16x32_bf16 v[38:41], v[214:217], v[206:209], v[38:41]
	v_mfma_f32_16x16x32_bf16 v[30:33], v[222:225], v[206:209], v[30:33]
	s_barrier
	s_add_i32 s54, s54, 2
	s_add_u32 s20, s20, 0x100
	s_addc_u32 s21, s21, 0
	s_add_u32 s52, s52, 0x100
	s_addc_u32 s53, s53, 0
.LBB0_528:
	s_add_u32 s22, s20, 0xfffc0080
	s_addc_u32 s23, s21, -1
	s_add_i32 s55, 0, 0x10000
	v_add_u32_e32 v144, s55, v146
	s_cmp_eq_u32 s54, 12
	s_cselect_b32 s25, s11, s23
	s_cselect_b32 s24, s15, s22
	s_cselect_b32 s23, s13, s53
	s_cselect_b32 s22, s51, s52
	s_add_i32 m0, s41, 0xc000
	ds_read_b128 v[170:173], v148 offset:1024
	ds_read_b128 v[190:193], v148 offset:3072
	ds_read_b128 v[198:201], v148 offset:5120
	ds_read_b128 v[206:209], v148 offset:7168
	global_load_lds_dwordx4 v140, s[20:21]
	v_lshl_add_u64 v[144:145], s[20:21], 0, v[142:143]
	s_add_i32 m0, s41, 0xe000
	s_nop 0
	global_load_lds_dwordx4 v[144:145], off
	s_waitcnt lgkmcnt(8)
	s_barrier
	s_waitcnt lgkmcnt(0)
	s_waitcnt lgkmcnt(0)
	v_mfma_f32_16x16x32_bf16 v[86:89], v[150:153], v[166:169], v[86:89]
	v_mfma_f32_16x16x32_bf16 v[82:85], v[158:161], v[166:169], v[82:85]
	v_mfma_f32_16x16x32_bf16 v[78:81], v[150:153], v[174:177], v[78:81]
	v_mfma_f32_16x16x32_bf16 v[74:77], v[158:161], v[174:177], v[74:77]
	v_mfma_f32_16x16x32_bf16 v[62:65], v[150:153], v[194:197], v[62:65]
	v_mfma_f32_16x16x32_bf16 v[58:61], v[158:161], v[194:197], v[58:61]
	v_mfma_f32_16x16x32_bf16 v[54:57], v[150:153], v[202:205], v[54:57]
	v_mfma_f32_16x16x32_bf16 v[50:53], v[158:161], v[202:205], v[50:53]
	v_mfma_f32_16x16x32_bf16 v[86:89], v[154:157], v[170:173], v[86:89]
	v_mfma_f32_16x16x32_bf16 v[82:85], v[162:165], v[170:173], v[82:85]
	v_mfma_f32_16x16x32_bf16 v[78:81], v[154:157], v[190:193], v[78:81]
	v_mfma_f32_16x16x32_bf16 v[74:77], v[162:165], v[190:193], v[74:77]
	v_mfma_f32_16x16x32_bf16 v[62:65], v[154:157], v[198:201], v[62:65]
	v_mfma_f32_16x16x32_bf16 v[58:61], v[162:165], v[198:201], v[58:61]
	v_mfma_f32_16x16x32_bf16 v[54:57], v[154:157], v[206:209], v[54:57]
	v_mfma_f32_16x16x32_bf16 v[50:53], v[162:165], v[206:209], v[50:53]
	s_barrier
	s_add_i32 s58, 0, 0x14000
	v_add_u32_e32 v144, s58, v146
	s_add_i32 s55, s55, s35
	ds_read_b128 v[210:213], v144
	ds_read_b128 v[214:217], v144 offset:1024
	ds_read_b128 v[218:221], v144 offset:2048
	ds_read_b128 v[222:225], v144 offset:3072
	s_add_u32 s64, s22, 0x80
	s_addc_u32 s65, s23, 0
	s_mov_b32 m0, s55
	s_nop 0
	global_load_lds_dwordx4 v134, s[22:23]
	s_add_i32 m0, s55, 0x2000
	s_nop 0
	global_load_lds_dwordx4 v130, s[22:23]
	s_barrier
	s_waitcnt lgkmcnt(0)
	s_waitcnt lgkmcnt(0)
	v_mfma_f32_16x16x32_bf16 v[126:129], v[210:213], v[166:169], v[126:129]
	v_mfma_f32_16x16x32_bf16 v[122:125], v[218:221], v[166:169], v[122:125]
	v_mfma_f32_16x16x32_bf16 v[118:121], v[210:213], v[174:177], v[118:121]
	v_mfma_f32_16x16x32_bf16 v[114:117], v[218:221], v[174:177], v[114:117]
	v_mfma_f32_16x16x32_bf16 v[110:113], v[210:213], v[194:197], v[110:113]
	v_mfma_f32_16x16x32_bf16 v[106:109], v[218:221], v[194:197], v[106:109]
	v_mfma_f32_16x16x32_bf16 v[102:105], v[210:213], v[202:205], v[102:105]
	v_mfma_f32_16x16x32_bf16 v[98:101], v[218:221], v[202:205], v[98:101]
	ds_read_b128 v[166:169], v148 offset:16384
	v_mfma_f32_16x16x32_bf16 v[126:129], v[214:217], v[170:173], v[126:129]
	v_mfma_f32_16x16x32_bf16 v[122:125], v[222:225], v[170:173], v[122:125]
	ds_read_b128 v[174:177], v148 offset:18432
	v_mfma_f32_16x16x32_bf16 v[118:121], v[214:217], v[190:193], v[118:121]
	v_mfma_f32_16x16x32_bf16 v[114:117], v[222:225], v[190:193], v[114:117]
	ds_read_b128 v[194:197], v148 offset:20480
	v_mfma_f32_16x16x32_bf16 v[110:113], v[214:217], v[198:201], v[110:113]
	v_mfma_f32_16x16x32_bf16 v[106:109], v[222:225], v[198:201], v[106:109]
	ds_read_b128 v[202:205], v148 offset:22528
	v_mfma_f32_16x16x32_bf16 v[102:105], v[214:217], v[206:209], v[102:105]
	v_mfma_f32_16x16x32_bf16 v[98:101], v[222:225], v[206:209], v[98:101]
	s_barrier
	s_mov_b32 m0, s41
	s_add_u32 s62, s24, 0x80
	s_addc_u32 s63, s25, 0
	ds_read_b128 v[170:173], v148 offset:17408
	ds_read_b128 v[190:193], v148 offset:19456
	ds_read_b128 v[198:201], v148 offset:21504
	ds_read_b128 v[206:209], v148 offset:23552
	global_load_lds_dwordx4 v136, s[24:25]
	s_mov_b32 m0, s42
	s_nop 0
	global_load_lds_dwordx4 v132, s[24:25]
	s_waitcnt vmcnt(8)
	s_barrier
	s_waitcnt lgkmcnt(0)
	s_waitcnt lgkmcnt(0)
	v_mfma_f32_16x16x32_bf16 v[34:37], v[150:153], v[166:169], v[34:37]
	v_mfma_f32_16x16x32_bf16 v[26:29], v[158:161], v[166:169], v[26:29]
	v_mfma_f32_16x16x32_bf16 v[22:25], v[150:153], v[174:177], v[22:25]
	v_mfma_f32_16x16x32_bf16 v[18:21], v[158:161], v[174:177], v[18:21]
	v_mfma_f32_16x16x32_bf16 v[14:17], v[150:153], v[194:197], v[14:17]
	v_mfma_f32_16x16x32_bf16 v[10:13], v[158:161], v[194:197], v[10:13]
	v_mfma_f32_16x16x32_bf16 v[6:9], v[150:153], v[202:205], v[6:9]
	v_mfma_f32_16x16x32_bf16 v[2:5], v[158:161], v[202:205], v[2:5]
	v_mfma_f32_16x16x32_bf16 v[34:37], v[154:157], v[170:173], v[34:37]
	v_mfma_f32_16x16x32_bf16 v[26:29], v[162:165], v[170:173], v[26:29]
	v_mfma_f32_16x16x32_bf16 v[22:25], v[154:157], v[190:193], v[22:25]
	v_mfma_f32_16x16x32_bf16 v[18:21], v[162:165], v[190:193], v[18:21]
	v_mfma_f32_16x16x32_bf16 v[14:17], v[154:157], v[198:201], v[14:17]
	v_mfma_f32_16x16x32_bf16 v[10:13], v[162:165], v[198:201], v[10:13]
	v_mfma_f32_16x16x32_bf16 v[6:9], v[154:157], v[206:209], v[6:9]
	v_mfma_f32_16x16x32_bf16 v[2:5], v[162:165], v[206:209], v[2:5]
	s_barrier
	v_add_u32_e32 v162, 0x18000, v146
	ds_read_b128 v[150:153], v162
	ds_read_b128 v[154:157], v162 offset:1024
	ds_read_b128 v[158:161], v162 offset:2048
	ds_read_b128 v[162:165], v162 offset:3072
	s_add_u32 s56, s22, 0x40000
	s_addc_u32 s57, s23, 0
	s_add_i32 s55, s58, s35
	s_mov_b32 m0, s55
	s_nop 0
	global_load_lds_dwordx4 v134, s[56:57]
	s_add_i32 m0, s55, 0x2000
	s_nop 0
	global_load_lds_dwordx4 v130, s[56:57]
	s_waitcnt vmcnt(6)
	s_barrier
	v_mfma_f32_16x16x32_bf16 v[94:97], v[210:213], v[166:169], v[94:97]
	v_mfma_f32_16x16x32_bf16 v[90:93], v[218:221], v[166:169], v[90:93]
	v_mfma_f32_16x16x32_bf16 v[70:73], v[210:213], v[174:177], v[70:73]
	v_mfma_f32_16x16x32_bf16 v[66:69], v[218:221], v[174:177], v[66:69]
	v_mfma_f32_16x16x32_bf16 v[46:49], v[210:213], v[194:197], v[46:49]
	v_mfma_f32_16x16x32_bf16 v[42:45], v[218:221], v[194:197], v[42:45]
	v_mfma_f32_16x16x32_bf16 v[38:41], v[210:213], v[202:205], v[38:41]
	v_mfma_f32_16x16x32_bf16 v[30:33], v[218:221], v[202:205], v[30:33]
	ds_read_b128 v[166:169], v148 offset:32768
	v_mfma_f32_16x16x32_bf16 v[94:97], v[214:217], v[170:173], v[94:97]
	v_mfma_f32_16x16x32_bf16 v[90:93], v[222:225], v[170:173], v[90:93]
	ds_read_b128 v[174:177], v148 offset:34816
	v_mfma_f32_16x16x32_bf16 v[70:73], v[214:217], v[190:193], v[70:73]
	v_mfma_f32_16x16x32_bf16 v[66:69], v[222:225], v[190:193], v[66:69]
	ds_read_b128 v[194:197], v148 offset:36864
	v_mfma_f32_16x16x32_bf16 v[46:49], v[214:217], v[198:201], v[46:49]
	v_mfma_f32_16x16x32_bf16 v[42:45], v[222:225], v[198:201], v[42:45]
	ds_read_b128 v[202:205], v148 offset:38912
	v_mfma_f32_16x16x32_bf16 v[38:41], v[214:217], v[206:209], v[38:41]
	v_mfma_f32_16x16x32_bf16 v[30:33], v[222:225], v[206:209], v[30:33]
	s_barrier
	s_add_i32 s55, 0, 0x18000
	v_add_u32_e32 v149, s55, v146
	s_add_u32 s24, s24, 0x40000
	s_addc_u32 s25, s25, 0
	s_mov_b32 m0, s43
	ds_read_b128 v[170:173], v148 offset:33792
	ds_read_b128 v[190:193], v148 offset:35840
	ds_read_b128 v[198:201], v148 offset:37888
	ds_read_b128 v[206:209], v148 offset:39936
	global_load_lds_dwordx4 v136, s[24:25]
	s_mov_b32 m0, s44
	s_nop 0
	global_load_lds_dwordx4 v132, s[24:25]
	s_waitcnt lgkmcnt(8)
	s_barrier
	s_waitcnt lgkmcnt(0)
	s_waitcnt lgkmcnt(0)
	v_mfma_f32_16x16x32_bf16 v[86:89], v[150:153], v[166:169], v[86:89]
	v_mfma_f32_16x16x32_bf16 v[82:85], v[158:161], v[166:169], v[82:85]
	v_mfma_f32_16x16x32_bf16 v[78:81], v[150:153], v[174:177], v[78:81]
	v_mfma_f32_16x16x32_bf16 v[74:77], v[158:161], v[174:177], v[74:77]
	v_mfma_f32_16x16x32_bf16 v[62:65], v[150:153], v[194:197], v[62:65]
	v_mfma_f32_16x16x32_bf16 v[58:61], v[158:161], v[194:197], v[58:61]
	v_mfma_f32_16x16x32_bf16 v[54:57], v[150:153], v[202:205], v[54:57]
	v_mfma_f32_16x16x32_bf16 v[50:53], v[158:161], v[202:205], v[50:53]
	v_mfma_f32_16x16x32_bf16 v[86:89], v[154:157], v[170:173], v[86:89]
	v_mfma_f32_16x16x32_bf16 v[82:85], v[162:165], v[170:173], v[82:85]
	v_mfma_f32_16x16x32_bf16 v[78:81], v[154:157], v[190:193], v[78:81]
	v_mfma_f32_16x16x32_bf16 v[74:77], v[162:165], v[190:193], v[74:77]
	v_mfma_f32_16x16x32_bf16 v[62:65], v[154:157], v[198:201], v[62:65]
	v_mfma_f32_16x16x32_bf16 v[58:61], v[162:165], v[198:201], v[58:61]
	v_mfma_f32_16x16x32_bf16 v[54:57], v[154:157], v[206:209], v[54:57]
	v_mfma_f32_16x16x32_bf16 v[50:53], v[162:165], v[206:209], v[50:53]
	s_barrier
	s_add_i32 s24, 0, 0x1c000
	s_add_i32 s25, s55, s35
	v_add_u32_e32 v149, s24, v146
	s_mov_b32 m0, s25
	ds_read_b128 v[210:213], v149
	ds_read_b128 v[214:217], v149 offset:1024
	ds_read_b128 v[218:221], v149 offset:2048
	ds_read_b128 v[222:225], v149 offset:3072
	global_load_lds_dwordx4 v134, s[64:65]
	s_add_i32 m0, s25, 0x2000
	s_nop 0
	global_load_lds_dwordx4 v130, s[64:65]
	s_barrier
	s_waitcnt lgkmcnt(0)
	s_waitcnt lgkmcnt(0)
	v_mfma_f32_16x16x32_bf16 v[126:129], v[210:213], v[166:169], v[126:129]
	v_mfma_f32_16x16x32_bf16 v[122:125], v[218:221], v[166:169], v[122:125]
	v_mfma_f32_16x16x32_bf16 v[118:121], v[210:213], v[174:177], v[118:121]
	v_mfma_f32_16x16x32_bf16 v[114:117], v[218:221], v[174:177], v[114:117]
	v_mfma_f32_16x16x32_bf16 v[110:113], v[210:213], v[194:197], v[110:113]
	v_mfma_f32_16x16x32_bf16 v[106:109], v[218:221], v[194:197], v[106:109]
	v_mfma_f32_16x16x32_bf16 v[102:105], v[210:213], v[202:205], v[102:105]
	v_mfma_f32_16x16x32_bf16 v[98:101], v[218:221], v[202:205], v[98:101]
	ds_read_b128 v[166:169], v148 offset:49152
	v_mfma_f32_16x16x32_bf16 v[126:129], v[214:217], v[170:173], v[126:129]
	v_mfma_f32_16x16x32_bf16 v[122:125], v[222:225], v[170:173], v[122:125]
	ds_read_b128 v[174:177], v148 offset:51200
	v_mfma_f32_16x16x32_bf16 v[118:121], v[214:217], v[190:193], v[118:121]
	v_mfma_f32_16x16x32_bf16 v[114:117], v[222:225], v[190:193], v[114:117]
	ds_read_b128 v[194:197], v148 offset:53248
	v_mfma_f32_16x16x32_bf16 v[110:113], v[214:217], v[198:201], v[110:113]
	v_mfma_f32_16x16x32_bf16 v[106:109], v[222:225], v[198:201], v[106:109]
	ds_read_b128 v[202:205], v148 offset:55296
	v_mfma_f32_16x16x32_bf16 v[102:105], v[214:217], v[206:209], v[102:105]
	v_mfma_f32_16x16x32_bf16 v[98:101], v[222:225], v[206:209], v[98:101]
	s_barrier
	s_mov_b32 m0, s46
	ds_read_b128 v[170:173], v148 offset:50176
	ds_read_b128 v[190:193], v148 offset:52224
	ds_read_b128 v[198:201], v148 offset:54272
	ds_read_b128 v[206:209], v148 offset:56320
	global_load_lds_dwordx4 v136, s[62:63]
	s_mov_b32 m0, s47
	s_nop 0
	global_load_lds_dwordx4 v132, s[62:63]
	s_waitcnt vmcnt(8)
	s_barrier
	s_waitcnt lgkmcnt(0)
	s_waitcnt lgkmcnt(0)
	v_mfma_f32_16x16x32_bf16 v[34:37], v[150:153], v[166:169], v[34:37]
	v_mfma_f32_16x16x32_bf16 v[26:29], v[158:161], v[166:169], v[26:29]
	v_mfma_f32_16x16x32_bf16 v[22:25], v[150:153], v[174:177], v[22:25]
	v_mfma_f32_16x16x32_bf16 v[18:21], v[158:161], v[174:177], v[18:21]
	v_mfma_f32_16x16x32_bf16 v[14:17], v[150:153], v[194:197], v[14:17]
	v_mfma_f32_16x16x32_bf16 v[10:13], v[158:161], v[194:197], v[10:13]
	v_mfma_f32_16x16x32_bf16 v[6:9], v[150:153], v[202:205], v[6:9]
	v_mfma_f32_16x16x32_bf16 v[2:5], v[158:161], v[202:205], v[2:5]
	v_mfma_f32_16x16x32_bf16 v[34:37], v[154:157], v[170:173], v[34:37]
	v_mfma_f32_16x16x32_bf16 v[26:29], v[162:165], v[170:173], v[26:29]
	v_mfma_f32_16x16x32_bf16 v[22:25], v[154:157], v[190:193], v[22:25]
	v_mfma_f32_16x16x32_bf16 v[18:21], v[162:165], v[190:193], v[18:21]
	v_mfma_f32_16x16x32_bf16 v[14:17], v[154:157], v[198:201], v[14:17]
	v_mfma_f32_16x16x32_bf16 v[10:13], v[162:165], v[198:201], v[10:13]
	v_mfma_f32_16x16x32_bf16 v[6:9], v[154:157], v[206:209], v[6:9]
	v_mfma_f32_16x16x32_bf16 v[2:5], v[162:165], v[206:209], v[2:5]
	s_barrier
	v_add_u32_e32 v162, 0x10000, v146
	ds_read_b128 v[150:153], v162
	ds_read_b128 v[154:157], v162 offset:1024
	ds_read_b128 v[158:161], v162 offset:2048
	ds_read_b128 v[162:165], v162 offset:3072
	s_add_u32 s22, s22, 0x40080
	s_addc_u32 s23, s23, 0
	s_add_i32 s24, s24, s35
	s_mov_b32 m0, s24
	s_nop 0
	global_load_lds_dwordx4 v134, s[22:23]
	v_lshl_add_u64 v[144:145], s[22:23], 0, v[130:131]
	s_add_i32 m0, s24, 0x2000
	s_nop 0
	global_load_lds_dwordx4 v[144:145], off
	s_waitcnt vmcnt(6)
	s_barrier
	v_mfma_f32_16x16x32_bf16 v[94:97], v[210:213], v[166:169], v[94:97]
	v_mfma_f32_16x16x32_bf16 v[90:93], v[218:221], v[166:169], v[90:93]
	v_mfma_f32_16x16x32_bf16 v[70:73], v[210:213], v[174:177], v[70:73]
	v_mfma_f32_16x16x32_bf16 v[66:69], v[218:221], v[174:177], v[66:69]
	v_mfma_f32_16x16x32_bf16 v[46:49], v[210:213], v[194:197], v[46:49]
	v_mfma_f32_16x16x32_bf16 v[42:45], v[218:221], v[194:197], v[42:45]
	v_mfma_f32_16x16x32_bf16 v[38:41], v[210:213], v[202:205], v[38:41]
	v_mfma_f32_16x16x32_bf16 v[30:33], v[218:221], v[202:205], v[30:33]
	ds_read_b128 v[166:169], v148
	v_mfma_f32_16x16x32_bf16 v[94:97], v[214:217], v[170:173], v[94:97]
	v_mfma_f32_16x16x32_bf16 v[90:93], v[222:225], v[170:173], v[90:93]
	ds_read_b128 v[174:177], v148 offset:2048
	v_mfma_f32_16x16x32_bf16 v[70:73], v[214:217], v[190:193], v[70:73]
	v_mfma_f32_16x16x32_bf16 v[66:69], v[222:225], v[190:193], v[66:69]
	ds_read_b128 v[194:197], v148 offset:4096
	v_mfma_f32_16x16x32_bf16 v[46:49], v[214:217], v[198:201], v[46:49]
	v_mfma_f32_16x16x32_bf16 v[42:45], v[222:225], v[198:201], v[42:45]
	ds_read_b128 v[202:205], v148 offset:6144
	v_mfma_f32_16x16x32_bf16 v[38:41], v[214:217], v[206:209], v[38:41]
	v_mfma_f32_16x16x32_bf16 v[30:33], v[222:225], v[206:209], v[30:33]
	s_barrier
	s_add_i32 s54, s54, 2
	s_add_u32 s20, s20, 0x100
	s_addc_u32 s21, s21, 0
	s_add_u32 s52, s52, 0x100
	s_addc_u32 s53, s53, 0
	s_cmp_gt_u32 s54, 13
	s_cbranch_scc0 .LBB0_528
	s_waitcnt lgkmcnt(0)
	v_lshl_add_u32 v144, s10, 8, v1
	s_cmp_lg_u32 s50, s45
	s_mov_b64 s[10:11], -1
	s_cbranch_scc0 .LBB0_531
	v_lshl_or_b32 v154, s50, 8, v147
	v_readlane_b32 s13, v255, 32
	v_ashrrev_i32_e32 v155, 31, v154
	v_lshlrev_b64 v[154:155], 1, v[154:155]
	v_mad_i64_i32 v[156:157], s[10:11], v144, s13, 0
	v_lshl_add_u64 v[156:157], v[156:157], 1, s[6:7]
	v_lshl_add_u64 v[156:157], v[156:157], 0, v[154:155]
	v_cvt_pk_bf16_f32 v126, v126, v127
	v_cvt_pk_bf16_f32 v127, v128, v129
	v_cvt_pk_bf16_f32 v128, v122, v123
	v_cvt_pk_bf16_f32 v129, v124, v125
	global_store_dwordx4 v[156:157], v[126:129], off offset:256
	v_cvt_pk_bf16_f32 v150, v86, v87
	v_cvt_pk_bf16_f32 v151, v88, v89
	v_or_b32_e32 v126, 16, v144
	v_mad_i64_i32 v[126:127], s[10:11], v126, s13, 0
	v_lshl_add_u64 v[126:127], v[126:127], 1, s[6:7]
	v_cvt_pk_bf16_f32 v152, v82, v83
	v_cvt_pk_bf16_f32 v153, v84, v85
	v_lshl_add_u64 v[126:127], v[126:127], 0, v[154:155]
	v_cvt_pk_bf16_f32 v118, v118, v119
	v_cvt_pk_bf16_f32 v119, v120, v121
	v_cvt_pk_bf16_f32 v120, v114, v115
	v_cvt_pk_bf16_f32 v121, v116, v117
	global_store_dwordx4 v[156:157], v[150:153], off
	global_store_dwordx4 v[126:127], v[118:121], off offset:256
	v_cvt_pk_bf16_f32 v122, v78, v79
	v_cvt_pk_bf16_f32 v123, v80, v81
	v_or_b32_e32 v118, 32, v144
	v_mad_i64_i32 v[118:119], s[10:11], v118, s13, 0
	v_lshl_add_u64 v[118:119], v[118:119], 1, s[6:7]
	v_cvt_pk_bf16_f32 v124, v74, v75
	v_cvt_pk_bf16_f32 v125, v76, v77
	v_lshl_add_u64 v[118:119], v[118:119], 0, v[154:155]
	v_cvt_pk_bf16_f32 v110, v110, v111
	v_cvt_pk_bf16_f32 v111, v112, v113
	v_cvt_pk_bf16_f32 v112, v106, v107
	v_cvt_pk_bf16_f32 v113, v108, v109
	global_store_dwordx4 v[126:127], v[122:125], off
	global_store_dwordx4 v[118:119], v[110:113], off offset:256
	v_cvt_pk_bf16_f32 v114, v62, v63
	v_cvt_pk_bf16_f32 v115, v64, v65
	v_or_b32_e32 v110, 48, v144
	v_mad_i64_i32 v[110:111], s[10:11], v110, s13, 0
	v_lshl_add_u64 v[110:111], v[110:111], 1, s[6:7]
	v_cvt_pk_bf16_f32 v116, v58, v59
	v_cvt_pk_bf16_f32 v117, v60, v61
	v_lshl_add_u64 v[110:111], v[110:111], 0, v[154:155]
	v_cvt_pk_bf16_f32 v102, v102, v103
	v_cvt_pk_bf16_f32 v103, v104, v105
	v_cvt_pk_bf16_f32 v104, v98, v99
	v_cvt_pk_bf16_f32 v105, v100, v101
	global_store_dwordx4 v[118:119], v[114:117], off
	global_store_dwordx4 v[110:111], v[102:105], off offset:256
	v_cvt_pk_bf16_f32 v106, v54, v55
	v_cvt_pk_bf16_f32 v107, v56, v57
	v_add_u32_e32 v102, 0x80, v144
	v_mad_i64_i32 v[102:103], s[10:11], v102, s13, 0
	v_lshl_add_u64 v[102:103], v[102:103], 1, s[6:7]
	v_cvt_pk_bf16_f32 v108, v50, v51
	v_cvt_pk_bf16_f32 v109, v52, v53
	v_lshl_add_u64 v[102:103], v[102:103], 0, v[154:155]
	v_cvt_pk_bf16_f32 v94, v94, v95
	v_cvt_pk_bf16_f32 v95, v96, v97
	v_cvt_pk_bf16_f32 v96, v90, v91
	v_cvt_pk_bf16_f32 v97, v92, v93
	global_store_dwordx4 v[110:111], v[106:109], off
	global_store_dwordx4 v[102:103], v[94:97], off offset:256
	v_cvt_pk_bf16_f32 v98, v34, v35
	v_cvt_pk_bf16_f32 v99, v36, v37
	v_add_u32_e32 v94, 0x90, v144
	v_mad_i64_i32 v[94:95], s[10:11], v94, s13, 0
	v_lshl_add_u64 v[94:95], v[94:95], 1, s[6:7]
	v_cvt_pk_bf16_f32 v100, v26, v27
	v_cvt_pk_bf16_f32 v101, v28, v29
	v_lshl_add_u64 v[94:95], v[94:95], 0, v[154:155]
	v_cvt_pk_bf16_f32 v70, v70, v71
	v_cvt_pk_bf16_f32 v71, v72, v73
	v_cvt_pk_bf16_f32 v72, v66, v67
	v_cvt_pk_bf16_f32 v73, v68, v69
	global_store_dwordx4 v[102:103], v[98:101], off
	global_store_dwordx4 v[94:95], v[70:73], off offset:256
	v_cvt_pk_bf16_f32 v90, v22, v23
	v_cvt_pk_bf16_f32 v91, v24, v25
	v_add_u32_e32 v70, 0xa0, v144
	v_mad_i64_i32 v[70:71], s[10:11], v70, s13, 0
	v_lshl_add_u64 v[70:71], v[70:71], 1, s[6:7]
	v_cvt_pk_bf16_f32 v92, v18, v19
	v_cvt_pk_bf16_f32 v93, v20, v21
	v_lshl_add_u64 v[70:71], v[70:71], 0, v[154:155]
	v_cvt_pk_bf16_f32 v46, v46, v47
	v_cvt_pk_bf16_f32 v47, v48, v49
	v_cvt_pk_bf16_f32 v48, v42, v43
	v_cvt_pk_bf16_f32 v49, v44, v45
	global_store_dwordx4 v[94:95], v[90:93], off
	global_store_dwordx4 v[70:71], v[46:49], off offset:256
	v_cvt_pk_bf16_f32 v66, v14, v15
	v_cvt_pk_bf16_f32 v67, v16, v17
	v_add_u32_e32 v46, 0xb0, v144
	v_mad_i64_i32 v[46:47], s[10:11], v46, s13, 0
	v_lshl_add_u64 v[46:47], v[46:47], 1, s[6:7]
	v_cvt_pk_bf16_f32 v68, v10, v11
	v_cvt_pk_bf16_f32 v69, v12, v13
	v_cvt_pk_bf16_f32 v42, v6, v7
	v_cvt_pk_bf16_f32 v43, v8, v9
	v_cvt_pk_bf16_f32 v44, v2, v3
	v_cvt_pk_bf16_f32 v45, v4, v5
	v_lshl_add_u64 v[46:47], v[46:47], 0, v[154:155]
	v_cvt_pk_bf16_f32 v38, v38, v39
	v_cvt_pk_bf16_f32 v39, v40, v41
	v_cvt_pk_bf16_f32 v40, v30, v31
	v_cvt_pk_bf16_f32 v41, v32, v33
	global_store_dwordx4 v[70:71], v[66:69], off
	global_store_dwordx4 v[46:47], v[42:45], off
	global_store_dwordx4 v[46:47], v[38:41], off offset:256
	s_mov_b64 s[10:11], 0

.LBB0_1407:
	s_ashr_i32 s3, s2, 31
	s_lshl_b64 s[12:13], s[2:3], 20
	s_add_u32 s12, s24, s12
	s_addc_u32 s13, s25, s13
	s_and_b64 s[6:7], s[6:7], exec
	s_cselect_b32 s3, s13, s17
	s_cselect_b32 s44, s12, s16
	s_add_u32 s45, s16, 0x100
	s_addc_u32 s46, s17, 0
	s_add_u32 s6, s14, 0x80
	s_addc_u32 s7, s15, 0
	v_lshl_add_u64 v[142:143], s[6:7], 0, v[138:139]
	v_lshl_add_u64 v[144:145], s[6:7], 0, v[140:141]
	s_mov_b32 s47, -2
	s_mov_b64 s[6:7], 0
	s_add_u32 s16, s14, s6
	s_addc_u32 s17, s15, s7
	s_add_u32 s16, s16, 0x100
	s_addc_u32 s17, s17, 0
	s_add_u32 s48, s45, s6
	s_addc_u32 s49, s46, s7
	s_add_i32 s50, 0, 0x10000
	v_add_u32_e32 v158, s50, v164
	ds_read_b128 v[146:149], v158
	ds_read_b128 v[150:153], v158 offset:1024
	ds_read_b128 v[154:157], v158 offset:2048
	ds_read_b128 v[158:161], v158 offset:3072
	s_cmpk_eq_i32 s6, 0xf00
	s_cselect_b32 s19, s11, s17
	s_cselect_b32 s18, s10, s16
	s_cselect_b32 s17, s3, s49
	s_cselect_b32 s16, s44, s48
	v_lshl_add_u64 v[162:163], v[142:143], 0, s[6:7]
	s_add_i32 m0, s30, 0xc000
	ds_read_b128 v[168:171], v166
	ds_read_b128 v[172:175], v166 offset:1024
	ds_read_b128 v[186:189], v166 offset:2048
	ds_read_b128 v[190:193], v166 offset:3072
	ds_read_b128 v[194:197], v166 offset:4096
	ds_read_b128 v[198:201], v166 offset:5120
	ds_read_b128 v[202:205], v166 offset:6144
	ds_read_b128 v[206:209], v166 offset:7168
	global_load_lds_dwordx4 v[162:163], off
	v_lshl_add_u64 v[162:163], v[144:145], 0, s[6:7]
	s_add_i32 m0, s30, 0xe000
	s_nop 0
	global_load_lds_dwordx4 v[162:163], off
	s_waitcnt lgkmcnt(8)
	s_barrier
	s_waitcnt lgkmcnt(0)
	s_waitcnt lgkmcnt(0)
	v_mfma_f32_16x16x32_bf16 v[126:129], v[146:149], v[168:171], 0
	v_mfma_f32_16x16x32_bf16 v[122:125], v[154:157], v[168:171], 0
	v_mfma_f32_16x16x32_bf16 v[110:113], v[146:149], v[186:189], 0
	v_mfma_f32_16x16x32_bf16 v[106:109], v[154:157], v[186:189], 0
	v_mfma_f32_16x16x32_bf16 v[94:97], v[146:149], v[194:197], 0
	v_mfma_f32_16x16x32_bf16 v[90:93], v[154:157], v[194:197], 0
	v_mfma_f32_16x16x32_bf16 v[78:81], v[146:149], v[202:205], 0
	v_mfma_f32_16x16x32_bf16 v[74:77], v[154:157], v[202:205], 0
	v_mfma_f32_16x16x32_bf16 v[126:129], v[150:153], v[172:175], v[126:129]
	v_mfma_f32_16x16x32_bf16 v[122:125], v[158:161], v[172:175], v[122:125]
	v_mfma_f32_16x16x32_bf16 v[110:113], v[150:153], v[190:193], v[110:113]
	v_mfma_f32_16x16x32_bf16 v[106:109], v[158:161], v[190:193], v[106:109]
	v_mfma_f32_16x16x32_bf16 v[94:97], v[150:153], v[198:201], v[94:97]
	v_mfma_f32_16x16x32_bf16 v[90:93], v[158:161], v[198:201], v[90:93]
	v_mfma_f32_16x16x32_bf16 v[78:81], v[150:153], v[206:209], v[78:81]
	v_mfma_f32_16x16x32_bf16 v[74:77], v[158:161], v[206:209], v[74:77]
	s_barrier
	s_add_i32 s51, 0, 0x14000
	v_add_u32_e32 v162, s51, v164
	s_add_i32 s48, s50, s29
	ds_read_b128 v[210:213], v162
	ds_read_b128 v[214:217], v162 offset:1024
	ds_read_b128 v[218:221], v162 offset:2048
	ds_read_b128 v[222:225], v162 offset:3072
	s_add_u32 s64, s16, 0x80
	s_addc_u32 s65, s17, 0
	s_mov_b32 m0, s48
	s_nop 0
	global_load_lds_dwordx4 v132, s[16:17]
	s_add_i32 m0, s48, 0x2000
	s_nop 0
	global_load_lds_dwordx4 v136, s[16:17]
	s_barrier
	s_waitcnt lgkmcnt(0)
	s_waitcnt lgkmcnt(0)
	v_mfma_f32_16x16x32_bf16 v[118:121], v[210:213], v[168:171], 0
	v_mfma_f32_16x16x32_bf16 v[114:117], v[218:221], v[168:171], 0
	v_mfma_f32_16x16x32_bf16 v[102:105], v[210:213], v[186:189], 0
	v_mfma_f32_16x16x32_bf16 v[98:101], v[218:221], v[186:189], 0
	v_mfma_f32_16x16x32_bf16 v[86:89], v[210:213], v[194:197], 0
	v_mfma_f32_16x16x32_bf16 v[82:85], v[218:221], v[194:197], 0
	v_mfma_f32_16x16x32_bf16 v[70:73], v[210:213], v[202:205], 0
	v_mfma_f32_16x16x32_bf16 v[66:69], v[218:221], v[202:205], 0
	ds_read_b128 v[168:171], v166 offset:16384
	v_mfma_f32_16x16x32_bf16 v[118:121], v[214:217], v[172:175], v[118:121]
	v_mfma_f32_16x16x32_bf16 v[114:117], v[222:225], v[172:175], v[114:117]
	ds_read_b128 v[186:189], v166 offset:18432
	v_mfma_f32_16x16x32_bf16 v[102:105], v[214:217], v[190:193], v[102:105]
	v_mfma_f32_16x16x32_bf16 v[98:101], v[222:225], v[190:193], v[98:101]
	ds_read_b128 v[194:197], v166 offset:20480
	v_mfma_f32_16x16x32_bf16 v[86:89], v[214:217], v[198:201], v[86:89]
	v_mfma_f32_16x16x32_bf16 v[82:85], v[222:225], v[198:201], v[82:85]
	ds_read_b128 v[202:205], v166 offset:22528
	v_mfma_f32_16x16x32_bf16 v[70:73], v[214:217], v[206:209], v[70:73]
	v_mfma_f32_16x16x32_bf16 v[66:69], v[222:225], v[206:209], v[66:69]
	s_barrier
	s_mov_b32 m0, s30
	s_add_u32 s62, s18, 0x80
	s_addc_u32 s63, s19, 0
	ds_read_b128 v[172:175], v166 offset:17408
	ds_read_b128 v[190:193], v166 offset:19456
	ds_read_b128 v[198:201], v166 offset:21504
	ds_read_b128 v[206:209], v166 offset:23552
	global_load_lds_dwordx4 v130, s[18:19]
	s_mov_b32 m0, s31
	s_nop 0
	global_load_lds_dwordx4 v134, s[18:19]
	s_waitcnt vmcnt(8)
	s_barrier
	s_waitcnt lgkmcnt(0)
	s_waitcnt lgkmcnt(0)
	v_mfma_f32_16x16x32_bf16 v[62:65], v[146:149], v[168:171], 0
	v_mfma_f32_16x16x32_bf16 v[58:61], v[154:157], v[168:171], 0
	v_mfma_f32_16x16x32_bf16 v[46:49], v[146:149], v[186:189], 0
	v_mfma_f32_16x16x32_bf16 v[42:45], v[154:157], v[186:189], 0
	v_mfma_f32_16x16x32_bf16 v[30:33], v[146:149], v[194:197], 0
	v_mfma_f32_16x16x32_bf16 v[26:29], v[154:157], v[194:197], 0
	v_mfma_f32_16x16x32_bf16 v[14:17], v[146:149], v[202:205], 0
	v_mfma_f32_16x16x32_bf16 v[10:13], v[154:157], v[202:205], 0
	v_mfma_f32_16x16x32_bf16 v[62:65], v[150:153], v[172:175], v[62:65]
	v_mfma_f32_16x16x32_bf16 v[58:61], v[158:161], v[172:175], v[58:61]
	v_mfma_f32_16x16x32_bf16 v[46:49], v[150:153], v[190:193], v[46:49]
	v_mfma_f32_16x16x32_bf16 v[42:45], v[158:161], v[190:193], v[42:45]
	v_mfma_f32_16x16x32_bf16 v[30:33], v[150:153], v[198:201], v[30:33]
	v_mfma_f32_16x16x32_bf16 v[26:29], v[158:161], v[198:201], v[26:29]
	v_mfma_f32_16x16x32_bf16 v[14:17], v[150:153], v[206:209], v[14:17]
	v_mfma_f32_16x16x32_bf16 v[10:13], v[158:161], v[206:209], v[10:13]
	s_barrier
	v_add_u32_e32 v158, 0x18000, v164
	ds_read_b128 v[146:149], v158
	ds_read_b128 v[150:153], v158 offset:1024
	ds_read_b128 v[154:157], v158 offset:2048
	ds_read_b128 v[158:161], v158 offset:3072
	s_add_u32 s48, s16, 0x80000
	s_addc_u32 s49, s17, 0
	s_add_i32 s50, s51, s29
	s_mov_b32 m0, s50
	s_nop 0
	global_load_lds_dwordx4 v132, s[48:49]
	s_add_i32 m0, s50, 0x2000
	s_nop 0
	global_load_lds_dwordx4 v136, s[48:49]
	s_waitcnt vmcnt(6)
	s_barrier
	v_mfma_f32_16x16x32_bf16 v[54:57], v[210:213], v[168:171], 0
	v_mfma_f32_16x16x32_bf16 v[50:53], v[218:221], v[168:171], 0
	v_mfma_f32_16x16x32_bf16 v[38:41], v[210:213], v[186:189], 0
	v_mfma_f32_16x16x32_bf16 v[34:37], v[218:221], v[186:189], 0
	v_mfma_f32_16x16x32_bf16 v[22:25], v[210:213], v[194:197], 0
	v_mfma_f32_16x16x32_bf16 v[18:21], v[218:221], v[194:197], 0
	v_mfma_f32_16x16x32_bf16 v[6:9], v[210:213], v[202:205], 0
	v_mfma_f32_16x16x32_bf16 v[2:5], v[218:221], v[202:205], 0
	ds_read_b128 v[168:171], v166 offset:32768
	v_mfma_f32_16x16x32_bf16 v[54:57], v[214:217], v[172:175], v[54:57]
	v_mfma_f32_16x16x32_bf16 v[50:53], v[222:225], v[172:175], v[50:53]
	ds_read_b128 v[186:189], v166 offset:34816
	v_mfma_f32_16x16x32_bf16 v[38:41], v[214:217], v[190:193], v[38:41]
	v_mfma_f32_16x16x32_bf16 v[34:37], v[222:225], v[190:193], v[34:37]
	ds_read_b128 v[194:197], v166 offset:36864
	v_mfma_f32_16x16x32_bf16 v[22:25], v[214:217], v[198:201], v[22:25]
	v_mfma_f32_16x16x32_bf16 v[18:21], v[222:225], v[198:201], v[18:21]
	ds_read_b128 v[202:205], v166 offset:38912
	v_mfma_f32_16x16x32_bf16 v[6:9], v[214:217], v[206:209], v[6:9]
	v_mfma_f32_16x16x32_bf16 v[2:5], v[222:225], v[206:209], v[2:5]
	s_barrier
	s_add_i32 s48, 0, 0x18000
	s_add_u32 s18, s18, s80
	s_addc_u32 s19, s19, 0
	s_mov_b32 m0, s34
	ds_read_b128 v[172:175], v166 offset:33792
	ds_read_b128 v[190:193], v166 offset:35840
	ds_read_b128 v[198:201], v166 offset:37888
	ds_read_b128 v[206:209], v166 offset:39936
	global_load_lds_dwordx4 v130, s[18:19]
	s_mov_b32 m0, s35
	s_nop 0
	global_load_lds_dwordx4 v134, s[18:19]
	s_waitcnt lgkmcnt(8)
	s_barrier
	s_waitcnt lgkmcnt(0)
	s_waitcnt lgkmcnt(0)
	v_mfma_f32_16x16x32_bf16 v[126:129], v[146:149], v[168:171], v[126:129]
	v_mfma_f32_16x16x32_bf16 v[122:125], v[154:157], v[168:171], v[122:125]
	v_mfma_f32_16x16x32_bf16 v[110:113], v[146:149], v[186:189], v[110:113]
	v_mfma_f32_16x16x32_bf16 v[106:109], v[154:157], v[186:189], v[106:109]
	v_mfma_f32_16x16x32_bf16 v[94:97], v[146:149], v[194:197], v[94:97]
	v_mfma_f32_16x16x32_bf16 v[90:93], v[154:157], v[194:197], v[90:93]
	v_mfma_f32_16x16x32_bf16 v[78:81], v[146:149], v[202:205], v[78:81]
	v_mfma_f32_16x16x32_bf16 v[74:77], v[154:157], v[202:205], v[74:77]
	v_mfma_f32_16x16x32_bf16 v[126:129], v[150:153], v[172:175], v[126:129]
	v_mfma_f32_16x16x32_bf16 v[122:125], v[158:161], v[172:175], v[122:125]
	v_mfma_f32_16x16x32_bf16 v[110:113], v[150:153], v[190:193], v[110:113]
	v_mfma_f32_16x16x32_bf16 v[106:109], v[158:161], v[190:193], v[106:109]
	v_mfma_f32_16x16x32_bf16 v[94:97], v[150:153], v[198:201], v[94:97]
	v_mfma_f32_16x16x32_bf16 v[90:93], v[158:161], v[198:201], v[90:93]
	v_mfma_f32_16x16x32_bf16 v[78:81], v[150:153], v[206:209], v[78:81]
	v_mfma_f32_16x16x32_bf16 v[74:77], v[158:161], v[206:209], v[74:77]
	s_barrier
	s_add_i32 s18, 0, 0x1c000
	s_add_i32 s19, s48, s29
	v_add_u32_e32 v167, s18, v164
	s_mov_b32 m0, s19
	ds_read_b128 v[210:213], v167
	ds_read_b128 v[214:217], v167 offset:1024
	ds_read_b128 v[218:221], v167 offset:2048
	ds_read_b128 v[222:225], v167 offset:3072
	global_load_lds_dwordx4 v132, s[64:65]
	s_add_i32 m0, s19, 0x2000
	s_nop 0
	global_load_lds_dwordx4 v136, s[64:65]
	s_barrier
	s_waitcnt lgkmcnt(0)
	s_waitcnt lgkmcnt(0)
	v_mfma_f32_16x16x32_bf16 v[118:121], v[210:213], v[168:171], v[118:121]
	v_mfma_f32_16x16x32_bf16 v[114:117], v[218:221], v[168:171], v[114:117]
	v_mfma_f32_16x16x32_bf16 v[102:105], v[210:213], v[186:189], v[102:105]
	v_mfma_f32_16x16x32_bf16 v[98:101], v[218:221], v[186:189], v[98:101]
	v_mfma_f32_16x16x32_bf16 v[86:89], v[210:213], v[194:197], v[86:89]
	v_mfma_f32_16x16x32_bf16 v[82:85], v[218:221], v[194:197], v[82:85]
	v_mfma_f32_16x16x32_bf16 v[70:73], v[210:213], v[202:205], v[70:73]
	v_mfma_f32_16x16x32_bf16 v[66:69], v[218:221], v[202:205], v[66:69]
	ds_read_b128 v[168:171], v166 offset:49152
	v_mfma_f32_16x16x32_bf16 v[118:121], v[214:217], v[172:175], v[118:121]
	v_mfma_f32_16x16x32_bf16 v[114:117], v[222:225], v[172:175], v[114:117]
	ds_read_b128 v[186:189], v166 offset:51200
	v_mfma_f32_16x16x32_bf16 v[102:105], v[214:217], v[190:193], v[102:105]
	v_mfma_f32_16x16x32_bf16 v[98:101], v[222:225], v[190:193], v[98:101]
	ds_read_b128 v[194:197], v166 offset:53248
	v_mfma_f32_16x16x32_bf16 v[86:89], v[214:217], v[198:201], v[86:89]
	v_mfma_f32_16x16x32_bf16 v[82:85], v[222:225], v[198:201], v[82:85]
	ds_read_b128 v[202:205], v166 offset:55296
	v_mfma_f32_16x16x32_bf16 v[70:73], v[214:217], v[206:209], v[70:73]
	v_mfma_f32_16x16x32_bf16 v[66:69], v[222:225], v[206:209], v[66:69]
	s_barrier
	s_mov_b32 m0, s38
	ds_read_b128 v[172:175], v166 offset:50176
	ds_read_b128 v[190:193], v166 offset:52224
	ds_read_b128 v[198:201], v166 offset:54272
	ds_read_b128 v[206:209], v166 offset:56320
	global_load_lds_dwordx4 v130, s[62:63]
	s_mov_b32 m0, s39
	s_nop 0
	global_load_lds_dwordx4 v134, s[62:63]
	s_waitcnt vmcnt(8)
	s_barrier
	s_waitcnt lgkmcnt(0)
	s_waitcnt lgkmcnt(0)
	v_mfma_f32_16x16x32_bf16 v[62:65], v[146:149], v[168:171], v[62:65]
	v_mfma_f32_16x16x32_bf16 v[58:61], v[154:157], v[168:171], v[58:61]
	v_mfma_f32_16x16x32_bf16 v[46:49], v[146:149], v[186:189], v[46:49]
	v_mfma_f32_16x16x32_bf16 v[42:45], v[154:157], v[186:189], v[42:45]
	v_mfma_f32_16x16x32_bf16 v[30:33], v[146:149], v[194:197], v[30:33]
	v_mfma_f32_16x16x32_bf16 v[26:29], v[154:157], v[194:197], v[26:29]
	v_mfma_f32_16x16x32_bf16 v[14:17], v[146:149], v[202:205], v[14:17]
	v_mfma_f32_16x16x32_bf16 v[10:13], v[154:157], v[202:205], v[10:13]
	v_mfma_f32_16x16x32_bf16 v[62:65], v[150:153], v[172:175], v[62:65]
	v_mfma_f32_16x16x32_bf16 v[58:61], v[158:161], v[172:175], v[58:61]
	v_mfma_f32_16x16x32_bf16 v[46:49], v[150:153], v[190:193], v[46:49]
	v_mfma_f32_16x16x32_bf16 v[42:45], v[158:161], v[190:193], v[42:45]
	v_mfma_f32_16x16x32_bf16 v[30:33], v[150:153], v[198:201], v[30:33]
	v_mfma_f32_16x16x32_bf16 v[26:29], v[158:161], v[198:201], v[26:29]
	v_mfma_f32_16x16x32_bf16 v[14:17], v[150:153], v[206:209], v[14:17]
	v_mfma_f32_16x16x32_bf16 v[10:13], v[158:161], v[206:209], v[10:13]
	s_barrier
	v_add_u32_e32 v158, 0x10000, v164
	ds_read_b128 v[146:149], v158
	ds_read_b128 v[150:153], v158 offset:1024
	ds_read_b128 v[154:157], v158 offset:2048
	ds_read_b128 v[158:161], v158 offset:3072
	s_add_u32 s16, s16, 0x80080
	s_addc_u32 s17, s17, 0
	s_add_i32 s18, s18, s29
	s_mov_b32 m0, s18
	s_nop 0
	global_load_lds_dwordx4 v132, s[16:17]
	s_add_i32 m0, s18, 0x2000
	s_nop 0
	global_load_lds_dwordx4 v136, s[16:17]
	s_waitcnt vmcnt(6)
	s_barrier
	v_mfma_f32_16x16x32_bf16 v[54:57], v[210:213], v[168:171], v[54:57]
	v_mfma_f32_16x16x32_bf16 v[50:53], v[218:221], v[168:171], v[50:53]
	v_mfma_f32_16x16x32_bf16 v[38:41], v[210:213], v[186:189], v[38:41]
	v_mfma_f32_16x16x32_bf16 v[34:37], v[218:221], v[186:189], v[34:37]
	v_mfma_f32_16x16x32_bf16 v[22:25], v[210:213], v[194:197], v[22:25]
	v_mfma_f32_16x16x32_bf16 v[18:21], v[218:221], v[194:197], v[18:21]
	v_mfma_f32_16x16x32_bf16 v[6:9], v[210:213], v[202:205], v[6:9]
	v_mfma_f32_16x16x32_bf16 v[2:5], v[218:221], v[202:205], v[2:5]
	ds_read_b128 v[168:171], v166
	v_mfma_f32_16x16x32_bf16 v[54:57], v[214:217], v[172:175], v[54:57]
	v_mfma_f32_16x16x32_bf16 v[50:53], v[222:225], v[172:175], v[50:53]
	ds_read_b128 v[186:189], v166 offset:2048
	v_mfma_f32_16x16x32_bf16 v[38:41], v[214:217], v[190:193], v[38:41]
	v_mfma_f32_16x16x32_bf16 v[34:37], v[222:225], v[190:193], v[34:37]
	ds_read_b128 v[194:197], v166 offset:4096
	v_mfma_f32_16x16x32_bf16 v[22:25], v[214:217], v[198:201], v[22:25]
	v_mfma_f32_16x16x32_bf16 v[18:21], v[222:225], v[198:201], v[18:21]
	ds_read_b128 v[202:205], v166 offset:6144
	v_mfma_f32_16x16x32_bf16 v[6:9], v[214:217], v[206:209], v[6:9]
	v_mfma_f32_16x16x32_bf16 v[2:5], v[222:225], v[206:209], v[2:5]
	s_barrier
	s_add_i32 s47, s47, 2
	s_add_u32 s6, s6, 0x100
	s_addc_u32 s7, s7, 0
.LBB0_1408:
	s_add_u32 s16, s14, s6
	s_addc_u32 s17, s15, s7
	s_add_u32 s16, s16, 0x100
	s_addc_u32 s17, s17, 0
	s_add_u32 s48, s45, s6
	s_addc_u32 s49, s46, s7
	s_add_i32 s50, 0, 0x10000
	s_cmpk_eq_i32 s6, 0xf00
	s_cselect_b32 s19, s11, s17
	s_cselect_b32 s18, s10, s16
	s_cselect_b32 s17, s3, s49
	s_cselect_b32 s16, s44, s48
	v_lshl_add_u64 v[162:163], v[142:143], 0, s[6:7]
	s_add_i32 m0, s30, 0xc000
	ds_read_b128 v[172:175], v166 offset:1024
	ds_read_b128 v[190:193], v166 offset:3072
	ds_read_b128 v[198:201], v166 offset:5120
	ds_read_b128 v[206:209], v166 offset:7168
	global_load_lds_dwordx4 v[162:163], off
	v_lshl_add_u64 v[162:163], v[144:145], 0, s[6:7]
	s_add_i32 m0, s30, 0xe000
	s_nop 0
	global_load_lds_dwordx4 v[162:163], off
	s_waitcnt lgkmcnt(8)
	s_barrier
	s_waitcnt lgkmcnt(0)
	s_waitcnt lgkmcnt(0)
	v_mfma_f32_16x16x32_bf16 v[126:129], v[146:149], v[168:171], v[126:129]
	v_mfma_f32_16x16x32_bf16 v[122:125], v[154:157], v[168:171], v[122:125]
	v_mfma_f32_16x16x32_bf16 v[110:113], v[146:149], v[186:189], v[110:113]
	v_mfma_f32_16x16x32_bf16 v[106:109], v[154:157], v[186:189], v[106:109]
	v_mfma_f32_16x16x32_bf16 v[94:97], v[146:149], v[194:197], v[94:97]
	v_mfma_f32_16x16x32_bf16 v[90:93], v[154:157], v[194:197], v[90:93]
	v_mfma_f32_16x16x32_bf16 v[78:81], v[146:149], v[202:205], v[78:81]
	v_mfma_f32_16x16x32_bf16 v[74:77], v[154:157], v[202:205], v[74:77]
	v_mfma_f32_16x16x32_bf16 v[126:129], v[150:153], v[172:175], v[126:129]
	v_mfma_f32_16x16x32_bf16 v[122:125], v[158:161], v[172:175], v[122:125]
	v_mfma_f32_16x16x32_bf16 v[110:113], v[150:153], v[190:193], v[110:113]
	v_mfma_f32_16x16x32_bf16 v[106:109], v[158:161], v[190:193], v[106:109]
	v_mfma_f32_16x16x32_bf16 v[94:97], v[150:153], v[198:201], v[94:97]
	v_mfma_f32_16x16x32_bf16 v[90:93], v[158:161], v[198:201], v[90:93]
	v_mfma_f32_16x16x32_bf16 v[78:81], v[150:153], v[206:209], v[78:81]
	v_mfma_f32_16x16x32_bf16 v[74:77], v[158:161], v[206:209], v[74:77]
	s_barrier
	s_add_i32 s51, 0, 0x14000
	v_add_u32_e32 v162, s51, v164
	s_add_i32 s48, s50, s29
	ds_read_b128 v[210:213], v162
	ds_read_b128 v[214:217], v162 offset:1024
	ds_read_b128 v[218:221], v162 offset:2048
	ds_read_b128 v[222:225], v162 offset:3072
	s_add_u32 s64, s16, 0x80
	s_addc_u32 s65, s17, 0
	s_mov_b32 m0, s48
	s_nop 0
	global_load_lds_dwordx4 v132, s[16:17]
	s_add_i32 m0, s48, 0x2000
	s_nop 0
	global_load_lds_dwordx4 v136, s[16:17]
	s_barrier
	s_waitcnt lgkmcnt(0)
	s_waitcnt lgkmcnt(0)
	v_mfma_f32_16x16x32_bf16 v[118:121], v[210:213], v[168:171], v[118:121]
	v_mfma_f32_16x16x32_bf16 v[114:117], v[218:221], v[168:171], v[114:117]
	v_mfma_f32_16x16x32_bf16 v[102:105], v[210:213], v[186:189], v[102:105]
	v_mfma_f32_16x16x32_bf16 v[98:101], v[218:221], v[186:189], v[98:101]
	v_mfma_f32_16x16x32_bf16 v[86:89], v[210:213], v[194:197], v[86:89]
	v_mfma_f32_16x16x32_bf16 v[82:85], v[218:221], v[194:197], v[82:85]
	v_mfma_f32_16x16x32_bf16 v[70:73], v[210:213], v[202:205], v[70:73]
	v_mfma_f32_16x16x32_bf16 v[66:69], v[218:221], v[202:205], v[66:69]
	ds_read_b128 v[168:171], v166 offset:16384
	v_mfma_f32_16x16x32_bf16 v[118:121], v[214:217], v[172:175], v[118:121]
	v_mfma_f32_16x16x32_bf16 v[114:117], v[222:225], v[172:175], v[114:117]
	ds_read_b128 v[186:189], v166 offset:18432
	v_mfma_f32_16x16x32_bf16 v[102:105], v[214:217], v[190:193], v[102:105]
	v_mfma_f32_16x16x32_bf16 v[98:101], v[222:225], v[190:193], v[98:101]
	ds_read_b128 v[194:197], v166 offset:20480
	v_mfma_f32_16x16x32_bf16 v[86:89], v[214:217], v[198:201], v[86:89]
	v_mfma_f32_16x16x32_bf16 v[82:85], v[222:225], v[198:201], v[82:85]
	ds_read_b128 v[202:205], v166 offset:22528
	v_mfma_f32_16x16x32_bf16 v[70:73], v[214:217], v[206:209], v[70:73]
	v_mfma_f32_16x16x32_bf16 v[66:69], v[222:225], v[206:209], v[66:69]
	s_barrier
	s_mov_b32 m0, s30
	s_add_u32 s62, s18, 0x80
	s_addc_u32 s63, s19, 0
	ds_read_b128 v[172:175], v166 offset:17408
	ds_read_b128 v[190:193], v166 offset:19456
	ds_read_b128 v[198:201], v166 offset:21504
	ds_read_b128 v[206:209], v166 offset:23552
	global_load_lds_dwordx4 v130, s[18:19]
	s_mov_b32 m0, s31
	s_nop 0
	global_load_lds_dwordx4 v134, s[18:19]
	s_waitcnt vmcnt(8)
	s_barrier
	s_waitcnt lgkmcnt(0)
	s_waitcnt lgkmcnt(0)
	v_mfma_f32_16x16x32_bf16 v[62:65], v[146:149], v[168:171], v[62:65]
	v_mfma_f32_16x16x32_bf16 v[58:61], v[154:157], v[168:171], v[58:61]
	v_mfma_f32_16x16x32_bf16 v[46:49], v[146:149], v[186:189], v[46:49]
	v_mfma_f32_16x16x32_bf16 v[42:45], v[154:157], v[186:189], v[42:45]
	v_mfma_f32_16x16x32_bf16 v[30:33], v[146:149], v[194:197], v[30:33]
	v_mfma_f32_16x16x32_bf16 v[26:29], v[154:157], v[194:197], v[26:29]
	v_mfma_f32_16x16x32_bf16 v[14:17], v[146:149], v[202:205], v[14:17]
	v_mfma_f32_16x16x32_bf16 v[10:13], v[154:157], v[202:205], v[10:13]
	v_mfma_f32_16x16x32_bf16 v[62:65], v[150:153], v[172:175], v[62:65]
	v_mfma_f32_16x16x32_bf16 v[58:61], v[158:161], v[172:175], v[58:61]
	v_mfma_f32_16x16x32_bf16 v[46:49], v[150:153], v[190:193], v[46:49]
	v_mfma_f32_16x16x32_bf16 v[42:45], v[158:161], v[190:193], v[42:45]
	v_mfma_f32_16x16x32_bf16 v[30:33], v[150:153], v[198:201], v[30:33]
	v_mfma_f32_16x16x32_bf16 v[26:29], v[158:161], v[198:201], v[26:29]
	v_mfma_f32_16x16x32_bf16 v[14:17], v[150:153], v[206:209], v[14:17]
	v_mfma_f32_16x16x32_bf16 v[10:13], v[158:161], v[206:209], v[10:13]
	s_barrier
	v_add_u32_e32 v158, 0x18000, v164
	ds_read_b128 v[146:149], v158
	ds_read_b128 v[150:153], v158 offset:1024
	ds_read_b128 v[154:157], v158 offset:2048
	ds_read_b128 v[158:161], v158 offset:3072
	s_add_u32 s48, s16, 0x80000
	s_addc_u32 s49, s17, 0
	s_add_i32 s50, s51, s29
	s_mov_b32 m0, s50
	s_nop 0
	global_load_lds_dwordx4 v132, s[48:49]
	s_add_i32 m0, s50, 0x2000
	s_nop 0
	global_load_lds_dwordx4 v136, s[48:49]
	s_waitcnt vmcnt(6)
	s_barrier
	v_mfma_f32_16x16x32_bf16 v[54:57], v[210:213], v[168:171], v[54:57]
	v_mfma_f32_16x16x32_bf16 v[50:53], v[218:221], v[168:171], v[50:53]
	v_mfma_f32_16x16x32_bf16 v[38:41], v[210:213], v[186:189], v[38:41]
	v_mfma_f32_16x16x32_bf16 v[34:37], v[218:221], v[186:189], v[34:37]
	v_mfma_f32_16x16x32_bf16 v[22:25], v[210:213], v[194:197], v[22:25]
	v_mfma_f32_16x16x32_bf16 v[18:21], v[218:221], v[194:197], v[18:21]
	v_mfma_f32_16x16x32_bf16 v[6:9], v[210:213], v[202:205], v[6:9]
	v_mfma_f32_16x16x32_bf16 v[2:5], v[218:221], v[202:205], v[2:5]
	ds_read_b128 v[168:171], v166 offset:32768
	v_mfma_f32_16x16x32_bf16 v[54:57], v[214:217], v[172:175], v[54:57]
	v_mfma_f32_16x16x32_bf16 v[50:53], v[222:225], v[172:175], v[50:53]
	ds_read_b128 v[186:189], v166 offset:34816
	v_mfma_f32_16x16x32_bf16 v[38:41], v[214:217], v[190:193], v[38:41]
	v_mfma_f32_16x16x32_bf16 v[34:37], v[222:225], v[190:193], v[34:37]
	ds_read_b128 v[194:197], v166 offset:36864
	v_mfma_f32_16x16x32_bf16 v[22:25], v[214:217], v[198:201], v[22:25]
	v_mfma_f32_16x16x32_bf16 v[18:21], v[222:225], v[198:201], v[18:21]
	ds_read_b128 v[202:205], v166 offset:38912
	v_mfma_f32_16x16x32_bf16 v[6:9], v[214:217], v[206:209], v[6:9]
	v_mfma_f32_16x16x32_bf16 v[2:5], v[222:225], v[206:209], v[2:5]
	s_barrier
	s_add_i32 s48, 0, 0x18000
	s_add_u32 s18, s18, s80
	s_addc_u32 s19, s19, 0
	s_mov_b32 m0, s34
	ds_read_b128 v[172:175], v166 offset:33792
	ds_read_b128 v[190:193], v166 offset:35840
	ds_read_b128 v[198:201], v166 offset:37888
	ds_read_b128 v[206:209], v166 offset:39936
	global_load_lds_dwordx4 v130, s[18:19]
	s_mov_b32 m0, s35
	s_nop 0
	global_load_lds_dwordx4 v134, s[18:19]
	s_waitcnt lgkmcnt(8)
	s_barrier
	s_waitcnt lgkmcnt(0)
	s_waitcnt lgkmcnt(0)
	v_mfma_f32_16x16x32_bf16 v[126:129], v[146:149], v[168:171], v[126:129]
	v_mfma_f32_16x16x32_bf16 v[122:125], v[154:157], v[168:171], v[122:125]
	v_mfma_f32_16x16x32_bf16 v[110:113], v[146:149], v[186:189], v[110:113]
	v_mfma_f32_16x16x32_bf16 v[106:109], v[154:157], v[186:189], v[106:109]
	v_mfma_f32_16x16x32_bf16 v[94:97], v[146:149], v[194:197], v[94:97]
	v_mfma_f32_16x16x32_bf16 v[90:93], v[154:157], v[194:197], v[90:93]
	v_mfma_f32_16x16x32_bf16 v[78:81], v[146:149], v[202:205], v[78:81]
	v_mfma_f32_16x16x32_bf16 v[74:77], v[154:157], v[202:205], v[74:77]
	v_mfma_f32_16x16x32_bf16 v[126:129], v[150:153], v[172:175], v[126:129]
	v_mfma_f32_16x16x32_bf16 v[122:125], v[158:161], v[172:175], v[122:125]
	v_mfma_f32_16x16x32_bf16 v[110:113], v[150:153], v[190:193], v[110:113]
	v_mfma_f32_16x16x32_bf16 v[106:109], v[158:161], v[190:193], v[106:109]
	v_mfma_f32_16x16x32_bf16 v[94:97], v[150:153], v[198:201], v[94:97]
	v_mfma_f32_16x16x32_bf16 v[90:93], v[158:161], v[198:201], v[90:93]
	v_mfma_f32_16x16x32_bf16 v[78:81], v[150:153], v[206:209], v[78:81]
	v_mfma_f32_16x16x32_bf16 v[74:77], v[158:161], v[206:209], v[74:77]
	s_barrier
	s_add_i32 s18, 0, 0x1c000
	s_add_i32 s19, s48, s29
	v_add_u32_e32 v167, s18, v164
	s_mov_b32 m0, s19
	ds_read_b128 v[210:213], v167
	ds_read_b128 v[214:217], v167 offset:1024
	ds_read_b128 v[218:221], v167 offset:2048
	ds_read_b128 v[222:225], v167 offset:3072
	global_load_lds_dwordx4 v132, s[64:65]
	s_add_i32 m0, s19, 0x2000
	s_nop 0
	global_load_lds_dwordx4 v136, s[64:65]
	s_barrier
	s_waitcnt lgkmcnt(0)
	s_waitcnt lgkmcnt(0)
	v_mfma_f32_16x16x32_bf16 v[118:121], v[210:213], v[168:171], v[118:121]
	v_mfma_f32_16x16x32_bf16 v[114:117], v[218:221], v[168:171], v[114:117]
	v_mfma_f32_16x16x32_bf16 v[102:105], v[210:213], v[186:189], v[102:105]
	v_mfma_f32_16x16x32_bf16 v[98:101], v[218:221], v[186:189], v[98:101]
	v_mfma_f32_16x16x32_bf16 v[86:89], v[210:213], v[194:197], v[86:89]
	v_mfma_f32_16x16x32_bf16 v[82:85], v[218:221], v[194:197], v[82:85]
	v_mfma_f32_16x16x32_bf16 v[70:73], v[210:213], v[202:205], v[70:73]
	v_mfma_f32_16x16x32_bf16 v[66:69], v[218:221], v[202:205], v[66:69]
	ds_read_b128 v[168:171], v166 offset:49152
	v_mfma_f32_16x16x32_bf16 v[118:121], v[214:217], v[172:175], v[118:121]
	v_mfma_f32_16x16x32_bf16 v[114:117], v[222:225], v[172:175], v[114:117]
	ds_read_b128 v[186:189], v166 offset:51200
	v_mfma_f32_16x16x32_bf16 v[102:105], v[214:217], v[190:193], v[102:105]
	v_mfma_f32_16x16x32_bf16 v[98:101], v[222:225], v[190:193], v[98:101]
	ds_read_b128 v[194:197], v166 offset:53248
	v_mfma_f32_16x16x32_bf16 v[86:89], v[214:217], v[198:201], v[86:89]
	v_mfma_f32_16x16x32_bf16 v[82:85], v[222:225], v[198:201], v[82:85]
	ds_read_b128 v[202:205], v166 offset:55296
	v_mfma_f32_16x16x32_bf16 v[70:73], v[214:217], v[206:209], v[70:73]
	v_mfma_f32_16x16x32_bf16 v[66:69], v[222:225], v[206:209], v[66:69]
	s_barrier
	s_mov_b32 m0, s38
	ds_read_b128 v[172:175], v166 offset:50176
	ds_read_b128 v[190:193], v166 offset:52224
	ds_read_b128 v[198:201], v166 offset:54272
	ds_read_b128 v[206:209], v166 offset:56320
	global_load_lds_dwordx4 v130, s[62:63]
	s_mov_b32 m0, s39
	s_nop 0
	global_load_lds_dwordx4 v134, s[62:63]
	s_waitcnt vmcnt(8)
	s_barrier
	s_waitcnt lgkmcnt(0)
	s_waitcnt lgkmcnt(0)
	v_mfma_f32_16x16x32_bf16 v[62:65], v[146:149], v[168:171], v[62:65]
	v_mfma_f32_16x16x32_bf16 v[58:61], v[154:157], v[168:171], v[58:61]
	v_mfma_f32_16x16x32_bf16 v[46:49], v[146:149], v[186:189], v[46:49]
	v_mfma_f32_16x16x32_bf16 v[42:45], v[154:157], v[186:189], v[42:45]
	v_mfma_f32_16x16x32_bf16 v[30:33], v[146:149], v[194:197], v[30:33]
	v_mfma_f32_16x16x32_bf16 v[26:29], v[154:157], v[194:197], v[26:29]
	v_mfma_f32_16x16x32_bf16 v[14:17], v[146:149], v[202:205], v[14:17]
	v_mfma_f32_16x16x32_bf16 v[10:13], v[154:157], v[202:205], v[10:13]
	v_mfma_f32_16x16x32_bf16 v[62:65], v[150:153], v[172:175], v[62:65]
	v_mfma_f32_16x16x32_bf16 v[58:61], v[158:161], v[172:175], v[58:61]
	v_mfma_f32_16x16x32_bf16 v[46:49], v[150:153], v[190:193], v[46:49]
	v_mfma_f32_16x16x32_bf16 v[42:45], v[158:161], v[190:193], v[42:45]
	v_mfma_f32_16x16x32_bf16 v[30:33], v[150:153], v[198:201], v[30:33]
	v_mfma_f32_16x16x32_bf16 v[26:29], v[158:161], v[198:201], v[26:29]
	v_mfma_f32_16x16x32_bf16 v[14:17], v[150:153], v[206:209], v[14:17]
	v_mfma_f32_16x16x32_bf16 v[10:13], v[158:161], v[206:209], v[10:13]
	s_barrier
	v_add_u32_e32 v158, 0x10000, v164
	ds_read_b128 v[146:149], v158
	ds_read_b128 v[150:153], v158 offset:1024
	ds_read_b128 v[154:157], v158 offset:2048
	ds_read_b128 v[158:161], v158 offset:3072
	s_add_u32 s16, s16, 0x80080
	s_addc_u32 s17, s17, 0
	s_add_i32 s18, s18, s29
	s_mov_b32 m0, s18
	s_nop 0
	global_load_lds_dwordx4 v132, s[16:17]
	s_add_i32 m0, s18, 0x2000
	s_nop 0
	global_load_lds_dwordx4 v136, s[16:17]
	s_waitcnt vmcnt(6)
	s_barrier
	v_mfma_f32_16x16x32_bf16 v[54:57], v[210:213], v[168:171], v[54:57]
	v_mfma_f32_16x16x32_bf16 v[50:53], v[218:221], v[168:171], v[50:53]
	v_mfma_f32_16x16x32_bf16 v[38:41], v[210:213], v[186:189], v[38:41]
	v_mfma_f32_16x16x32_bf16 v[34:37], v[218:221], v[186:189], v[34:37]
	v_mfma_f32_16x16x32_bf16 v[22:25], v[210:213], v[194:197], v[22:25]
	v_mfma_f32_16x16x32_bf16 v[18:21], v[218:221], v[194:197], v[18:21]
	v_mfma_f32_16x16x32_bf16 v[6:9], v[210:213], v[202:205], v[6:9]
	v_mfma_f32_16x16x32_bf16 v[2:5], v[218:221], v[202:205], v[2:5]
	ds_read_b128 v[168:171], v166
	v_mfma_f32_16x16x32_bf16 v[54:57], v[214:217], v[172:175], v[54:57]
	v_mfma_f32_16x16x32_bf16 v[50:53], v[222:225], v[172:175], v[50:53]
	ds_read_b128 v[186:189], v166 offset:2048
	v_mfma_f32_16x16x32_bf16 v[38:41], v[214:217], v[190:193], v[38:41]
	v_mfma_f32_16x16x32_bf16 v[34:37], v[222:225], v[190:193], v[34:37]
	ds_read_b128 v[194:197], v166 offset:4096
	v_mfma_f32_16x16x32_bf16 v[22:25], v[214:217], v[198:201], v[22:25]
	v_mfma_f32_16x16x32_bf16 v[18:21], v[222:225], v[198:201], v[18:21]
	ds_read_b128 v[202:205], v166 offset:6144
	v_mfma_f32_16x16x32_bf16 v[6:9], v[214:217], v[206:209], v[6:9]
	v_mfma_f32_16x16x32_bf16 v[2:5], v[222:225], v[206:209], v[2:5]
	s_barrier
	s_add_i32 s47, s47, 2
	s_add_u32 s6, s6, 0x100
	s_addc_u32 s7, s7, 0
	s_cmp_gt_u32 s47, 29
	s_cbranch_scc0 .LBB0_1408
	s_waitcnt lgkmcnt(0)
	s_ashr_i32 s3, s33, 5
	s_mul_hi_i32 s7, s3, 0x9000
	s_mul_i32 s3, s3, 0x9000
	v_lshl_or_b32 v168, s43, 8, v165
	s_add_u32 s6, s36, s3
	s_addc_u32 s7, s37, s7
	v_ashrrev_i32_e32 v169, 31, v168
	v_lshl_add_u64 v[162:163], v[168:169], 2, s[6:7]
	global_load_dwordx4 v[142:145], v[162:163], off offset:16
	global_load_dwordx4 v[146:149], v[162:163], off
	v_mov_b32_e32 v158, v162
	v_mov_b32_e32 v159, v163
	v_lshl_add_u32 v162, s33, 8, v1
	v_ashrrev_i32_e32 v163, 31, v162
	v_lshlrev_b64 v[152:153], 12, v[162:163]
	v_lshl_add_u64 v[152:153], s[8:9], 0, v[152:153]
	v_lshl_add_u64 v[152:153], v[168:169], 1, v[152:153]
	v_mov_b32_e32 v156, 0x10000
	v_mov_b32_e32 v157, 0
	global_load_dwordx4 v[174:177], v[152:153], off offset:2048
	global_load_dwordx4 v[186:189], v[152:153], off offset:2304
	v_lshl_add_u64 v[152:153], v[152:153], 0, v[156:157]
	global_load_dwordx4 v[190:193], v[152:153], off offset:2048
	global_load_dwordx4 v[194:197], v[152:153], off offset:2304
	v_lshl_add_u64 v[152:153], v[152:153], 0, v[156:157]
	global_load_dwordx4 v[198:201], v[152:153], off offset:2048
	global_load_dwordx4 v[202:205], v[152:153], off offset:2304
	v_lshl_add_u64 v[152:153], v[152:153], 0, v[156:157]
	global_load_dwordx4 v[206:209], v[152:153], off offset:2048
	global_load_dwordx4 v[210:213], v[152:153], off offset:2304
	v_mov_b32_e32 v156, 0x50000
	v_lshl_add_u64 v[152:153], v[152:153], 0, v[156:157]
	v_mov_b32_e32 v156, 0x10000
	global_load_dwordx4 v[214:217], v[152:153], off offset:2048
	global_load_dwordx4 v[218:221], v[152:153], off offset:2304
	v_lshl_add_u64 v[152:153], v[152:153], 0, v[156:157]
	global_load_dwordx4 v[222:225], v[152:153], off offset:2048
	global_load_dwordx4 v[226:229], v[152:153], off offset:2304
	v_lshl_add_u64 v[152:153], v[152:153], 0, v[156:157]
	global_load_dwordx4 v[230:233], v[152:153], off offset:2048
	global_load_dwordx4 v[236:239], v[152:153], off offset:2304
	v_lshl_add_u64 v[152:153], v[152:153], 0, v[156:157]
	global_load_dwordx4 v[246:249], v[152:153], off offset:2048
	global_load_dwordx4 v[250:253], v[152:153], off offset:2304
	s_mov_b64 s[6:7], 0x80000
	s_and_b64 vcc, exec, s[4:5]
	s_mov_b32 s43, s2
	s_mov_b64 s[16:17], s[12:13]
	s_mov_b64 s[14:15], s[10:11]
	s_waitcnt vmcnt(16)
	v_pk_add_f32 v[150:151], v[144:145], 1.0 op_sel_hi:[1,0]
	v_pk_add_f32 v[154:155], v[142:143], 1.0 op_sel_hi:[1,0]
	global_load_dwordx4 v[142:145], v[158:159], off offset:512
	global_load_dwordx4 v[158:161], v[158:159], off offset:528
	v_pk_add_f32 v[156:157], v[146:147], 1.0 op_sel_hi:[1,0]
	v_pk_add_f32 v[152:153], v[148:149], 1.0 op_sel_hi:[1,0]
	s_mov_b32 s33, s42
	s_waitcnt vmcnt(0)
	v_pk_add_f32 v[146:147], v[144:145], 1.0 op_sel_hi:[1,0]
	v_pk_add_f32 v[144:145], v[158:159], 1.0 op_sel_hi:[1,0]
	v_lshlrev_b64 v[158:159], 12, v[162:163]
	v_pk_add_f32 v[148:149], v[142:143], 1.0 op_sel_hi:[1,0]
	v_pk_add_f32 v[142:143], v[160:161], 1.0 op_sel_hi:[1,0]
	v_lshl_add_u64 v[158:159], s[8:9], 0, v[158:159]
	v_lshlrev_b64 v[160:161], 1, v[168:169]
	v_lshl_add_u64 v[158:159], v[158:159], 0, v[160:161]
	v_mov_b32_e32 v168, v174
	v_mov_b32_e32 v169, v175
	v_mov_b32_e32 v170, v176
	v_mov_b32_e32 v171, v177
	s_nop 0
	v_lshlrev_b32_e32 v172, 16, v168
	v_and_b32_e32 v173, 0xffff0000, v168
	v_lshlrev_b32_e32 v168, 16, v169
	v_and_b32_e32 v169, 0xffff0000, v169
	v_pk_fma_f32 v[128:129], v[128:129], v[152:153], v[168:169]
	v_lshlrev_b32_e32 v168, 16, v170
	v_and_b32_e32 v169, 0xffff0000, v170
	v_pk_fma_f32 v[168:169], v[122:123], v[154:155], v[168:169]
	v_lshlrev_b32_e32 v122, 16, v171
	v_and_b32_e32 v123, 0xffff0000, v171
	v_pk_fma_f32 v[126:127], v[126:127], v[156:157], v[172:173]
	v_pk_fma_f32 v[170:171], v[124:125], v[150:151], v[122:123]
	v_cvt_pk_bf16_f32 v122, v126, v127
	v_cvt_pk_bf16_f32 v123, v128, v129
	v_cvt_pk_bf16_f32 v124, v168, v169
	v_cvt_pk_bf16_f32 v125, v170, v171
	global_store_dwordx4 v[158:159], v[122:125], off offset:2048
	s_nop 1
	v_mov_b32_e32 v122, v186
	v_mov_b32_e32 v123, v187
	v_mov_b32_e32 v124, v188
	v_mov_b32_e32 v125, v189
	s_nop 0
	v_lshlrev_b32_e32 v126, 16, v122
	v_and_b32_e32 v127, 0xffff0000, v122
	v_lshlrev_b32_e32 v122, 16, v123
	v_and_b32_e32 v123, 0xffff0000, v123
	v_pk_fma_f32 v[120:121], v[120:121], v[146:147], v[122:123]
	v_lshlrev_b32_e32 v122, 16, v124
	v_and_b32_e32 v123, 0xffff0000, v124
	v_pk_fma_f32 v[122:123], v[114:115], v[144:145], v[122:123]
	v_lshlrev_b32_e32 v114, 16, v125
	v_and_b32_e32 v115, 0xffff0000, v125
	v_pk_fma_f32 v[118:119], v[118:119], v[148:149], v[126:127]
	v_pk_fma_f32 v[124:125], v[116:117], v[142:143], v[114:115]
	v_cvt_pk_bf16_f32 v114, v118, v119
	v_cvt_pk_bf16_f32 v115, v120, v121
	v_cvt_pk_bf16_f32 v116, v122, v123
	v_cvt_pk_bf16_f32 v117, v124, v125
	global_store_dwordx4 v[158:159], v[114:117], off offset:2304
	s_nop 1
	v_or_b32_e32 v114, 16, v162
	v_ashrrev_i32_e32 v115, 31, v114
	v_lshlrev_b64 v[114:115], 12, v[114:115]
	v_lshl_add_u64 v[114:115], s[8:9], 0, v[114:115]
	v_lshl_add_u64 v[118:119], v[114:115], 0, v[160:161]
	v_mov_b32_e32 v114, v190
	v_mov_b32_e32 v115, v191
	v_mov_b32_e32 v116, v192
	v_mov_b32_e32 v117, v193
	s_nop 0
	v_lshlrev_b32_e32 v120, 16, v114
	v_and_b32_e32 v121, 0xffff0000, v114
	v_lshlrev_b32_e32 v114, 16, v115
	v_and_b32_e32 v115, 0xffff0000, v115
	v_pk_fma_f32 v[112:113], v[112:113], v[152:153], v[114:115]
	v_lshlrev_b32_e32 v114, 16, v116
	v_and_b32_e32 v115, 0xffff0000, v116
	v_pk_fma_f32 v[114:115], v[106:107], v[154:155], v[114:115]
	v_lshlrev_b32_e32 v106, 16, v117
	v_and_b32_e32 v107, 0xffff0000, v117
	v_pk_fma_f32 v[110:111], v[110:111], v[156:157], v[120:121]
	v_pk_fma_f32 v[116:117], v[108:109], v[150:151], v[106:107]
	v_cvt_pk_bf16_f32 v106, v110, v111
	v_cvt_pk_bf16_f32 v107, v112, v113
	v_cvt_pk_bf16_f32 v108, v114, v115
	v_cvt_pk_bf16_f32 v109, v116, v117
	global_store_dwordx4 v[118:119], v[106:109], off offset:2048
	s_nop 1
	v_mov_b32_e32 v106, v194
	v_mov_b32_e32 v107, v195
	v_mov_b32_e32 v108, v196
	v_mov_b32_e32 v109, v197
	s_nop 0
	v_lshlrev_b32_e32 v110, 16, v106
	v_and_b32_e32 v111, 0xffff0000, v106
	v_lshlrev_b32_e32 v106, 16, v107
	v_and_b32_e32 v107, 0xffff0000, v107
	v_pk_fma_f32 v[104:105], v[104:105], v[146:147], v[106:107]
	v_lshlrev_b32_e32 v106, 16, v108
	v_and_b32_e32 v107, 0xffff0000, v108
	v_pk_fma_f32 v[106:107], v[98:99], v[144:145], v[106:107]
	v_lshlrev_b32_e32 v98, 16, v109
	v_and_b32_e32 v99, 0xffff0000, v109
	v_pk_fma_f32 v[102:103], v[102:103], v[148:149], v[110:111]
	v_pk_fma_f32 v[108:109], v[100:101], v[142:143], v[98:99]
	v_cvt_pk_bf16_f32 v98, v102, v103
	v_cvt_pk_bf16_f32 v99, v104, v105
	v_cvt_pk_bf16_f32 v100, v106, v107
	v_cvt_pk_bf16_f32 v101, v108, v109
	global_store_dwordx4 v[118:119], v[98:101], off offset:2304
	s_nop 1
	v_or_b32_e32 v98, 32, v162
	v_ashrrev_i32_e32 v99, 31, v98
	v_lshlrev_b64 v[98:99], 12, v[98:99]
	v_lshl_add_u64 v[98:99], s[8:9], 0, v[98:99]
	v_lshl_add_u64 v[102:103], v[98:99], 0, v[160:161]
	v_mov_b32_e32 v98, v198
	v_mov_b32_e32 v99, v199
	v_mov_b32_e32 v100, v200
	v_mov_b32_e32 v101, v201
	s_nop 0
	v_lshlrev_b32_e32 v104, 16, v98
	v_and_b32_e32 v105, 0xffff0000, v98
	v_lshlrev_b32_e32 v98, 16, v99
	v_and_b32_e32 v99, 0xffff0000, v99
	v_pk_fma_f32 v[96:97], v[96:97], v[152:153], v[98:99]
	v_lshlrev_b32_e32 v98, 16, v100
	v_and_b32_e32 v99, 0xffff0000, v100
	v_pk_fma_f32 v[98:99], v[90:91], v[154:155], v[98:99]
	v_lshlrev_b32_e32 v90, 16, v101
	v_and_b32_e32 v91, 0xffff0000, v101
	v_pk_fma_f32 v[94:95], v[94:95], v[156:157], v[104:105]
	v_pk_fma_f32 v[100:101], v[92:93], v[150:151], v[90:91]
	v_cvt_pk_bf16_f32 v90, v94, v95
	v_cvt_pk_bf16_f32 v91, v96, v97
	v_cvt_pk_bf16_f32 v92, v98, v99
	v_cvt_pk_bf16_f32 v93, v100, v101
	global_store_dwordx4 v[102:103], v[90:93], off offset:2048
	s_nop 1
	v_mov_b32_e32 v90, v202
	v_mov_b32_e32 v91, v203
	v_mov_b32_e32 v92, v204
	v_mov_b32_e32 v93, v205
	s_nop 0
	v_lshlrev_b32_e32 v94, 16, v90
	v_and_b32_e32 v95, 0xffff0000, v90
	v_lshlrev_b32_e32 v90, 16, v91
	v_and_b32_e32 v91, 0xffff0000, v91
	v_pk_fma_f32 v[88:89], v[88:89], v[146:147], v[90:91]
	v_lshlrev_b32_e32 v90, 16, v92
	v_and_b32_e32 v91, 0xffff0000, v92
	v_pk_fma_f32 v[90:91], v[82:83], v[144:145], v[90:91]
	v_lshlrev_b32_e32 v82, 16, v93
	v_and_b32_e32 v83, 0xffff0000, v93
	v_pk_fma_f32 v[86:87], v[86:87], v[148:149], v[94:95]
	v_pk_fma_f32 v[92:93], v[84:85], v[142:143], v[82:83]
	v_cvt_pk_bf16_f32 v82, v86, v87
	v_cvt_pk_bf16_f32 v83, v88, v89
	v_cvt_pk_bf16_f32 v84, v90, v91
	v_cvt_pk_bf16_f32 v85, v92, v93
	global_store_dwordx4 v[102:103], v[82:85], off offset:2304
	s_nop 1
	v_or_b32_e32 v82, 48, v162
	v_ashrrev_i32_e32 v83, 31, v82
	v_lshlrev_b64 v[82:83], 12, v[82:83]
	v_lshl_add_u64 v[82:83], s[8:9], 0, v[82:83]
	v_lshl_add_u64 v[82:83], v[82:83], 0, v[160:161]
	v_mov_b32_e32 v84, v206
	v_mov_b32_e32 v85, v207
	v_mov_b32_e32 v86, v208
	v_mov_b32_e32 v87, v209
	s_nop 0
	v_lshlrev_b32_e32 v88, 16, v84
	v_and_b32_e32 v89, 0xffff0000, v84
	v_lshlrev_b32_e32 v84, 16, v85
	v_and_b32_e32 v85, 0xffff0000, v85
	v_pk_fma_f32 v[80:81], v[80:81], v[152:153], v[84:85]
	v_lshlrev_b32_e32 v84, 16, v86
	v_and_b32_e32 v85, 0xffff0000, v86
	v_pk_fma_f32 v[84:85], v[74:75], v[154:155], v[84:85]
	v_lshlrev_b32_e32 v74, 16, v87
	v_and_b32_e32 v75, 0xffff0000, v87
	v_pk_fma_f32 v[78:79], v[78:79], v[156:157], v[88:89]
	v_pk_fma_f32 v[86:87], v[76:77], v[150:151], v[74:75]
	v_cvt_pk_bf16_f32 v74, v78, v79
	v_cvt_pk_bf16_f32 v75, v80, v81
	v_cvt_pk_bf16_f32 v76, v84, v85
	v_cvt_pk_bf16_f32 v77, v86, v87
	global_store_dwordx4 v[82:83], v[74:77], off offset:2048
	s_nop 1
	v_mov_b32_e32 v74, v210
	v_mov_b32_e32 v75, v211
	v_mov_b32_e32 v76, v212
	v_mov_b32_e32 v77, v213
	s_nop 0
	v_lshlrev_b32_e32 v78, 16, v74
	v_and_b32_e32 v79, 0xffff0000, v74
	v_lshlrev_b32_e32 v74, 16, v75
	v_and_b32_e32 v75, 0xffff0000, v75
	v_pk_fma_f32 v[72:73], v[72:73], v[146:147], v[74:75]
	v_lshlrev_b32_e32 v74, 16, v76
	v_and_b32_e32 v75, 0xffff0000, v76
	v_pk_fma_f32 v[74:75], v[66:67], v[144:145], v[74:75]
	v_lshlrev_b32_e32 v66, 16, v77
	v_and_b32_e32 v67, 0xffff0000, v77
	v_pk_fma_f32 v[70:71], v[70:71], v[148:149], v[78:79]
	v_pk_fma_f32 v[76:77], v[68:69], v[142:143], v[66:67]
	v_cvt_pk_bf16_f32 v66, v70, v71
	v_cvt_pk_bf16_f32 v67, v72, v73
	v_cvt_pk_bf16_f32 v68, v74, v75
	v_cvt_pk_bf16_f32 v69, v76, v77
	v_lshl_add_u64 v[70:71], v[158:159], 0, s[6:7]
	global_store_dwordx4 v[82:83], v[66:69], off offset:2304
	s_nop 1
	v_mov_b32_e32 v66, v214
	v_mov_b32_e32 v67, v215
	v_mov_b32_e32 v68, v216
	v_mov_b32_e32 v69, v217
	s_mov_b64 s[6:7], 0x90000
	s_nop 0
	v_lshlrev_b32_e32 v72, 16, v66
	v_and_b32_e32 v73, 0xffff0000, v66
	v_lshlrev_b32_e32 v66, 16, v67
	v_and_b32_e32 v67, 0xffff0000, v67
	v_pk_fma_f32 v[64:65], v[64:65], v[152:153], v[66:67]
	v_lshlrev_b32_e32 v66, 16, v68
	v_and_b32_e32 v67, 0xffff0000, v68
	v_pk_fma_f32 v[66:67], v[58:59], v[154:155], v[66:67]
	v_lshlrev_b32_e32 v58, 16, v69
	v_and_b32_e32 v59, 0xffff0000, v69
	v_pk_fma_f32 v[62:63], v[62:63], v[156:157], v[72:73]
	v_pk_fma_f32 v[68:69], v[60:61], v[150:151], v[58:59]
	v_cvt_pk_bf16_f32 v58, v62, v63
	v_cvt_pk_bf16_f32 v59, v64, v65
	v_cvt_pk_bf16_f32 v60, v66, v67
	v_cvt_pk_bf16_f32 v61, v68, v69
	global_store_dwordx4 v[70:71], v[58:61], off offset:2048
	s_nop 1
	v_mov_b32_e32 v58, v218
	v_mov_b32_e32 v59, v219
	v_mov_b32_e32 v60, v220
	v_mov_b32_e32 v61, v221
	s_nop 0
	v_lshlrev_b32_e32 v62, 16, v58
	v_and_b32_e32 v63, 0xffff0000, v58
	v_lshlrev_b32_e32 v58, 16, v59
	v_and_b32_e32 v59, 0xffff0000, v59
	v_pk_fma_f32 v[56:57], v[56:57], v[146:147], v[58:59]
	v_lshlrev_b32_e32 v58, 16, v60
	v_and_b32_e32 v59, 0xffff0000, v60
	v_pk_fma_f32 v[58:59], v[50:51], v[144:145], v[58:59]
	v_lshlrev_b32_e32 v50, 16, v61
	v_and_b32_e32 v51, 0xffff0000, v61
	v_pk_fma_f32 v[54:55], v[54:55], v[148:149], v[62:63]
	v_pk_fma_f32 v[60:61], v[52:53], v[142:143], v[50:51]
	v_cvt_pk_bf16_f32 v50, v54, v55
	v_cvt_pk_bf16_f32 v51, v56, v57
	v_cvt_pk_bf16_f32 v52, v58, v59
	v_cvt_pk_bf16_f32 v53, v60, v61
	v_lshl_add_u64 v[54:55], v[158:159], 0, s[6:7]
	global_store_dwordx4 v[70:71], v[50:53], off offset:2304
	s_nop 1
	v_mov_b32_e32 v50, v222
	v_mov_b32_e32 v51, v223
	v_mov_b32_e32 v52, v224
	v_mov_b32_e32 v53, v225
	s_mov_b64 s[6:7], 0xa0000
	s_nop 0
	v_lshlrev_b32_e32 v56, 16, v50
	v_and_b32_e32 v57, 0xffff0000, v50
	v_lshlrev_b32_e32 v50, 16, v51
	v_and_b32_e32 v51, 0xffff0000, v51
	v_pk_fma_f32 v[48:49], v[48:49], v[152:153], v[50:51]
	v_lshlrev_b32_e32 v50, 16, v52
	v_and_b32_e32 v51, 0xffff0000, v52
	v_pk_fma_f32 v[50:51], v[42:43], v[154:155], v[50:51]
	v_lshlrev_b32_e32 v42, 16, v53
	v_and_b32_e32 v43, 0xffff0000, v53
	v_pk_fma_f32 v[46:47], v[46:47], v[156:157], v[56:57]
	v_pk_fma_f32 v[52:53], v[44:45], v[150:151], v[42:43]
	v_cvt_pk_bf16_f32 v42, v46, v47
	v_cvt_pk_bf16_f32 v43, v48, v49
	v_cvt_pk_bf16_f32 v44, v50, v51
	v_cvt_pk_bf16_f32 v45, v52, v53
	global_store_dwordx4 v[54:55], v[42:45], off offset:2048
	s_nop 1
	v_mov_b32_e32 v42, v226
	v_mov_b32_e32 v43, v227
	v_mov_b32_e32 v44, v228
	v_mov_b32_e32 v45, v229
	s_nop 0
	v_lshlrev_b32_e32 v46, 16, v42
	v_and_b32_e32 v47, 0xffff0000, v42
	v_lshlrev_b32_e32 v42, 16, v43
	v_and_b32_e32 v43, 0xffff0000, v43
	v_pk_fma_f32 v[40:41], v[40:41], v[146:147], v[42:43]
	v_lshlrev_b32_e32 v42, 16, v44
	v_and_b32_e32 v43, 0xffff0000, v44
	v_pk_fma_f32 v[42:43], v[34:35], v[144:145], v[42:43]
	v_lshlrev_b32_e32 v34, 16, v45
	v_and_b32_e32 v35, 0xffff0000, v45
	v_pk_fma_f32 v[38:39], v[38:39], v[148:149], v[46:47]
	v_pk_fma_f32 v[44:45], v[36:37], v[142:143], v[34:35]
	v_cvt_pk_bf16_f32 v34, v38, v39
	v_cvt_pk_bf16_f32 v35, v40, v41
	v_cvt_pk_bf16_f32 v36, v42, v43
	v_cvt_pk_bf16_f32 v37, v44, v45
	v_lshl_add_u64 v[38:39], v[158:159], 0, s[6:7]
	global_store_dwordx4 v[54:55], v[34:37], off offset:2304
	s_nop 1
	v_mov_b32_e32 v34, v230
	v_mov_b32_e32 v35, v231
	v_mov_b32_e32 v36, v232
	v_mov_b32_e32 v37, v233
	s_mov_b64 s[6:7], 0xb0000
	s_nop 0
	v_lshlrev_b32_e32 v40, 16, v34
	v_and_b32_e32 v41, 0xffff0000, v34
	v_lshlrev_b32_e32 v34, 16, v35
	v_and_b32_e32 v35, 0xffff0000, v35
	v_pk_fma_f32 v[32:33], v[32:33], v[152:153], v[34:35]
	v_lshlrev_b32_e32 v34, 16, v36
	v_and_b32_e32 v35, 0xffff0000, v36
	v_pk_fma_f32 v[34:35], v[26:27], v[154:155], v[34:35]
	v_lshlrev_b32_e32 v26, 16, v37
	v_and_b32_e32 v27, 0xffff0000, v37
	v_pk_fma_f32 v[30:31], v[30:31], v[156:157], v[40:41]
	v_pk_fma_f32 v[36:37], v[28:29], v[150:151], v[26:27]
	v_cvt_pk_bf16_f32 v26, v30, v31
	v_cvt_pk_bf16_f32 v27, v32, v33
	v_cvt_pk_bf16_f32 v28, v34, v35
	v_cvt_pk_bf16_f32 v29, v36, v37
	global_store_dwordx4 v[38:39], v[26:29], off offset:2048
	s_nop 1
	v_mov_b32_e32 v26, v236
	v_mov_b32_e32 v27, v237
	v_mov_b32_e32 v28, v238
	v_mov_b32_e32 v29, v239
	s_nop 0
	v_lshlrev_b32_e32 v30, 16, v26
	v_and_b32_e32 v31, 0xffff0000, v26
	v_lshlrev_b32_e32 v26, 16, v27
	v_and_b32_e32 v27, 0xffff0000, v27
	v_pk_fma_f32 v[24:25], v[24:25], v[146:147], v[26:27]
	v_lshlrev_b32_e32 v26, 16, v28
	v_and_b32_e32 v27, 0xffff0000, v28
	v_pk_fma_f32 v[26:27], v[18:19], v[144:145], v[26:27]
	v_lshlrev_b32_e32 v18, 16, v29
	v_and_b32_e32 v19, 0xffff0000, v29
	v_pk_fma_f32 v[22:23], v[22:23], v[148:149], v[30:31]
	v_pk_fma_f32 v[28:29], v[20:21], v[142:143], v[18:19]
	v_cvt_pk_bf16_f32 v18, v22, v23
	v_cvt_pk_bf16_f32 v19, v24, v25
	v_cvt_pk_bf16_f32 v20, v26, v27
	v_cvt_pk_bf16_f32 v21, v28, v29
	global_store_dwordx4 v[38:39], v[18:21], off offset:2304
	s_nop 1
	v_lshl_add_u64 v[18:19], v[158:159], 0, s[6:7]
	v_mov_b32_e32 v20, v246
	v_mov_b32_e32 v21, v247
	v_mov_b32_e32 v22, v248
	v_mov_b32_e32 v23, v249
	s_nop 0
	v_lshlrev_b32_e32 v24, 16, v20
	v_and_b32_e32 v25, 0xffff0000, v20
	v_lshlrev_b32_e32 v20, 16, v21
	v_and_b32_e32 v21, 0xffff0000, v21
	v_pk_fma_f32 v[16:17], v[16:17], v[152:153], v[20:21]
	v_lshlrev_b32_e32 v20, 16, v22
	v_and_b32_e32 v21, 0xffff0000, v22
	v_pk_fma_f32 v[20:21], v[10:11], v[154:155], v[20:21]
	v_lshlrev_b32_e32 v10, 16, v23
	v_and_b32_e32 v11, 0xffff0000, v23
	v_pk_fma_f32 v[14:15], v[14:15], v[156:157], v[24:25]
	v_pk_fma_f32 v[22:23], v[12:13], v[150:151], v[10:11]
	v_cvt_pk_bf16_f32 v10, v14, v15
	v_cvt_pk_bf16_f32 v11, v16, v17
	v_cvt_pk_bf16_f32 v12, v20, v21
	v_cvt_pk_bf16_f32 v13, v22, v23
	global_store_dwordx4 v[18:19], v[10:13], off offset:2048
	s_nop 1
	v_mov_b32_e32 v10, v250
	v_mov_b32_e32 v11, v251
	v_mov_b32_e32 v12, v252
	v_mov_b32_e32 v13, v253
	s_nop 0
	v_lshlrev_b32_e32 v14, 16, v10
	v_and_b32_e32 v15, 0xffff0000, v10
	v_lshlrev_b32_e32 v10, 16, v11
	v_and_b32_e32 v11, 0xffff0000, v11
	v_pk_fma_f32 v[8:9], v[8:9], v[146:147], v[10:11]
	v_lshlrev_b32_e32 v10, 16, v12
	v_and_b32_e32 v11, 0xffff0000, v12
	v_pk_fma_f32 v[10:11], v[2:3], v[144:145], v[10:11]
	v_lshlrev_b32_e32 v2, 16, v13
	v_and_b32_e32 v3, 0xffff0000, v13
	v_pk_fma_f32 v[6:7], v[6:7], v[148:149], v[14:15]
	v_pk_fma_f32 v[12:13], v[4:5], v[142:143], v[2:3]
	v_cvt_pk_bf16_f32 v2, v6, v7
	v_cvt_pk_bf16_f32 v3, v8, v9
	v_cvt_pk_bf16_f32 v4, v10, v11
	v_cvt_pk_bf16_f32 v5, v12, v13
	global_store_dwordx4 v[18:19], v[2:5], off offset:2304
	s_cbranch_vccz .LBB0_1399
	s_waitcnt vmcnt(0)
	s_cmpk_gt_u32 s22, 0xff
	s_cbranch_scc1 .LBB0_1412
	s_barrier
